# in-projection epilogue: per-wave hand-written fast path (plain, rope q/k, transposed V/K copies pipelined through LDS, rms partial sums); hipcc epilogue kept only for the shared rope-key columns
# speedup vs baseline: 1.0188x; 1.0097x over previous
; #define G_STAGE(bufoff, gbase, voff) do { _Pragma("unroll") for (int _i = 0; _i < 2; ++_i) \
;         __builtin_amdgcn_global_load_lds((const unsigned*)((const char*)(gbase) + (voff)[_i]), (LAS unsigned*)(lds + (bufoff) + ldsw + _i * 8192), 16, 0, 0); } while (0)
; #define G_LDA(dst, b, h) do { _Pragma("unroll") for (int m = 0; m < 4; ++m) _Pragma("unroll") for (int k = 0; k < 2; ++k) dst[m][k] = *(const LAS bf16x8*)(lds + G_SA(b, h) + aoff + m * 2048 + k * 1024); } while (0)
; #define G_LDB(dst, b, h) do { _Pragma("unroll") for (int n = 0; n < 2; ++n) _Pragma("unroll") for (int k = 0; k < 2; ++k) dst[n][k] = *(const LAS bf16x8*)(lds + G_SB(b, h) + boff + n * 2048 + k * 1024); } while (0)
; #define G_MMA(ai, bj, At, Bt_) do { __builtin_amdgcn_s_setprio(1); _Pragma("unroll") for (int m = 0; m < 4; ++m) _Pragma("unroll") for (int n = 0; n < 2; ++n) _Pragma("unroll") for (int k = 0; k < 2; ++k) \
;         acc[ai][bj][m][n] = __builtin_amdgcn_mfma_f32_16x16x32_bf16(Bt_[n][k], At[m][k], acc[ai][bj][m][n], 0, 0, 0); __builtin_amdgcn_s_setprio(0); } while (0)
; #define G_WAIT_V(n) asm volatile("s_waitcnt vmcnt(" #n ")" ::: "memory")
; #define G_WAIT_L(n) asm volatile("s_waitcnt lgkmcnt(" #n ")" ::: "memory")
; #define G_BAR __builtin_amdgcn_s_barrier()
; #define G_SCHED __builtin_amdgcn_sched_barrier(0)
; template <class Epi, bool PERMROWS = false>
; DI void gemm_phase(LAS unsigned char* lds, const bf16_t* A, int lda, const bf16_t* Bt, int K, const Sched& S, const Epi& E) {
;     ...
;             G_LDB(B0, 0, 0); G_SCHED; G_LDA(At, 0, 0); G_STAGE(G_SA(1, 1), a1 + hstepA, voffA);
;             G_WAIT_L(8); G_BAR; G_WAIT_L(0); G_MMA(0, 0, At, B0); G_BAR; G_SCHED;
;             G_LDB(B1, 0, 1); G_STAGE(G_SB(0, 0), b2, voffB);
;             G_BAR; G_WAIT_L(0); G_MMA(0, 1, At, B1); G_BAR;
;             G_LDA(At, 0, 1); G_STAGE(G_SA(0, 0), a2, voffA);
;             G_BAR; G_WAIT_L(0); G_MMA(1, 0, At, B0); G_BAR; G_SCHED;
;             G_STAGE(G_SB(0, 1), b2 + hstepB, voffB);
;             G_WAIT_V(6); G_BAR; G_MMA(1, 1, At, B1); G_BAR;
.LBB0_534:
	s_waitcnt lgkmcnt(0)
	ds_read_b128 v[150:153], v174
	ds_read_b128 v[154:157], v174 offset:1024
	ds_read_b128 v[158:161], v174 offset:2048
	ds_read_b128 v[162:165], v174 offset:3072
	s_add_u32 s12, s10, 0xfff80080
	s_addc_u32 s13, s11, -1
	s_cmp_eq_u32 s62, 28
	s_cselect_b32 s57, s2, s13
	s_cselect_b32 s56, s3, s12
	s_cselect_b32 s13, s9, s37
	s_cselect_b32 s12, s27, s35
	v_lshl_add_u64 v[208:209], s[10:11], 0, v[144:145]
	s_add_i32 m0, s71, 0xc000
	ds_read_b128 v[166:169], v175
	ds_read_b128 v[178:181], v175 offset:1024
	ds_read_b128 v[182:185], v175 offset:2048
	ds_read_b128 v[186:189], v175 offset:3072
	ds_read_b128 v[190:193], v175 offset:4096
	ds_read_b128 v[194:197], v175 offset:5120
	ds_read_b128 v[198:201], v175 offset:6144
	ds_read_b128 v[204:207], v175 offset:7168
	global_load_lds_dwordx4 v[208:209], off
	v_lshl_add_u64 v[208:209], s[10:11], 0, v[142:143]
	s_add_i32 m0, s71, 0xe000
	s_nop 0
	global_load_lds_dwordx4 v[208:209], off
	s_waitcnt lgkmcnt(8)
	s_barrier
	s_waitcnt lgkmcnt(0)
	s_setprio 1
	s_waitcnt lgkmcnt(0)
	v_mfma_f32_16x16x32_bf16 v[124:127], v[150:153], v[166:169], v[124:127]
	v_mfma_f32_16x16x32_bf16 v[120:123], v[158:161], v[166:169], v[120:123]
	v_mfma_f32_16x16x32_bf16 v[108:111], v[150:153], v[182:185], v[108:111]
	v_mfma_f32_16x16x32_bf16 v[104:107], v[158:161], v[182:185], v[104:107]
	v_mfma_f32_16x16x32_bf16 v[92:95], v[150:153], v[190:193], v[92:95]
	v_mfma_f32_16x16x32_bf16 v[88:91], v[158:161], v[190:193], v[88:91]
	v_mfma_f32_16x16x32_bf16 v[76:79], v[150:153], v[198:201], v[76:79]
	v_mfma_f32_16x16x32_bf16 v[72:75], v[158:161], v[198:201], v[72:75]
	v_mfma_f32_16x16x32_bf16 v[124:127], v[154:157], v[178:181], v[124:127]
	v_mfma_f32_16x16x32_bf16 v[120:123], v[162:165], v[178:181], v[120:123]
	v_mfma_f32_16x16x32_bf16 v[108:111], v[154:157], v[186:189], v[108:111]
	v_mfma_f32_16x16x32_bf16 v[104:107], v[162:165], v[186:189], v[104:107]
	v_mfma_f32_16x16x32_bf16 v[92:95], v[154:157], v[194:197], v[92:95]
	v_mfma_f32_16x16x32_bf16 v[88:91], v[162:165], v[194:197], v[88:91]
	v_mfma_f32_16x16x32_bf16 v[76:79], v[154:157], v[204:207], v[76:79]
	v_mfma_f32_16x16x32_bf16 v[72:75], v[162:165], v[204:207], v[72:75]
	s_setprio 0
	s_barrier
	s_add_i32 s28, s85, s70
	v_lshl_add_u64 v[224:225], s[12:13], 0, v[128:129]
	s_mov_b32 m0, s28
	ds_read_b128 v[208:211], v176
	ds_read_b128 v[212:215], v176 offset:1024
	ds_read_b128 v[216:219], v176 offset:2048
	ds_read_b128 v[220:223], v176 offset:3072
	global_load_lds_dwordx4 v[224:225], off
	v_lshl_add_u64 v[226:227], s[12:13], 0, v[130:131]
	s_add_i32 m0, s28, 0x2000
	s_nop 0
	global_load_lds_dwordx4 v[226:227], off
	s_barrier
	s_waitcnt lgkmcnt(0)
	s_setprio 1
	s_waitcnt lgkmcnt(0)
	v_mfma_f32_16x16x32_bf16 v[116:119], v[208:211], v[166:169], v[116:119]
	v_mfma_f32_16x16x32_bf16 v[112:115], v[216:219], v[166:169], v[112:115]
	v_mfma_f32_16x16x32_bf16 v[100:103], v[208:211], v[182:185], v[100:103]
	v_mfma_f32_16x16x32_bf16 v[96:99], v[216:219], v[182:185], v[96:99]
	v_mfma_f32_16x16x32_bf16 v[84:87], v[208:211], v[190:193], v[84:87]
	v_mfma_f32_16x16x32_bf16 v[80:83], v[216:219], v[190:193], v[80:83]
	v_mfma_f32_16x16x32_bf16 v[68:71], v[208:211], v[198:201], v[68:71]
	v_mfma_f32_16x16x32_bf16 v[64:67], v[216:219], v[198:201], v[64:67]
	v_mfma_f32_16x16x32_bf16 v[116:119], v[212:215], v[178:181], v[116:119]
	v_mfma_f32_16x16x32_bf16 v[112:115], v[220:223], v[178:181], v[112:115]
	v_mfma_f32_16x16x32_bf16 v[100:103], v[212:215], v[186:189], v[100:103]
	v_mfma_f32_16x16x32_bf16 v[96:99], v[220:223], v[186:189], v[96:99]
	v_mfma_f32_16x16x32_bf16 v[84:87], v[212:215], v[194:197], v[84:87]
	v_mfma_f32_16x16x32_bf16 v[80:83], v[220:223], v[194:197], v[80:83]
	v_mfma_f32_16x16x32_bf16 v[68:71], v[212:215], v[204:207], v[68:71]
	v_mfma_f32_16x16x32_bf16 v[64:67], v[220:223], v[204:207], v[64:67]
	s_setprio 0
	s_mov_b32 m0, s71
	v_lshl_add_u64 v[228:229], s[56:57], 0, v[128:129]
	s_barrier
	ds_read_b128 v[166:169], v175 offset:16384
	ds_read_b128 v[178:181], v175 offset:17408
	ds_read_b128 v[182:185], v175 offset:18432
	ds_read_b128 v[186:189], v175 offset:19456
	ds_read_b128 v[190:193], v175 offset:20480
	ds_read_b128 v[194:197], v175 offset:21504
	ds_read_b128 v[198:201], v175 offset:22528
	ds_read_b128 v[204:207], v175 offset:23552
	global_load_lds_dwordx4 v[228:229], off
	v_lshl_add_u64 v[230:231], s[56:57], 0, v[130:131]
	s_mov_b32 m0, s72
	s_nop 0
	global_load_lds_dwordx4 v[230:231], off
	s_barrier
	s_waitcnt lgkmcnt(0)
	s_setprio 1
	s_waitcnt lgkmcnt(0)
	v_mfma_f32_16x16x32_bf16 v[60:63], v[150:153], v[166:169], v[60:63]
	v_mfma_f32_16x16x32_bf16 v[56:59], v[158:161], v[166:169], v[56:59]
	v_mfma_f32_16x16x32_bf16 v[44:47], v[150:153], v[182:185], v[44:47]
	v_mfma_f32_16x16x32_bf16 v[40:43], v[158:161], v[182:185], v[40:43]
	v_mfma_f32_16x16x32_bf16 v[28:31], v[150:153], v[190:193], v[28:31]
	v_mfma_f32_16x16x32_bf16 v[24:27], v[158:161], v[190:193], v[24:27]
	v_mfma_f32_16x16x32_bf16 v[12:15], v[150:153], v[198:201], v[12:15]
	v_mfma_f32_16x16x32_bf16 v[8:11], v[158:161], v[198:201], v[8:11]
	v_mfma_f32_16x16x32_bf16 v[60:63], v[154:157], v[178:181], v[60:63]
	v_mfma_f32_16x16x32_bf16 v[56:59], v[162:165], v[178:181], v[56:59]
	v_mfma_f32_16x16x32_bf16 v[44:47], v[154:157], v[186:189], v[44:47]
	v_mfma_f32_16x16x32_bf16 v[40:43], v[162:165], v[186:189], v[40:43]
	v_mfma_f32_16x16x32_bf16 v[28:31], v[154:157], v[194:197], v[28:31]
	v_mfma_f32_16x16x32_bf16 v[24:27], v[162:165], v[194:197], v[24:27]
	v_mfma_f32_16x16x32_bf16 v[12:15], v[154:157], v[204:207], v[12:15]
	v_mfma_f32_16x16x32_bf16 v[8:11], v[162:165], v[204:207], v[8:11]
	s_setprio 0
	s_barrier
; #define G_STAGE(bufoff, gbase, voff) do { _Pragma("unroll") for (int _i = 0; _i < 2; ++_i) \
;         __builtin_amdgcn_global_load_lds((const unsigned*)((const char*)(gbase) + (voff)[_i]), (LAS unsigned*)(lds + (bufoff) + ldsw + _i * 8192), 16, 0, 0); } while (0)
; #define G_LDA(dst, b, h) do { _Pragma("unroll") for (int m = 0; m < 4; ++m) _Pragma("unroll") for (int k = 0; k < 2; ++k) dst[m][k] = *(const LAS bf16x8*)(lds + G_SA(b, h) + aoff + m * 2048 + k * 1024); } while (0)
; #define G_LDB(dst, b, h) do { _Pragma("unroll") for (int n = 0; n < 2; ++n) _Pragma("unroll") for (int k = 0; k < 2; ++k) dst[n][k] = *(const LAS bf16x8*)(lds + G_SB(b, h) + boff + n * 2048 + k * 1024); } while (0)
; #define G_MMA(ai, bj, At, Bt_) do { __builtin_amdgcn_s_setprio(1); _Pragma("unroll") for (int m = 0; m < 4; ++m) _Pragma("unroll") for (int n = 0; n < 2; ++n) _Pragma("unroll") for (int k = 0; k < 2; ++k) \
;         acc[ai][bj][m][n] = __builtin_amdgcn_mfma_f32_16x16x32_bf16(Bt_[n][k], At[m][k], acc[ai][bj][m][n], 0, 0, 0); __builtin_amdgcn_s_setprio(0); } while (0)
; #define G_WAIT_V(n) asm volatile("s_waitcnt vmcnt(" #n ")" ::: "memory")
; #define G_WAIT_L(n) asm volatile("s_waitcnt lgkmcnt(" #n ")" ::: "memory")
; #define G_BAR __builtin_amdgcn_s_barrier()
; #define G_SCHED __builtin_amdgcn_sched_barrier(0)
; template <class Epi, bool PERMROWS = false>
; DI void gemm_phase(LAS unsigned char* lds, const bf16_t* A, int lda, const bf16_t* Bt, int K, const Sched& S, const Epi& E) {
;     ...
;             G_STAGE(G_SB(0, 1), b2 + hstepB, voffB);
;             G_WAIT_V(6); G_BAR; G_MMA(1, 1, At, B1); G_BAR;
;             G_LDB(B0, 1, 0); G_SCHED; G_LDA(At, 1, 0); G_STAGE(G_SA(0, 1), a2 + hstepA, voffA);
;             G_WAIT_L(8); G_BAR; G_WAIT_L(0); G_MMA(0, 0, At, B0); G_BAR; G_SCHED;
;             G_LDB(B1, 1, 1); G_STAGE(G_SB(1, 0), b3, voffB);
;             G_BAR; G_WAIT_L(0); G_MMA(0, 1, At, B1); G_BAR;
;             G_LDA(At, 1, 1); G_STAGE(G_SA(1, 0), a3, voffA);
;             G_BAR; G_WAIT_L(0); G_MMA(1, 0, At, B0); G_BAR; G_SCHED;
	s_add_u32 s28, s12, 0x80000
	s_addc_u32 s29, s13, 0
	s_add_i32 s63, s86, s70
	v_lshl_add_u64 v[150:151], s[28:29], 0, v[128:129]
	s_mov_b32 m0, s63
	s_nop 0
	global_load_lds_dwordx4 v[150:151], off
	v_lshl_add_u64 v[150:151], s[28:29], 0, v[130:131]
	s_add_i32 m0, s63, 0x2000
	s_nop 0
	global_load_lds_dwordx4 v[150:151], off
	s_waitcnt vmcnt(6)
	s_barrier
	s_setprio 1
	v_mfma_f32_16x16x32_bf16 v[52:55], v[208:211], v[166:169], v[52:55]
	v_mfma_f32_16x16x32_bf16 v[48:51], v[216:219], v[166:169], v[48:51]
	v_mfma_f32_16x16x32_bf16 v[36:39], v[208:211], v[182:185], v[36:39]
	v_mfma_f32_16x16x32_bf16 v[32:35], v[216:219], v[182:185], v[32:35]
	v_mfma_f32_16x16x32_bf16 v[20:23], v[208:211], v[190:193], v[20:23]
	v_mfma_f32_16x16x32_bf16 v[16:19], v[216:219], v[190:193], v[16:19]
	v_mfma_f32_16x16x32_bf16 v[4:7], v[208:211], v[198:201], v[4:7]
	v_mfma_f32_16x16x32_bf16 v[0:3], v[216:219], v[198:201], v[0:3]
	v_mfma_f32_16x16x32_bf16 v[52:55], v[212:215], v[178:181], v[52:55]
	v_mfma_f32_16x16x32_bf16 v[48:51], v[220:223], v[178:181], v[48:51]
	v_mfma_f32_16x16x32_bf16 v[36:39], v[212:215], v[186:189], v[36:39]
	v_mfma_f32_16x16x32_bf16 v[32:35], v[220:223], v[186:189], v[32:35]
	v_mfma_f32_16x16x32_bf16 v[20:23], v[212:215], v[194:197], v[20:23]
	v_mfma_f32_16x16x32_bf16 v[16:19], v[220:223], v[194:197], v[16:19]
	v_mfma_f32_16x16x32_bf16 v[4:7], v[212:215], v[204:207], v[4:7]
	v_mfma_f32_16x16x32_bf16 v[0:3], v[220:223], v[204:207], v[0:3]
	s_setprio 0
	s_add_i32 s63, 0, 0x18000
	v_add_u32_e32 v132, s63, v170
	s_barrier
	ds_read_b128 v[150:153], v132
	ds_read_b128 v[154:157], v132 offset:1024
	ds_read_b128 v[158:161], v132 offset:2048
	ds_read_b128 v[162:165], v132 offset:3072
	s_add_u32 s28, s56, 0x80000
	s_addc_u32 s29, s57, 0
	s_mov_b32 m0, s73
	v_lshl_add_u64 v[208:209], s[28:29], 0, v[128:129]
	ds_read_b128 v[166:169], v175 offset:32768
	ds_read_b128 v[178:181], v175 offset:33792
	ds_read_b128 v[182:185], v175 offset:34816
	ds_read_b128 v[186:189], v175 offset:35840
	ds_read_b128 v[190:193], v175 offset:36864
	ds_read_b128 v[194:197], v175 offset:37888
	ds_read_b128 v[198:201], v175 offset:38912
	ds_read_b128 v[204:207], v175 offset:39936
	global_load_lds_dwordx4 v[208:209], off
	v_lshl_add_u64 v[208:209], s[28:29], 0, v[130:131]
	s_mov_b32 m0, s74
	s_nop 0
	global_load_lds_dwordx4 v[208:209], off
	s_waitcnt lgkmcnt(8)
	s_barrier
	s_waitcnt lgkmcnt(0)
	s_setprio 1
	s_waitcnt lgkmcnt(0)
	v_mfma_f32_16x16x32_bf16 v[124:127], v[150:153], v[166:169], v[124:127]
	v_mfma_f32_16x16x32_bf16 v[120:123], v[158:161], v[166:169], v[120:123]
	v_mfma_f32_16x16x32_bf16 v[108:111], v[150:153], v[182:185], v[108:111]
	v_mfma_f32_16x16x32_bf16 v[104:107], v[158:161], v[182:185], v[104:107]
	v_mfma_f32_16x16x32_bf16 v[92:95], v[150:153], v[190:193], v[92:95]
	v_mfma_f32_16x16x32_bf16 v[88:91], v[158:161], v[190:193], v[88:91]
	v_mfma_f32_16x16x32_bf16 v[76:79], v[150:153], v[198:201], v[76:79]
	v_mfma_f32_16x16x32_bf16 v[72:75], v[158:161], v[198:201], v[72:75]
	v_mfma_f32_16x16x32_bf16 v[124:127], v[154:157], v[178:181], v[124:127]
	v_mfma_f32_16x16x32_bf16 v[120:123], v[162:165], v[178:181], v[120:123]
	v_mfma_f32_16x16x32_bf16 v[108:111], v[154:157], v[186:189], v[108:111]
	v_mfma_f32_16x16x32_bf16 v[104:107], v[162:165], v[186:189], v[104:107]
	v_mfma_f32_16x16x32_bf16 v[92:95], v[154:157], v[194:197], v[92:95]
	v_mfma_f32_16x16x32_bf16 v[88:91], v[162:165], v[194:197], v[88:91]
	v_mfma_f32_16x16x32_bf16 v[76:79], v[154:157], v[204:207], v[76:79]
	v_mfma_f32_16x16x32_bf16 v[72:75], v[162:165], v[204:207], v[72:75]
	s_setprio 0
	s_barrier
	s_add_i32 s28, 0, 0x1c000
	s_add_i32 s29, s63, s70
	v_add_u32_e32 v132, s28, v170
	v_lshl_add_u64 v[224:225], v[224:225], 0, s[14:15]
	s_mov_b32 m0, s29
	ds_read_b128 v[208:211], v132
	ds_read_b128 v[212:215], v132 offset:1024
	ds_read_b128 v[216:219], v132 offset:2048
	ds_read_b128 v[220:223], v132 offset:3072
	global_load_lds_dwordx4 v[224:225], off
	v_lshl_add_u64 v[224:225], v[226:227], 0, s[14:15]
	s_add_i32 m0, s29, 0x2000
	s_nop 0
	global_load_lds_dwordx4 v[224:225], off
	s_barrier
	s_waitcnt lgkmcnt(0)
	s_setprio 1
	s_waitcnt lgkmcnt(0)
	v_mfma_f32_16x16x32_bf16 v[116:119], v[208:211], v[166:169], v[116:119]
	v_mfma_f32_16x16x32_bf16 v[112:115], v[216:219], v[166:169], v[112:115]
	v_mfma_f32_16x16x32_bf16 v[100:103], v[208:211], v[182:185], v[100:103]
	v_mfma_f32_16x16x32_bf16 v[96:99], v[216:219], v[182:185], v[96:99]
	v_mfma_f32_16x16x32_bf16 v[84:87], v[208:211], v[190:193], v[84:87]
	v_mfma_f32_16x16x32_bf16 v[80:83], v[216:219], v[190:193], v[80:83]
	v_mfma_f32_16x16x32_bf16 v[68:71], v[208:211], v[198:201], v[68:71]
	v_mfma_f32_16x16x32_bf16 v[64:67], v[216:219], v[198:201], v[64:67]
	v_mfma_f32_16x16x32_bf16 v[116:119], v[212:215], v[178:181], v[116:119]
	v_mfma_f32_16x16x32_bf16 v[112:115], v[220:223], v[178:181], v[112:115]
	v_mfma_f32_16x16x32_bf16 v[100:103], v[212:215], v[186:189], v[100:103]
	v_mfma_f32_16x16x32_bf16 v[96:99], v[220:223], v[186:189], v[96:99]
	v_mfma_f32_16x16x32_bf16 v[84:87], v[212:215], v[194:197], v[84:87]
	v_mfma_f32_16x16x32_bf16 v[80:83], v[220:223], v[194:197], v[80:83]
	v_mfma_f32_16x16x32_bf16 v[68:71], v[212:215], v[204:207], v[68:71]
	v_mfma_f32_16x16x32_bf16 v[64:67], v[220:223], v[204:207], v[64:67]
	s_setprio 0
	s_mov_b32 m0, s76
	v_lshl_add_u64 v[224:225], v[228:229], 0, s[14:15]
	s_barrier
	ds_read_b128 v[166:169], v175 offset:49152
	ds_read_b128 v[178:181], v175 offset:50176
	ds_read_b128 v[182:185], v175 offset:51200
	ds_read_b128 v[186:189], v175 offset:52224
	ds_read_b128 v[190:193], v175 offset:53248
	ds_read_b128 v[194:197], v175 offset:54272
	ds_read_b128 v[198:201], v175 offset:55296
	ds_read_b128 v[204:207], v175 offset:56320
	global_load_lds_dwordx4 v[224:225], off
	v_lshl_add_u64 v[224:225], v[230:231], 0, s[14:15]
	s_mov_b32 m0, s77
	s_nop 0
	global_load_lds_dwordx4 v[224:225], off
	s_barrier
; #define G_STAGE(bufoff, gbase, voff) do { _Pragma("unroll") for (int _i = 0; _i < 2; ++_i) \
;         __builtin_amdgcn_global_load_lds((const unsigned*)((const char*)(gbase) + (voff)[_i]), (LAS unsigned*)(lds + (bufoff) + ldsw + _i * 8192), 16, 0, 0); } while (0)
; #define G_LDA(dst, b, h) do { _Pragma("unroll") for (int m = 0; m < 4; ++m) _Pragma("unroll") for (int k = 0; k < 2; ++k) dst[m][k] = *(const LAS bf16x8*)(lds + G_SA(b, h) + aoff + m * 2048 + k * 1024); } while (0)
; #define G_LDB(dst, b, h) do { _Pragma("unroll") for (int n = 0; n < 2; ++n) _Pragma("unroll") for (int k = 0; k < 2; ++k) dst[n][k] = *(const LAS bf16x8*)(lds + G_SB(b, h) + boff + n * 2048 + k * 1024); } while (0)
; #define G_BAR __builtin_amdgcn_s_barrier()
; template <class Epi, bool PERMROWS = false>
; DI void gemm_phase(LAS unsigned char* lds, const bf16_t* A, int lda, const bf16_t* Bt, int K, const Sched& S, const Epi& E) {
;     ...
;             G_WAIT_V(6); G_BAR; G_MMA(1, 1, At, B1); G_BAR;
;             G_LDB(B0, 1, 0); G_SCHED; G_LDA(At, 1, 0); G_STAGE(G_SA(0, 1), a2 + hstepA, voffA);
;             G_WAIT_L(8); G_BAR; G_WAIT_L(0); G_MMA(0, 0, At, B0); G_BAR; G_SCHED;
;             G_LDB(B1, 1, 1); G_STAGE(G_SB(1, 0), b3, voffB);
;             G_BAR; G_WAIT_L(0); G_MMA(0, 1, At, B1); G_BAR;
;             G_LDA(At, 1, 1); G_STAGE(G_SA(1, 0), a3, voffA);
;             G_BAR; G_WAIT_L(0); G_MMA(1, 0, At, B0); G_BAR; G_SCHED;
;             G_STAGE(G_SB(1, 1), b3 + hstepB, voffB);
;             G_WAIT_V(6); G_BAR; G_MMA(1, 1, At, B1); G_BAR;
;     DI void operator()(const f32x4 (&acc)[2][2][4][2], const Unit& u, int wr, int wc, int fr, int fq) const {
;         bf16_t* P = (bf16_t*)(ws + WS_P);
;         const int b = u.pm / 9;
; #pragma unroll
;         for (int ai = 0; ai < 2; ++ai)
; #pragma unroll
;             for (int m = 0; m < 4; ++m) {
;                 const int row = u.pm * BM + ai * HALF + wr * 64 + m * 16 + fr;
;                 const int r = row - b * RB; const bool lat = r >= CL; const int t = r - CL;
; #pragma unroll
;                 for (int bj = 0; bj < 2; ++bj) {
;                     const int colg = u.pn * BM + bj * HALF + wc * 32;
;                     f32x4 v0 = acc[ai][bj][m][0], v1 = acc[ai][bj][m][1];
;                     const int c0 = colg + 4 * fq;
;                     if (colg >= INW) continue;
;                     if (colg >= C_NAV && colg < C_CQ) {
	s_waitcnt lgkmcnt(0)
	s_setprio 1
	s_waitcnt lgkmcnt(0)
	v_mfma_f32_16x16x32_bf16 v[60:63], v[150:153], v[166:169], v[60:63]
	v_mfma_f32_16x16x32_bf16 v[56:59], v[158:161], v[166:169], v[56:59]
	v_mfma_f32_16x16x32_bf16 v[44:47], v[150:153], v[182:185], v[44:47]
	v_mfma_f32_16x16x32_bf16 v[40:43], v[158:161], v[182:185], v[40:43]
	v_mfma_f32_16x16x32_bf16 v[28:31], v[150:153], v[190:193], v[28:31]
	v_mfma_f32_16x16x32_bf16 v[24:27], v[158:161], v[190:193], v[24:27]
	v_mfma_f32_16x16x32_bf16 v[12:15], v[150:153], v[198:201], v[12:15]
	v_mfma_f32_16x16x32_bf16 v[8:11], v[158:161], v[198:201], v[8:11]
	v_mfma_f32_16x16x32_bf16 v[60:63], v[154:157], v[178:181], v[60:63]
	v_mfma_f32_16x16x32_bf16 v[56:59], v[162:165], v[178:181], v[56:59]
	v_mfma_f32_16x16x32_bf16 v[44:47], v[154:157], v[186:189], v[44:47]
	v_mfma_f32_16x16x32_bf16 v[40:43], v[162:165], v[186:189], v[40:43]
	v_mfma_f32_16x16x32_bf16 v[28:31], v[154:157], v[194:197], v[28:31]
	v_mfma_f32_16x16x32_bf16 v[24:27], v[162:165], v[194:197], v[24:27]
	v_mfma_f32_16x16x32_bf16 v[12:15], v[154:157], v[204:207], v[12:15]
	v_mfma_f32_16x16x32_bf16 v[8:11], v[162:165], v[204:207], v[8:11]
	s_setprio 0
	s_barrier
	s_add_u32 s12, s12, 0x80080
	s_addc_u32 s13, s13, 0
	s_add_i32 s28, s28, s70
	v_lshl_add_u64 v[150:151], s[12:13], 0, v[128:129]
	s_mov_b32 m0, s28
	s_nop 0
	global_load_lds_dwordx4 v[150:151], off
	v_lshl_add_u64 v[150:151], s[12:13], 0, v[130:131]
	s_add_i32 m0, s28, 0x2000
	s_nop 0
	global_load_lds_dwordx4 v[150:151], off
	s_waitcnt vmcnt(6)
	s_barrier
	s_setprio 1
	v_mfma_f32_16x16x32_bf16 v[52:55], v[208:211], v[166:169], v[52:55]
	v_mfma_f32_16x16x32_bf16 v[48:51], v[216:219], v[166:169], v[48:51]
	v_mfma_f32_16x16x32_bf16 v[36:39], v[208:211], v[182:185], v[36:39]
	v_mfma_f32_16x16x32_bf16 v[32:35], v[216:219], v[182:185], v[32:35]
	v_mfma_f32_16x16x32_bf16 v[20:23], v[208:211], v[190:193], v[20:23]
	v_mfma_f32_16x16x32_bf16 v[16:19], v[216:219], v[190:193], v[16:19]
	v_mfma_f32_16x16x32_bf16 v[4:7], v[208:211], v[198:201], v[4:7]
	v_mfma_f32_16x16x32_bf16 v[0:3], v[216:219], v[198:201], v[0:3]
	v_mfma_f32_16x16x32_bf16 v[52:55], v[212:215], v[178:181], v[52:55]
	v_mfma_f32_16x16x32_bf16 v[48:51], v[220:223], v[178:181], v[48:51]
	v_mfma_f32_16x16x32_bf16 v[36:39], v[212:215], v[186:189], v[36:39]
	v_mfma_f32_16x16x32_bf16 v[32:35], v[220:223], v[186:189], v[32:35]
	v_mfma_f32_16x16x32_bf16 v[20:23], v[212:215], v[194:197], v[20:23]
	v_mfma_f32_16x16x32_bf16 v[16:19], v[220:223], v[194:197], v[16:19]
	v_mfma_f32_16x16x32_bf16 v[4:7], v[212:215], v[204:207], v[4:7]
	v_mfma_f32_16x16x32_bf16 v[0:3], v[220:223], v[204:207], v[0:3]
	s_setprio 0
	s_add_i32 s62, s62, 2
	s_add_u32 s35, s35, 0x100
	s_addc_u32 s37, s37, 0
	s_add_u32 s10, s10, 0x100
	s_addc_u32 s11, s11, 0
	s_cmp_gt_u32 s62, 29
	s_barrier
	s_cbranch_scc0 .LBB0_534
	v_bfe_u32 v194, v202, 6, 2
	v_and_b32_e32 v169, 15, v202
	v_readfirstlane_b32 s9, v194
	s_lshl_b32 s35, s0, 8
	s_lshl_b32 s93, s9, 5
	s_add_u32 s35, s35, s93
	s_mov_b32 s37, 1
	s_cmpk_lt_u32 s35, 0x600
	s_cbranch_scc1 .Lip0_c0_d
	s_mov_b32 s37, 4
	s_cmpk_lt_u32 s35, 0x900
	s_cbranch_scc1 .Lip0_c0_d
	s_mov_b32 s37, 6
	s_cmpk_lt_u32 s35, 0xd00
	s_cbranch_scc1 .Lip0_c0_d
	s_cmpk_lt_u32 s35, 0xd40
	s_cbranch_scc1 .Lip0_old
	s_mov_b32 s37, 2
	s_cmpk_lt_u32 s35, 0xfc0
	s_cbranch_scc1 .Lip0_c0_d
	s_mov_b32 s37, 3
	s_cmpk_lt_u32 s35, 0x1240
	s_cbranch_scc1 .Lip0_c0_d
	s_mov_b32 s37, 5
	s_cmpk_lt_u32 s35, 0x14c0
	s_cbranch_scc1 .Lip0_c0_d
	s_mov_b32 s37, 1
	s_cmpk_lt_u32 s35, 0x1740
	s_cbranch_scc1 .Lip0_c0_d
	s_mov_b32 s37, 0
.Lip0_c0_d:
	s_add_u32 s35, s35, 0x80
	s_mov_b32 s92, 1
	s_cmpk_lt_u32 s35, 0x600
	s_cbranch_scc1 .Lip0_c1_d
	s_mov_b32 s92, 4
	s_cmpk_lt_u32 s35, 0x900
	s_cbranch_scc1 .Lip0_c1_d
	s_mov_b32 s92, 6
	s_cmpk_lt_u32 s35, 0xd00
	s_cbranch_scc1 .Lip0_c1_d
	s_cmpk_lt_u32 s35, 0xd40
	s_cbranch_scc1 .Lip0_old
	s_mov_b32 s92, 2
	s_cmpk_lt_u32 s35, 0xfc0
	s_cbranch_scc1 .Lip0_c1_d
	s_mov_b32 s92, 3
	s_cmpk_lt_u32 s35, 0x1240
	s_cbranch_scc1 .Lip0_c1_d
	s_mov_b32 s92, 5
	s_cmpk_lt_u32 s35, 0x14c0
	s_cbranch_scc1 .Lip0_c1_d
	s_mov_b32 s92, 1
	s_cmpk_lt_u32 s35, 0x1740
	s_cbranch_scc1 .Lip0_c1_d
	s_mov_b32 s92, 0
.Lip0_c1_d:
	s_sub_u32 s35, s35, 0x80
	v_bfe_u32 v194, v202, 8, 1
	v_lshl_add_u32 v195, v194, 6, v169
	v_bfe_u32 v196, v202, 4, 2
	v_and_b32_e32 v197, 63, v202
	s_mul_i32 s32, s8, 57
	s_lshr_b32 s32, s32, 9
	s_mul_i32 s93, s32, 9
	s_sub_u32 s27, s8, s93
	v_mul_u32_u24_e32 v169, 0x3000, v195
	v_lshl_add_u32 v150, v196, 3, v169
	v_add_u32_e32 v151, 0x30000, v150
	v_add_u32_e32 v152, 0x60000, v150
	v_add_u32_e32 v153, 0x90000, v150
	v_add_u32_e32 v154, 0x180000, v150
	v_add_u32_e32 v155, 0x1b0000, v150
	v_add_u32_e32 v156, 0x1e0000, v150
	v_add_u32_e32 v157, 0x210000, v150
	v_lshrrev_b32_e32 v169, 6, v202
	v_lshlrev_b32_e32 v169, 10, v169
	v_add_u32_e32 v169, 0x20000, v169
	v_and_b32_e32 v194, 15, v202
	v_lshl_add_u32 v167, v196, 7, v169
	v_lshl_add_u32 v167, v194, 1, v167
	v_lshrrev_b32_e32 v194, 1, v197
	v_lshl_add_u32 v168, v194, 5, v169
	v_and_b32_e32 v169, 1, v197
	v_lshl_add_u32 v168, v169, 4, v168
	v_mul_u32_u24_e32 v166, 0x1200, v194
	v_lshl_add_u32 v166, v169, 4, v166
	v_bfe_u32 v169, v202, 8, 1
	v_lshl_add_u32 v166, v169, 7, v166
	s_cmp_eq_u32 s37, 0
	s_cbranch_scc1 .Lip0_k0_end
	s_cmp_eq_u32 s37, 1
	s_cbranch_scc1 .Lip0_k0_plain
	s_cmp_eq_u32 s37, 4
	s_cbranch_scc1 .Lip0_k0_nav
	s_cmp_eq_u32 s37, 5
	s_cbranch_scc1 .Lip0_k0_rv
	s_cmp_eq_u32 s37, 6
	s_cbranch_scc1 .Lip0_k0_ssq
	s_cmp_eq_u32 s27, 0
	s_cbranch_scc1 .Lip0_nr0
; DI void rope4(f32x4& v0, f32x4& v1, const float* tab  ) {
;     const f32x4 t0 = *(const f32x4*)tab, t1 = *(const f32x4*)(tab + 4);
;     const float c[4] = {t0[0], t0[2], t1[0], t1[2]}, s[4] = {t0[1], t0[3], t1[1], t1[3]};
; #pragma unroll
;     for (int j = 0; j < 4; ++j) { const float a = v0[j], b = v1[j]; v0[j] = a * c[j] - b * s[j]; v1[j] = b * c[j] + a * s[j]; }
; }
;     DI void operator()(const f32x4 (&acc)[2][2][4][2], const Unit& u, int wr, int wc, int fr, int fq) const {
;     ...
;                     } else if (colg >= C_RQ && colg < C_RV) {
;                         if (lat) rope4(v0, v1, (const float*)(ws + WS_TABR) + ((size_t)t * 64 + (((colg - C_RQ) & 127) >> 5) * 16 + 4 * fq) * 2);
	s_sub_u32 s97, s35, 0xd40
	s_and_b32 s97, s97, 0x7f
	s_lshr_b32 s97, s97, 5
	s_lshl_b32 s97, s97, 7
	s_sub_u32 s93, s27, 1
	s_lshl_b32 s93, s93, 17
	s_add_u32 s93, s93, s97
	v_lshlrev_b32_e32 v169, 5, v196
	v_lshl_add_u32 v158, v195, 9, v169
	v_add_u32_e32 v158, s93, v158
	v_add_u32_e32 v159, 0x2000, v158
	v_add_u32_e32 v160, 0x4000, v158
	v_add_u32_e32 v161, 0x6000, v158
	v_add_u32_e32 v162, 0x10000, v158
	v_add_u32_e32 v163, 0x12000, v158
	v_add_u32_e32 v164, 0x14000, v158
	v_add_u32_e32 v165, 0x16000, v158
	s_add_u32 s10, s50, 0x100000
	s_addc_u32 s11, s51, 0
	global_load_dwordx4 v[204:207], v158, s[10:11]
	global_load_dwordx4 v[208:211], v158, s[10:11] offset:16
	global_load_dwordx4 v[212:215], v159, s[10:11]
	global_load_dwordx4 v[216:219], v159, s[10:11] offset:16
	global_load_dwordx4 v[220:223], v160, s[10:11]
	global_load_dwordx4 v[224:227], v160, s[10:11] offset:16
	global_load_dwordx4 v[228:231], v161, s[10:11]
	global_load_dwordx4 v[232:235], v161, s[10:11] offset:16
	global_load_dwordx4 v[236:239], v162, s[10:11]
	global_load_dwordx4 v[240:243], v162, s[10:11] offset:16
	global_load_dwordx4 v[244:247], v163, s[10:11]
	global_load_dwordx4 v[248:251], v163, s[10:11] offset:16
	global_load_dwordx4 v[178:181], v164, s[10:11]
	global_load_dwordx4 v[182:185], v164, s[10:11] offset:16
	global_load_dwordx4 v[186:189], v165, s[10:11]
	global_load_dwordx4 v[190:193], v165, s[10:11] offset:16
	s_waitcnt vmcnt(0)
	v_mul_f32_e32 v169, v124, v205
	v_mul_f32_e32 v124, v124, v204
	v_fma_f32 v124, -v120, v205, v124
	v_fma_f32 v120, v120, v204, v169
	v_mul_f32_e32 v169, v125, v207
	v_mul_f32_e32 v125, v125, v206
	v_fma_f32 v125, -v121, v207, v125
	v_fma_f32 v121, v121, v206, v169
	v_mul_f32_e32 v169, v126, v209
	v_mul_f32_e32 v126, v126, v208
	v_fma_f32 v126, -v122, v209, v126
	v_fma_f32 v122, v122, v208, v169
	v_mul_f32_e32 v169, v127, v211
	v_mul_f32_e32 v127, v127, v210
	v_fma_f32 v127, -v123, v211, v127
	v_fma_f32 v123, v123, v210, v169
	v_mul_f32_e32 v169, v108, v213
	v_mul_f32_e32 v108, v108, v212
	v_fma_f32 v108, -v104, v213, v108
	v_fma_f32 v104, v104, v212, v169
	v_mul_f32_e32 v169, v109, v215
	v_mul_f32_e32 v109, v109, v214
	v_fma_f32 v109, -v105, v215, v109
	v_fma_f32 v105, v105, v214, v169
	v_mul_f32_e32 v169, v110, v217
	v_mul_f32_e32 v110, v110, v216
	v_fma_f32 v110, -v106, v217, v110
	v_fma_f32 v106, v106, v216, v169
	v_mul_f32_e32 v169, v111, v219
	v_mul_f32_e32 v111, v111, v218
	v_fma_f32 v111, -v107, v219, v111
	v_fma_f32 v107, v107, v218, v169
	v_mul_f32_e32 v169, v92, v221
	v_mul_f32_e32 v92, v92, v220
	v_fma_f32 v92, -v88, v221, v92
	v_fma_f32 v88, v88, v220, v169
	v_mul_f32_e32 v169, v93, v223
	v_mul_f32_e32 v93, v93, v222
	v_fma_f32 v93, -v89, v223, v93
	v_fma_f32 v89, v89, v222, v169
	v_mul_f32_e32 v169, v94, v225
	v_mul_f32_e32 v94, v94, v224
	v_fma_f32 v94, -v90, v225, v94
	v_fma_f32 v90, v90, v224, v169
	v_mul_f32_e32 v169, v95, v227
	v_mul_f32_e32 v95, v95, v226
	v_fma_f32 v95, -v91, v227, v95
	v_fma_f32 v91, v91, v226, v169
	v_mul_f32_e32 v169, v76, v229
	v_mul_f32_e32 v76, v76, v228
	v_fma_f32 v76, -v72, v229, v76
	v_fma_f32 v72, v72, v228, v169
	v_mul_f32_e32 v169, v77, v231
	v_mul_f32_e32 v77, v77, v230
	v_fma_f32 v77, -v73, v231, v77
	v_fma_f32 v73, v73, v230, v169
	v_mul_f32_e32 v169, v78, v233
	v_mul_f32_e32 v78, v78, v232
	v_fma_f32 v78, -v74, v233, v78
	v_fma_f32 v74, v74, v232, v169
	v_mul_f32_e32 v169, v79, v235
	v_mul_f32_e32 v79, v79, v234
	v_fma_f32 v79, -v75, v235, v79
	v_fma_f32 v75, v75, v234, v169
	v_mul_f32_e32 v169, v60, v237
	v_mul_f32_e32 v60, v60, v236
	v_fma_f32 v60, -v56, v237, v60
	v_fma_f32 v56, v56, v236, v169
	v_mul_f32_e32 v169, v61, v239
	v_mul_f32_e32 v61, v61, v238
	v_fma_f32 v61, -v57, v239, v61
	v_fma_f32 v57, v57, v238, v169
	v_mul_f32_e32 v169, v62, v241
	v_mul_f32_e32 v62, v62, v240
	v_fma_f32 v62, -v58, v241, v62
	v_fma_f32 v58, v58, v240, v169
	v_mul_f32_e32 v169, v63, v243
	v_mul_f32_e32 v63, v63, v242
	v_fma_f32 v63, -v59, v243, v63
	v_fma_f32 v59, v59, v242, v169
	v_mul_f32_e32 v169, v44, v245
	v_mul_f32_e32 v44, v44, v244
	v_fma_f32 v44, -v40, v245, v44
	v_fma_f32 v40, v40, v244, v169
	v_mul_f32_e32 v169, v45, v247
	v_mul_f32_e32 v45, v45, v246
	v_fma_f32 v45, -v41, v247, v45
	v_fma_f32 v41, v41, v246, v169
	v_mul_f32_e32 v169, v46, v249
	v_mul_f32_e32 v46, v46, v248
	v_fma_f32 v46, -v42, v249, v46
	v_fma_f32 v42, v42, v248, v169
	v_mul_f32_e32 v169, v47, v251
	v_mul_f32_e32 v47, v47, v250
	v_fma_f32 v47, -v43, v251, v47
	v_fma_f32 v43, v43, v250, v169
	v_mul_f32_e32 v169, v28, v179
	v_mul_f32_e32 v28, v28, v178
	v_fma_f32 v28, -v24, v179, v28
	v_fma_f32 v24, v24, v178, v169
	v_mul_f32_e32 v169, v29, v181
	v_mul_f32_e32 v29, v29, v180
	v_fma_f32 v29, -v25, v181, v29
	v_fma_f32 v25, v25, v180, v169
	v_mul_f32_e32 v169, v30, v183
	v_mul_f32_e32 v30, v30, v182
	v_fma_f32 v30, -v26, v183, v30
	v_fma_f32 v26, v26, v182, v169
	v_mul_f32_e32 v169, v31, v185
	v_mul_f32_e32 v31, v31, v184
	v_fma_f32 v31, -v27, v185, v31
	v_fma_f32 v27, v27, v184, v169
	v_mul_f32_e32 v169, v12, v187
	v_mul_f32_e32 v12, v12, v186
	v_fma_f32 v12, -v8, v187, v12
	v_fma_f32 v8, v8, v186, v169
	v_mul_f32_e32 v169, v13, v189
	v_mul_f32_e32 v13, v13, v188
	v_fma_f32 v13, -v9, v189, v13
	v_fma_f32 v9, v9, v188, v169
	v_mul_f32_e32 v169, v14, v191
	v_mul_f32_e32 v14, v14, v190
	v_fma_f32 v14, -v10, v191, v14
	v_fma_f32 v10, v10, v190, v169
	v_mul_f32_e32 v169, v15, v193
	v_mul_f32_e32 v15, v15, v192
	v_fma_f32 v15, -v11, v193, v15
	v_fma_f32 v11, v11, v192, v169
; #define LAS __attribute__((address_space(3)))
; DI unsigned cvt_pk_bf16(float lo, float hi) { unsigned r; asm volatile("v_cvt_pk_bf16_f32 %0, %1, %2" : "=v"(r) : "v"(lo), "v"(hi)); return r; }
; DI void st_bf16x4(bf16_t* p, f32x4 v) { u32x2 w; w.x = cvt_pk_bf16(v[0], v[1]); w.y = cvt_pk_bf16(v[2], v[3]); *(u32x2*)p = w; }
; DI void st_tr16x32(LAS unsigned char* area, bf16_t* dst_f0_t0  , f32x4 v0, f32x4 v1, int fr, int fq, int lane) {
;     const unsigned p01 = cvt_pk_bf16(v0[0], v0[1]), p23 = cvt_pk_bf16(v0[2], v0[3]), q01 = cvt_pk_bf16(v1[0], v1[1]), q23 = cvt_pk_bf16(v1[2], v1[3]);
;     LAS bf16_t* w = (LAS bf16_t*)(area + (4 * fq) * 32 + fr * 2);
;     w[0 * 16] = (bf16_t)(p01 & 0xffffu); w[1 * 16] = (bf16_t)(p01 >> 16); w[2 * 16] = (bf16_t)(p23 & 0xffffu); w[3 * 16] = (bf16_t)(p23 >> 16);
;     w[16 * 16] = (bf16_t)(q01 & 0xffffu); w[17 * 16] = (bf16_t)(q01 >> 16); w[18 * 16] = (bf16_t)(q23 & 0xffffu); w[19 * 16] = (bf16_t)(q23 >> 16);
;     asm volatile("s_waitcnt lgkmcnt(0)" ::: "memory");
;     const u32x4 row = *(const LAS u32x4*)(area + (lane >> 1) * 32 + (lane & 1) * 16);
;     asm volatile("" ::: "memory");
;     *(u32x4*)(dst_f0_t0 + (size_t)(lane >> 1) * RB + (lane & 1) * 8) = row;
; }
;     DI void operator()(const f32x4 (&acc)[2][2][4][2], const Unit& u, int wr, int wc, int fr, int fq) const {
;     ...
;                         if (colg >= C_RK) {
;                             v0 *= 0.08838834764831845f; v1 *= 0.08838834764831845f;
;                             st_tr16x32(spare + (wr * 4 + wc) * 1024, (bf16_t*)(ws + WS_KTR) + ((size_t)b * 640 + (colg - C_RK)) * RB + (r - fr), v0, v1, fr, fq, fq * 16 + fr);
;                         }
;                         st_bf16x4(P + (size_t)row * INP + c0, v0); st_bf16x4(P + (size_t)row * INP + c0 + 16, v1);
.Lip0_nr0:
	s_cmp_eq_u32 s37, 3
	s_cbranch_scc0 .Lip0_k0_plain
	s_mov_b32 s96, 0x3db504f3
	v_mul_f32_e32 v124, s96, v124
	v_mul_f32_e32 v125, s96, v125
	v_mul_f32_e32 v126, s96, v126
	v_mul_f32_e32 v127, s96, v127
	v_mul_f32_e32 v120, s96, v120
	v_mul_f32_e32 v121, s96, v121
	v_mul_f32_e32 v122, s96, v122
	v_mul_f32_e32 v123, s96, v123
	v_mul_f32_e32 v108, s96, v108
	v_mul_f32_e32 v109, s96, v109
	v_mul_f32_e32 v110, s96, v110
	v_mul_f32_e32 v111, s96, v111
	v_mul_f32_e32 v104, s96, v104
	v_mul_f32_e32 v105, s96, v105
	v_mul_f32_e32 v106, s96, v106
	v_mul_f32_e32 v107, s96, v107
	v_mul_f32_e32 v92, s96, v92
	v_mul_f32_e32 v93, s96, v93
	v_mul_f32_e32 v94, s96, v94
	v_mul_f32_e32 v95, s96, v95
	v_mul_f32_e32 v88, s96, v88
	v_mul_f32_e32 v89, s96, v89
	v_mul_f32_e32 v90, s96, v90
	v_mul_f32_e32 v91, s96, v91
	v_mul_f32_e32 v76, s96, v76
	v_mul_f32_e32 v77, s96, v77
	v_mul_f32_e32 v78, s96, v78
	v_mul_f32_e32 v79, s96, v79
	v_mul_f32_e32 v72, s96, v72
	v_mul_f32_e32 v73, s96, v73
	v_mul_f32_e32 v74, s96, v74
	v_mul_f32_e32 v75, s96, v75
	v_mul_f32_e32 v60, s96, v60
	v_mul_f32_e32 v61, s96, v61
	v_mul_f32_e32 v62, s96, v62
	v_mul_f32_e32 v63, s96, v63
	v_mul_f32_e32 v56, s96, v56
	v_mul_f32_e32 v57, s96, v57
	v_mul_f32_e32 v58, s96, v58
	v_mul_f32_e32 v59, s96, v59
	v_mul_f32_e32 v44, s96, v44
	v_mul_f32_e32 v45, s96, v45
	v_mul_f32_e32 v46, s96, v46
	v_mul_f32_e32 v47, s96, v47
	v_mul_f32_e32 v40, s96, v40
	v_mul_f32_e32 v41, s96, v41
	v_mul_f32_e32 v42, s96, v42
	v_mul_f32_e32 v43, s96, v43
	v_mul_f32_e32 v28, s96, v28
	v_mul_f32_e32 v29, s96, v29
	v_mul_f32_e32 v30, s96, v30
	v_mul_f32_e32 v31, s96, v31
	v_mul_f32_e32 v24, s96, v24
	v_mul_f32_e32 v25, s96, v25
	v_mul_f32_e32 v26, s96, v26
	v_mul_f32_e32 v27, s96, v27
	v_mul_f32_e32 v12, s96, v12
	v_mul_f32_e32 v13, s96, v13
	v_mul_f32_e32 v14, s96, v14
	v_mul_f32_e32 v15, s96, v15
	v_mul_f32_e32 v8, s96, v8
	v_mul_f32_e32 v9, s96, v9
	v_mul_f32_e32 v10, s96, v10
	v_mul_f32_e32 v11, s96, v11
	s_mul_i32 s93, s32, 640
	s_add_u32 s93, s93, s35
	s_sub_u32 s93, s93, 0xfc0
	s_mul_i32 s93, s93, 0x900
	s_lshl_b32 s96, s27, 8
	s_add_u32 s93, s93, s96
	s_lshl_b32 s93, s93, 1
	s_add_u32 s10, s50, 0x19860000
	s_addc_u32 s11, s51, 0
	s_add_u32 s10, s10, s93
	s_addc_u32 s11, s11, 0
	v_cvt_pk_bf16_f32 v236, v124, v125
	v_cvt_pk_bf16_f32 v237, v126, v127
	v_cvt_pk_bf16_f32 v238, v120, v121
	v_cvt_pk_bf16_f32 v239, v122, v123
	ds_write_b16 v167, v236 offset:0
	ds_write_b16_d16_hi v167, v236 offset:32
	ds_write_b16 v167, v237 offset:64
	ds_write_b16_d16_hi v167, v237 offset:96
	ds_write_b16 v167, v238 offset:512
	ds_write_b16_d16_hi v167, v238 offset:544
	ds_write_b16 v167, v239 offset:576
	ds_write_b16_d16_hi v167, v239 offset:608
	ds_read_b128 v[204:207], v168
	v_cvt_pk_bf16_f32 v240, v108, v109
	v_cvt_pk_bf16_f32 v241, v110, v111
	v_cvt_pk_bf16_f32 v242, v104, v105
	v_cvt_pk_bf16_f32 v243, v106, v107
	ds_write_b16 v167, v240 offset:0
	ds_write_b16_d16_hi v167, v240 offset:32
	ds_write_b16 v167, v241 offset:64
	ds_write_b16_d16_hi v167, v241 offset:96
	ds_write_b16 v167, v242 offset:512
	ds_write_b16_d16_hi v167, v242 offset:544
	ds_write_b16 v167, v243 offset:576
	ds_write_b16_d16_hi v167, v243 offset:608
	ds_read_b128 v[208:211], v168
	s_waitcnt lgkmcnt(9)
	global_store_dwordx4 v166, v[204:207], s[10:11] offset:0
	v_cvt_pk_bf16_f32 v236, v92, v93
	v_cvt_pk_bf16_f32 v237, v94, v95
	v_cvt_pk_bf16_f32 v238, v88, v89
	v_cvt_pk_bf16_f32 v239, v90, v91
	ds_write_b16 v167, v236 offset:0
	ds_write_b16_d16_hi v167, v236 offset:32
	ds_write_b16 v167, v237 offset:64
	ds_write_b16_d16_hi v167, v237 offset:96
	ds_write_b16 v167, v238 offset:512
	ds_write_b16_d16_hi v167, v238 offset:544
	ds_write_b16 v167, v239 offset:576
	ds_write_b16_d16_hi v167, v239 offset:608
	ds_read_b128 v[204:207], v168
	s_waitcnt lgkmcnt(9)
	global_store_dwordx4 v166, v[208:211], s[10:11] offset:32
	v_cvt_pk_bf16_f32 v240, v76, v77
	v_cvt_pk_bf16_f32 v241, v78, v79
	v_cvt_pk_bf16_f32 v242, v72, v73
	v_cvt_pk_bf16_f32 v243, v74, v75
	ds_write_b16 v167, v240 offset:0
	ds_write_b16_d16_hi v167, v240 offset:32
	ds_write_b16 v167, v241 offset:64
	ds_write_b16_d16_hi v167, v241 offset:96
	ds_write_b16 v167, v242 offset:512
	ds_write_b16_d16_hi v167, v242 offset:544
	ds_write_b16 v167, v243 offset:576
	ds_write_b16_d16_hi v167, v243 offset:608
	ds_read_b128 v[208:211], v168
	s_waitcnt lgkmcnt(9)
	global_store_dwordx4 v166, v[204:207], s[10:11] offset:64
	v_cvt_pk_bf16_f32 v236, v60, v61
	v_cvt_pk_bf16_f32 v237, v62, v63
	v_cvt_pk_bf16_f32 v238, v56, v57
	v_cvt_pk_bf16_f32 v239, v58, v59
	ds_write_b16 v167, v236 offset:0
	ds_write_b16_d16_hi v167, v236 offset:32
	ds_write_b16 v167, v237 offset:64
	ds_write_b16_d16_hi v167, v237 offset:96
	ds_write_b16 v167, v238 offset:512
	ds_write_b16_d16_hi v167, v238 offset:544
	ds_write_b16 v167, v239 offset:576
	ds_write_b16_d16_hi v167, v239 offset:608
	ds_read_b128 v[204:207], v168
	s_waitcnt lgkmcnt(9)
	global_store_dwordx4 v166, v[208:211], s[10:11] offset:96
	v_cvt_pk_bf16_f32 v240, v44, v45
	v_cvt_pk_bf16_f32 v241, v46, v47
	v_cvt_pk_bf16_f32 v242, v40, v41
	v_cvt_pk_bf16_f32 v243, v42, v43
	ds_write_b16 v167, v240 offset:0
	ds_write_b16_d16_hi v167, v240 offset:32
	ds_write_b16 v167, v241 offset:64
	ds_write_b16_d16_hi v167, v241 offset:96
	ds_write_b16 v167, v242 offset:512
	ds_write_b16_d16_hi v167, v242 offset:544
	ds_write_b16 v167, v243 offset:576
	ds_write_b16_d16_hi v167, v243 offset:608
	ds_read_b128 v[208:211], v168
	s_waitcnt lgkmcnt(9)
	global_store_dwordx4 v166, v[204:207], s[10:11] offset:256
	v_cvt_pk_bf16_f32 v236, v28, v29
	v_cvt_pk_bf16_f32 v237, v30, v31
	v_cvt_pk_bf16_f32 v238, v24, v25
	v_cvt_pk_bf16_f32 v239, v26, v27
	ds_write_b16 v167, v236 offset:0
	ds_write_b16_d16_hi v167, v236 offset:32
	ds_write_b16 v167, v237 offset:64
	ds_write_b16_d16_hi v167, v237 offset:96
	ds_write_b16 v167, v238 offset:512
	ds_write_b16_d16_hi v167, v238 offset:544
	ds_write_b16 v167, v239 offset:576
	ds_write_b16_d16_hi v167, v239 offset:608
	ds_read_b128 v[204:207], v168
	s_waitcnt lgkmcnt(9)
	global_store_dwordx4 v166, v[208:211], s[10:11] offset:288
	v_cvt_pk_bf16_f32 v240, v12, v13
	v_cvt_pk_bf16_f32 v241, v14, v15
	v_cvt_pk_bf16_f32 v242, v8, v9
	v_cvt_pk_bf16_f32 v243, v10, v11
	ds_write_b16 v167, v240 offset:0
	ds_write_b16_d16_hi v167, v240 offset:32
	ds_write_b16 v167, v241 offset:64
	ds_write_b16_d16_hi v167, v241 offset:96
	ds_write_b16 v167, v242 offset:512
	ds_write_b16_d16_hi v167, v242 offset:544
	ds_write_b16 v167, v243 offset:576
	ds_write_b16_d16_hi v167, v243 offset:608
	ds_read_b128 v[208:211], v168
	s_waitcnt lgkmcnt(9)
	global_store_dwordx4 v166, v[204:207], s[10:11] offset:320
	s_waitcnt lgkmcnt(0)
	global_store_dwordx4 v166, v[208:211], s[10:11] offset:352
	s_nop 1
; #define LAS __attribute__((address_space(3)))
; DI unsigned cvt_pk_bf16(float lo, float hi) { unsigned r; asm volatile("v_cvt_pk_bf16_f32 %0, %1, %2" : "=v"(r) : "v"(lo), "v"(hi)); return r; }
; DI void st_bf16x4(bf16_t* p, f32x4 v) { u32x2 w; w.x = cvt_pk_bf16(v[0], v[1]); w.y = cvt_pk_bf16(v[2], v[3]); *(u32x2*)p = w; }
; DI void st_tr16x32(LAS unsigned char* area, bf16_t* dst_f0_t0  , f32x4 v0, f32x4 v1, int fr, int fq, int lane) {
;     const unsigned p01 = cvt_pk_bf16(v0[0], v0[1]), p23 = cvt_pk_bf16(v0[2], v0[3]), q01 = cvt_pk_bf16(v1[0], v1[1]), q23 = cvt_pk_bf16(v1[2], v1[3]);
;     LAS bf16_t* w = (LAS bf16_t*)(area + (4 * fq) * 32 + fr * 2);
;     w[0 * 16] = (bf16_t)(p01 & 0xffffu); w[1 * 16] = (bf16_t)(p01 >> 16); w[2 * 16] = (bf16_t)(p23 & 0xffffu); w[3 * 16] = (bf16_t)(p23 >> 16);
;     w[16 * 16] = (bf16_t)(q01 & 0xffffu); w[17 * 16] = (bf16_t)(q01 >> 16); w[18 * 16] = (bf16_t)(q23 & 0xffffu); w[19 * 16] = (bf16_t)(q23 >> 16);
;     asm volatile("s_waitcnt lgkmcnt(0)" ::: "memory");
;     const u32x4 row = *(const LAS u32x4*)(area + (lane >> 1) * 32 + (lane & 1) * 16);
;     asm volatile("" ::: "memory");
;     *(u32x4*)(dst_f0_t0 + (size_t)(lane >> 1) * RB + (lane & 1) * 8) = row;
; }
;     DI void operator()(const f32x4 (&acc)[2][2][4][2], const Unit& u, int wr, int wc, int fr, int fq) const {
;     ...
;                         st_bf16x4(P + (size_t)row * INP + c0, v0); st_bf16x4(P + (size_t)row * INP + c0 + 16, v1);
;                     } else {
;                         if (colg >= C_CQ && colg < C_KPE) {
;                             float ss = v0[0] * v0[0] + v0[1] * v0[1] + v0[2] * v0[2] + v0[3] * v0[3] + v1[0] * v1[0] + v1[1] * v1[1] + v1[2] * v1[2] + v1[3] * v1[3];
;                             ss += __shfl_xor(ss, 16); ss += __shfl_xor(ss, 32);
;                             if (fq == 0) ((float*)(ws + WS_SSQ))[(size_t)row * 32 + ((colg - C_CQ) >> 5)] = ss;
;                         }
;                         st_bf16x4(P + (size_t)row * INP + c0, v0); st_bf16x4(P + (size_t)row * INP + c0 + 16, v1);
.Lip0_k0_plain:
	s_mul_i32 s93, s8, 0x300000
	s_add_u32 s2, s50, 0x113a0000
	s_addc_u32 s3, s51, 0
	s_add_u32 s2, s2, s93
	s_addc_u32 s3, s3, 0
	s_lshl_b32 s93, s35, 1
	s_add_u32 s2, s2, s93
	s_addc_u32 s3, s3, 0
	v_cvt_pk_bf16_f32 v124, v124, v125
	v_cvt_pk_bf16_f32 v125, v126, v127
	global_store_dwordx2 v150, v[124:125], s[2:3] offset:0
	v_cvt_pk_bf16_f32 v120, v120, v121
	v_cvt_pk_bf16_f32 v121, v122, v123
	global_store_dwordx2 v150, v[120:121], s[2:3] offset:32
	v_cvt_pk_bf16_f32 v108, v108, v109
	v_cvt_pk_bf16_f32 v109, v110, v111
	global_store_dwordx2 v151, v[108:109], s[2:3] offset:0
	v_cvt_pk_bf16_f32 v104, v104, v105
	v_cvt_pk_bf16_f32 v105, v106, v107
	global_store_dwordx2 v151, v[104:105], s[2:3] offset:32
	v_cvt_pk_bf16_f32 v92, v92, v93
	v_cvt_pk_bf16_f32 v93, v94, v95
	global_store_dwordx2 v152, v[92:93], s[2:3] offset:0
	v_cvt_pk_bf16_f32 v88, v88, v89
	v_cvt_pk_bf16_f32 v89, v90, v91
	global_store_dwordx2 v152, v[88:89], s[2:3] offset:32
	v_cvt_pk_bf16_f32 v76, v76, v77
	v_cvt_pk_bf16_f32 v77, v78, v79
	global_store_dwordx2 v153, v[76:77], s[2:3] offset:0
	v_cvt_pk_bf16_f32 v72, v72, v73
	v_cvt_pk_bf16_f32 v73, v74, v75
	global_store_dwordx2 v153, v[72:73], s[2:3] offset:32
	v_cvt_pk_bf16_f32 v60, v60, v61
	v_cvt_pk_bf16_f32 v61, v62, v63
	global_store_dwordx2 v154, v[60:61], s[2:3] offset:0
	v_cvt_pk_bf16_f32 v56, v56, v57
	v_cvt_pk_bf16_f32 v57, v58, v59
	global_store_dwordx2 v154, v[56:57], s[2:3] offset:32
	v_cvt_pk_bf16_f32 v44, v44, v45
	v_cvt_pk_bf16_f32 v45, v46, v47
	global_store_dwordx2 v155, v[44:45], s[2:3] offset:0
	v_cvt_pk_bf16_f32 v40, v40, v41
	v_cvt_pk_bf16_f32 v41, v42, v43
	global_store_dwordx2 v155, v[40:41], s[2:3] offset:32
	v_cvt_pk_bf16_f32 v28, v28, v29
	v_cvt_pk_bf16_f32 v29, v30, v31
	global_store_dwordx2 v156, v[28:29], s[2:3] offset:0
	v_cvt_pk_bf16_f32 v24, v24, v25
	v_cvt_pk_bf16_f32 v25, v26, v27
	global_store_dwordx2 v156, v[24:25], s[2:3] offset:32
	v_cvt_pk_bf16_f32 v12, v12, v13
	v_cvt_pk_bf16_f32 v13, v14, v15
	global_store_dwordx2 v157, v[12:13], s[2:3] offset:0
	v_cvt_pk_bf16_f32 v8, v8, v9
	v_cvt_pk_bf16_f32 v9, v10, v11
	global_store_dwordx2 v157, v[8:9], s[2:3] offset:32
	s_branch .Lip0_k0_end
.Lip0_k0_nav:
	s_mul_i32 s93, s32, 768
	s_add_u32 s93, s93, s35
	s_sub_u32 s93, s93, 0x600
	s_mul_i32 s93, s93, 0x900
	s_lshl_b32 s96, s27, 8
	s_add_u32 s93, s93, s96
	s_lshl_b32 s93, s93, 1
	s_add_u32 s10, s50, 0x17fa0000
	s_addc_u32 s11, s51, 0
	s_add_u32 s10, s10, s93
	s_addc_u32 s11, s11, 0
	v_cvt_pk_bf16_f32 v236, v124, v125
	v_cvt_pk_bf16_f32 v237, v126, v127
	v_cvt_pk_bf16_f32 v238, v120, v121
	v_cvt_pk_bf16_f32 v239, v122, v123
	ds_write_b16 v167, v236 offset:0
	ds_write_b16_d16_hi v167, v236 offset:32
	ds_write_b16 v167, v237 offset:64
	ds_write_b16_d16_hi v167, v237 offset:96
	ds_write_b16 v167, v238 offset:512
	ds_write_b16_d16_hi v167, v238 offset:544
	ds_write_b16 v167, v239 offset:576
	ds_write_b16_d16_hi v167, v239 offset:608
	ds_read_b128 v[204:207], v168
	v_cvt_pk_bf16_f32 v240, v108, v109
	v_cvt_pk_bf16_f32 v241, v110, v111
	v_cvt_pk_bf16_f32 v242, v104, v105
	v_cvt_pk_bf16_f32 v243, v106, v107
	ds_write_b16 v167, v240 offset:0
	ds_write_b16_d16_hi v167, v240 offset:32
	ds_write_b16 v167, v241 offset:64
	ds_write_b16_d16_hi v167, v241 offset:96
	ds_write_b16 v167, v242 offset:512
	ds_write_b16_d16_hi v167, v242 offset:544
	ds_write_b16 v167, v243 offset:576
	ds_write_b16_d16_hi v167, v243 offset:608
	ds_read_b128 v[208:211], v168
	s_waitcnt lgkmcnt(9)
	global_store_dwordx4 v166, v[204:207], s[10:11] offset:0
	v_cvt_pk_bf16_f32 v236, v92, v93
	v_cvt_pk_bf16_f32 v237, v94, v95
	v_cvt_pk_bf16_f32 v238, v88, v89
	v_cvt_pk_bf16_f32 v239, v90, v91
	ds_write_b16 v167, v236 offset:0
	ds_write_b16_d16_hi v167, v236 offset:32
	ds_write_b16 v167, v237 offset:64
	ds_write_b16_d16_hi v167, v237 offset:96
	ds_write_b16 v167, v238 offset:512
	ds_write_b16_d16_hi v167, v238 offset:544
	ds_write_b16 v167, v239 offset:576
	ds_write_b16_d16_hi v167, v239 offset:608
	ds_read_b128 v[204:207], v168
	s_waitcnt lgkmcnt(9)
	global_store_dwordx4 v166, v[208:211], s[10:11] offset:32
	v_cvt_pk_bf16_f32 v240, v76, v77
	v_cvt_pk_bf16_f32 v241, v78, v79
	v_cvt_pk_bf16_f32 v242, v72, v73
	v_cvt_pk_bf16_f32 v243, v74, v75
	ds_write_b16 v167, v240 offset:0
	ds_write_b16_d16_hi v167, v240 offset:32
	ds_write_b16 v167, v241 offset:64
	ds_write_b16_d16_hi v167, v241 offset:96
	ds_write_b16 v167, v242 offset:512
	ds_write_b16_d16_hi v167, v242 offset:544
	ds_write_b16 v167, v243 offset:576
	ds_write_b16_d16_hi v167, v243 offset:608
	ds_read_b128 v[208:211], v168
	s_waitcnt lgkmcnt(9)
	global_store_dwordx4 v166, v[204:207], s[10:11] offset:64
	v_cvt_pk_bf16_f32 v236, v60, v61
	v_cvt_pk_bf16_f32 v237, v62, v63
	v_cvt_pk_bf16_f32 v238, v56, v57
	v_cvt_pk_bf16_f32 v239, v58, v59
	ds_write_b16 v167, v236 offset:0
	ds_write_b16_d16_hi v167, v236 offset:32
	ds_write_b16 v167, v237 offset:64
	ds_write_b16_d16_hi v167, v237 offset:96
	ds_write_b16 v167, v238 offset:512
	ds_write_b16_d16_hi v167, v238 offset:544
	ds_write_b16 v167, v239 offset:576
	ds_write_b16_d16_hi v167, v239 offset:608
	ds_read_b128 v[204:207], v168
	s_waitcnt lgkmcnt(9)
	global_store_dwordx4 v166, v[208:211], s[10:11] offset:96
	v_cvt_pk_bf16_f32 v240, v44, v45
	v_cvt_pk_bf16_f32 v241, v46, v47
	v_cvt_pk_bf16_f32 v242, v40, v41
	v_cvt_pk_bf16_f32 v243, v42, v43
	ds_write_b16 v167, v240 offset:0
	ds_write_b16_d16_hi v167, v240 offset:32
	ds_write_b16 v167, v241 offset:64
	ds_write_b16_d16_hi v167, v241 offset:96
	ds_write_b16 v167, v242 offset:512
	ds_write_b16_d16_hi v167, v242 offset:544
	ds_write_b16 v167, v243 offset:576
	ds_write_b16_d16_hi v167, v243 offset:608
	ds_read_b128 v[208:211], v168
	s_waitcnt lgkmcnt(9)
	global_store_dwordx4 v166, v[204:207], s[10:11] offset:256
	v_cvt_pk_bf16_f32 v236, v28, v29
	v_cvt_pk_bf16_f32 v237, v30, v31
	v_cvt_pk_bf16_f32 v238, v24, v25
	v_cvt_pk_bf16_f32 v239, v26, v27
	ds_write_b16 v167, v236 offset:0
	ds_write_b16_d16_hi v167, v236 offset:32
	ds_write_b16 v167, v237 offset:64
	ds_write_b16_d16_hi v167, v237 offset:96
	ds_write_b16 v167, v238 offset:512
	ds_write_b16_d16_hi v167, v238 offset:544
	ds_write_b16 v167, v239 offset:576
	ds_write_b16_d16_hi v167, v239 offset:608
	ds_read_b128 v[204:207], v168
	s_waitcnt lgkmcnt(9)
	global_store_dwordx4 v166, v[208:211], s[10:11] offset:288
	v_cvt_pk_bf16_f32 v240, v12, v13
	v_cvt_pk_bf16_f32 v241, v14, v15
	v_cvt_pk_bf16_f32 v242, v8, v9
	v_cvt_pk_bf16_f32 v243, v10, v11
	ds_write_b16 v167, v240 offset:0
	ds_write_b16_d16_hi v167, v240 offset:32
	ds_write_b16 v167, v241 offset:64
	ds_write_b16_d16_hi v167, v241 offset:96
	ds_write_b16 v167, v242 offset:512
	ds_write_b16_d16_hi v167, v242 offset:544
	ds_write_b16 v167, v243 offset:576
	ds_write_b16_d16_hi v167, v243 offset:608
	ds_read_b128 v[208:211], v168
	s_waitcnt lgkmcnt(9)
	global_store_dwordx4 v166, v[204:207], s[10:11] offset:320
	s_waitcnt lgkmcnt(0)
	global_store_dwordx4 v166, v[208:211], s[10:11] offset:352
	s_nop 1
	s_branch .Lip0_k0_end
; #define LAS __attribute__((address_space(3)))
; DI unsigned cvt_pk_bf16(float lo, float hi) { unsigned r; asm volatile("v_cvt_pk_bf16_f32 %0, %1, %2" : "=v"(r) : "v"(lo), "v"(hi)); return r; }
; DI void st_tr16x32(LAS unsigned char* area, bf16_t* dst_f0_t0  , f32x4 v0, f32x4 v1, int fr, int fq, int lane) {
;     const unsigned p01 = cvt_pk_bf16(v0[0], v0[1]), p23 = cvt_pk_bf16(v0[2], v0[3]), q01 = cvt_pk_bf16(v1[0], v1[1]), q23 = cvt_pk_bf16(v1[2], v1[3]);
;     LAS bf16_t* w = (LAS bf16_t*)(area + (4 * fq) * 32 + fr * 2);
;     w[0 * 16] = (bf16_t)(p01 & 0xffffu); w[1 * 16] = (bf16_t)(p01 >> 16); w[2 * 16] = (bf16_t)(p23 & 0xffffu); w[3 * 16] = (bf16_t)(p23 >> 16);
;     w[16 * 16] = (bf16_t)(q01 & 0xffffu); w[17 * 16] = (bf16_t)(q01 >> 16); w[18 * 16] = (bf16_t)(q23 & 0xffffu); w[19 * 16] = (bf16_t)(q23 >> 16);
;     asm volatile("s_waitcnt lgkmcnt(0)" ::: "memory");
;     const u32x4 row = *(const LAS u32x4*)(area + (lane >> 1) * 32 + (lane & 1) * 16);
;     asm volatile("" ::: "memory");
;     *(u32x4*)(dst_f0_t0 + (size_t)(lane >> 1) * RB + (lane & 1) * 8) = row;
; }
;     DI void operator()(const f32x4 (&acc)[2][2][4][2], const Unit& u, int wr, int wc, int fr, int fq) const {
;     ...
;                     } else if (colg >= C_RV && colg < C_RG) {
;                         st_tr16x32(spare + (wr * 4 + wc) * 1024, (bf16_t*)(ws + WS_VTR) + ((size_t)b * 640 + (colg - C_RV)) * RB + (r - fr), v0, v1, fr, fq, fq * 16 + fr);
.Lip0_k0_rv:
	s_mul_i32 s93, s32, 640
	s_add_u32 s93, s93, s35
	s_sub_u32 s93, s93, 0x1240
	s_mul_i32 s93, s93, 0x900
	s_lshl_b32 s96, s27, 8
	s_add_u32 s93, s93, s96
	s_lshl_b32 s93, s93, 1
	s_add_u32 s10, s50, 0x18d20000
	s_addc_u32 s11, s51, 0
	s_add_u32 s10, s10, s93
	s_addc_u32 s11, s11, 0
	v_cvt_pk_bf16_f32 v236, v124, v125
	v_cvt_pk_bf16_f32 v237, v126, v127
	v_cvt_pk_bf16_f32 v238, v120, v121
	v_cvt_pk_bf16_f32 v239, v122, v123
	ds_write_b16 v167, v236 offset:0
	ds_write_b16_d16_hi v167, v236 offset:32
	ds_write_b16 v167, v237 offset:64
	ds_write_b16_d16_hi v167, v237 offset:96
	ds_write_b16 v167, v238 offset:512
	ds_write_b16_d16_hi v167, v238 offset:544
	ds_write_b16 v167, v239 offset:576
	ds_write_b16_d16_hi v167, v239 offset:608
	ds_read_b128 v[204:207], v168
	v_cvt_pk_bf16_f32 v240, v108, v109
	v_cvt_pk_bf16_f32 v241, v110, v111
	v_cvt_pk_bf16_f32 v242, v104, v105
	v_cvt_pk_bf16_f32 v243, v106, v107
	ds_write_b16 v167, v240 offset:0
	ds_write_b16_d16_hi v167, v240 offset:32
	ds_write_b16 v167, v241 offset:64
	ds_write_b16_d16_hi v167, v241 offset:96
	ds_write_b16 v167, v242 offset:512
	ds_write_b16_d16_hi v167, v242 offset:544
	ds_write_b16 v167, v243 offset:576
	ds_write_b16_d16_hi v167, v243 offset:608
	ds_read_b128 v[208:211], v168
	s_waitcnt lgkmcnt(9)
	global_store_dwordx4 v166, v[204:207], s[10:11] offset:0
	v_cvt_pk_bf16_f32 v236, v92, v93
	v_cvt_pk_bf16_f32 v237, v94, v95
	v_cvt_pk_bf16_f32 v238, v88, v89
	v_cvt_pk_bf16_f32 v239, v90, v91
	ds_write_b16 v167, v236 offset:0
	ds_write_b16_d16_hi v167, v236 offset:32
	ds_write_b16 v167, v237 offset:64
	ds_write_b16_d16_hi v167, v237 offset:96
	ds_write_b16 v167, v238 offset:512
	ds_write_b16_d16_hi v167, v238 offset:544
	ds_write_b16 v167, v239 offset:576
	ds_write_b16_d16_hi v167, v239 offset:608
	ds_read_b128 v[204:207], v168
	s_waitcnt lgkmcnt(9)
	global_store_dwordx4 v166, v[208:211], s[10:11] offset:32
	v_cvt_pk_bf16_f32 v240, v76, v77
	v_cvt_pk_bf16_f32 v241, v78, v79
	v_cvt_pk_bf16_f32 v242, v72, v73
	v_cvt_pk_bf16_f32 v243, v74, v75
	ds_write_b16 v167, v240 offset:0
	ds_write_b16_d16_hi v167, v240 offset:32
	ds_write_b16 v167, v241 offset:64
	ds_write_b16_d16_hi v167, v241 offset:96
	ds_write_b16 v167, v242 offset:512
	ds_write_b16_d16_hi v167, v242 offset:544
	ds_write_b16 v167, v243 offset:576
	ds_write_b16_d16_hi v167, v243 offset:608
	ds_read_b128 v[208:211], v168
	s_waitcnt lgkmcnt(9)
	global_store_dwordx4 v166, v[204:207], s[10:11] offset:64
	v_cvt_pk_bf16_f32 v236, v60, v61
	v_cvt_pk_bf16_f32 v237, v62, v63
	v_cvt_pk_bf16_f32 v238, v56, v57
	v_cvt_pk_bf16_f32 v239, v58, v59
	ds_write_b16 v167, v236 offset:0
	ds_write_b16_d16_hi v167, v236 offset:32
	ds_write_b16 v167, v237 offset:64
	ds_write_b16_d16_hi v167, v237 offset:96
	ds_write_b16 v167, v238 offset:512
	ds_write_b16_d16_hi v167, v238 offset:544
	ds_write_b16 v167, v239 offset:576
	ds_write_b16_d16_hi v167, v239 offset:608
	ds_read_b128 v[204:207], v168
	s_waitcnt lgkmcnt(9)
	global_store_dwordx4 v166, v[208:211], s[10:11] offset:96
	v_cvt_pk_bf16_f32 v240, v44, v45
	v_cvt_pk_bf16_f32 v241, v46, v47
	v_cvt_pk_bf16_f32 v242, v40, v41
	v_cvt_pk_bf16_f32 v243, v42, v43
	ds_write_b16 v167, v240 offset:0
	ds_write_b16_d16_hi v167, v240 offset:32
	ds_write_b16 v167, v241 offset:64
	ds_write_b16_d16_hi v167, v241 offset:96
	ds_write_b16 v167, v242 offset:512
	ds_write_b16_d16_hi v167, v242 offset:544
	ds_write_b16 v167, v243 offset:576
	ds_write_b16_d16_hi v167, v243 offset:608
	ds_read_b128 v[208:211], v168
	s_waitcnt lgkmcnt(9)
	global_store_dwordx4 v166, v[204:207], s[10:11] offset:256
	v_cvt_pk_bf16_f32 v236, v28, v29
	v_cvt_pk_bf16_f32 v237, v30, v31
	v_cvt_pk_bf16_f32 v238, v24, v25
	v_cvt_pk_bf16_f32 v239, v26, v27
	ds_write_b16 v167, v236 offset:0
	ds_write_b16_d16_hi v167, v236 offset:32
	ds_write_b16 v167, v237 offset:64
	ds_write_b16_d16_hi v167, v237 offset:96
	ds_write_b16 v167, v238 offset:512
	ds_write_b16_d16_hi v167, v238 offset:544
	ds_write_b16 v167, v239 offset:576
	ds_write_b16_d16_hi v167, v239 offset:608
	ds_read_b128 v[204:207], v168
	s_waitcnt lgkmcnt(9)
	global_store_dwordx4 v166, v[208:211], s[10:11] offset:288
	v_cvt_pk_bf16_f32 v240, v12, v13
	v_cvt_pk_bf16_f32 v241, v14, v15
	v_cvt_pk_bf16_f32 v242, v8, v9
	v_cvt_pk_bf16_f32 v243, v10, v11
	ds_write_b16 v167, v240 offset:0
	ds_write_b16_d16_hi v167, v240 offset:32
	ds_write_b16 v167, v241 offset:64
	ds_write_b16_d16_hi v167, v241 offset:96
	ds_write_b16 v167, v242 offset:512
	ds_write_b16_d16_hi v167, v242 offset:544
	ds_write_b16 v167, v243 offset:576
	ds_write_b16_d16_hi v167, v243 offset:608
	ds_read_b128 v[208:211], v168
	s_waitcnt lgkmcnt(9)
	global_store_dwordx4 v166, v[204:207], s[10:11] offset:320
	s_waitcnt lgkmcnt(0)
	global_store_dwordx4 v166, v[208:211], s[10:11] offset:352
	s_nop 1
	s_branch .Lip0_k0_end
; DI void st_bf16x4(bf16_t* p, f32x4 v) { u32x2 w; w.x = cvt_pk_bf16(v[0], v[1]); w.y = cvt_pk_bf16(v[2], v[3]); *(u32x2*)p = w; }
;     DI void operator()(const f32x4 (&acc)[2][2][4][2], const Unit& u, int wr, int wc, int fr, int fq) const {
;     ...
;                         if (colg >= C_CQ && colg < C_KPE) {
;                             float ss = v0[0] * v0[0] + v0[1] * v0[1] + v0[2] * v0[2] + v0[3] * v0[3] + v1[0] * v1[0] + v1[1] * v1[1] + v1[2] * v1[2] + v1[3] * v1[3];
;                             ss += __shfl_xor(ss, 16); ss += __shfl_xor(ss, 32);
;                             if (fq == 0) ((float*)(ws + WS_SSQ))[(size_t)row * 32 + ((colg - C_CQ) >> 5)] = ss;
;                         }
;                         st_bf16x4(P + (size_t)row * INP + c0, v0); st_bf16x4(P + (size_t)row * INP + c0 + 16, v1);
.Lip0_k0_ssq:
	v_xor_b32_e32 v198, 16, v197
	v_lshlrev_b32_e32 v198, 2, v198
	v_xor_b32_e32 v199, 32, v197
	v_lshlrev_b32_e32 v199, 2, v199
	v_mul_f32_e32 v158, v124, v124
	v_fmac_f32_e32 v158, v125, v125
	v_fmac_f32_e32 v158, v126, v126
	v_fmac_f32_e32 v158, v127, v127
	v_fmac_f32_e32 v158, v120, v120
	v_fmac_f32_e32 v158, v121, v121
	v_fmac_f32_e32 v158, v122, v122
	v_fmac_f32_e32 v158, v123, v123
	v_mul_f32_e32 v159, v108, v108
	v_fmac_f32_e32 v159, v109, v109
	v_fmac_f32_e32 v159, v110, v110
	v_fmac_f32_e32 v159, v111, v111
	v_fmac_f32_e32 v159, v104, v104
	v_fmac_f32_e32 v159, v105, v105
	v_fmac_f32_e32 v159, v106, v106
	v_fmac_f32_e32 v159, v107, v107
	v_mul_f32_e32 v160, v92, v92
	v_fmac_f32_e32 v160, v93, v93
	v_fmac_f32_e32 v160, v94, v94
	v_fmac_f32_e32 v160, v95, v95
	v_fmac_f32_e32 v160, v88, v88
	v_fmac_f32_e32 v160, v89, v89
	v_fmac_f32_e32 v160, v90, v90
	v_fmac_f32_e32 v160, v91, v91
	v_mul_f32_e32 v161, v76, v76
	v_fmac_f32_e32 v161, v77, v77
	v_fmac_f32_e32 v161, v78, v78
	v_fmac_f32_e32 v161, v79, v79
	v_fmac_f32_e32 v161, v72, v72
	v_fmac_f32_e32 v161, v73, v73
	v_fmac_f32_e32 v161, v74, v74
	v_fmac_f32_e32 v161, v75, v75
	v_mul_f32_e32 v162, v60, v60
	v_fmac_f32_e32 v162, v61, v61
	v_fmac_f32_e32 v162, v62, v62
	v_fmac_f32_e32 v162, v63, v63
	v_fmac_f32_e32 v162, v56, v56
	v_fmac_f32_e32 v162, v57, v57
	v_fmac_f32_e32 v162, v58, v58
	v_fmac_f32_e32 v162, v59, v59
	v_mul_f32_e32 v163, v44, v44
	v_fmac_f32_e32 v163, v45, v45
	v_fmac_f32_e32 v163, v46, v46
	v_fmac_f32_e32 v163, v47, v47
	v_fmac_f32_e32 v163, v40, v40
	v_fmac_f32_e32 v163, v41, v41
	v_fmac_f32_e32 v163, v42, v42
	v_fmac_f32_e32 v163, v43, v43
	v_mul_f32_e32 v164, v28, v28
	v_fmac_f32_e32 v164, v29, v29
	v_fmac_f32_e32 v164, v30, v30
	v_fmac_f32_e32 v164, v31, v31
	v_fmac_f32_e32 v164, v24, v24
	v_fmac_f32_e32 v164, v25, v25
	v_fmac_f32_e32 v164, v26, v26
	v_fmac_f32_e32 v164, v27, v27
	v_mul_f32_e32 v165, v12, v12
	v_fmac_f32_e32 v165, v13, v13
	v_fmac_f32_e32 v165, v14, v14
	v_fmac_f32_e32 v165, v15, v15
	v_fmac_f32_e32 v165, v8, v8
	v_fmac_f32_e32 v165, v9, v9
	v_fmac_f32_e32 v165, v10, v10
	v_fmac_f32_e32 v165, v11, v11
	ds_bpermute_b32 v204, v198, v158
	ds_bpermute_b32 v205, v198, v159
	ds_bpermute_b32 v206, v198, v160
	ds_bpermute_b32 v207, v198, v161
	ds_bpermute_b32 v208, v198, v162
	ds_bpermute_b32 v209, v198, v163
	ds_bpermute_b32 v210, v198, v164
	ds_bpermute_b32 v211, v198, v165
	s_waitcnt lgkmcnt(0)
	v_add_f32_e32 v158, v158, v204
	v_add_f32_e32 v159, v159, v205
	v_add_f32_e32 v160, v160, v206
	v_add_f32_e32 v161, v161, v207
	v_add_f32_e32 v162, v162, v208
	v_add_f32_e32 v163, v163, v209
	v_add_f32_e32 v164, v164, v210
	v_add_f32_e32 v165, v165, v211
	ds_bpermute_b32 v204, v199, v158
	ds_bpermute_b32 v205, v199, v159
	ds_bpermute_b32 v206, v199, v160
	ds_bpermute_b32 v207, v199, v161
	ds_bpermute_b32 v208, v199, v162
	ds_bpermute_b32 v209, v199, v163
	ds_bpermute_b32 v210, v199, v164
	ds_bpermute_b32 v211, v199, v165
	s_waitcnt lgkmcnt(0)
	v_add_f32_e32 v158, v158, v204
	v_add_f32_e32 v159, v159, v205
	v_add_f32_e32 v160, v160, v206
	v_add_f32_e32 v161, v161, v207
	v_add_f32_e32 v162, v162, v208
	v_add_f32_e32 v163, v163, v209
	v_add_f32_e32 v164, v164, v210
	v_add_f32_e32 v165, v165, v211
	s_lshl_b32 s93, s8, 15
	s_add_u32 s10, s50, 0x200000
	s_addc_u32 s11, s51, 0
	s_add_u32 s10, s10, s93
	s_addc_u32 s11, s11, 0
	s_sub_u32 s93, s35, 0x900
	s_lshr_b32 s93, s93, 5
	s_lshl_b32 s93, s93, 2
	s_add_u32 s10, s10, s93
	s_addc_u32 s11, s11, 0
	v_lshlrev_b32_e32 v212, 7, v195
	v_add_u32_e32 v213, 0x800, v212
	v_add_u32_e32 v214, 0x1000, v212
	v_add_u32_e32 v215, 0x1800, v212
	v_add_u32_e32 v216, 0x4000, v212
	v_add_u32_e32 v217, 0x4800, v212
	v_add_u32_e32 v218, 0x5000, v212
	v_add_u32_e32 v219, 0x5800, v212
	v_cmp_eq_u32_e64 s[2:3], 0, v196
	s_mov_b64 exec, s[2:3]
	global_store_dword v212, v158, s[10:11]
	global_store_dword v213, v159, s[10:11]
	global_store_dword v214, v160, s[10:11]
	global_store_dword v215, v161, s[10:11]
	global_store_dword v216, v162, s[10:11]
	global_store_dword v217, v163, s[10:11]
	global_store_dword v218, v164, s[10:11]
	global_store_dword v219, v165, s[10:11]
	s_mov_b64 exec, -1
	s_branch .Lip0_k0_plain
.Lip0_k0_end:
	s_add_u32 s35, s35, 0x80
	s_cmp_eq_u32 s92, 0
	s_cbranch_scc1 .Lip0_k1_end
	s_cmp_eq_u32 s92, 1
	s_cbranch_scc1 .Lip0_k1_plain
	s_cmp_eq_u32 s92, 4
	s_cbranch_scc1 .Lip0_k1_nav
	s_cmp_eq_u32 s92, 5
	s_cbranch_scc1 .Lip0_k1_rv
	s_cmp_eq_u32 s92, 6
	s_cbranch_scc1 .Lip0_k1_ssq
	s_cmp_eq_u32 s27, 0
	s_cbranch_scc1 .Lip0_nr1
; DI void rope4(f32x4& v0, f32x4& v1, const float* tab  ) {
;     const f32x4 t0 = *(const f32x4*)tab, t1 = *(const f32x4*)(tab + 4);
;     const float c[4] = {t0[0], t0[2], t1[0], t1[2]}, s[4] = {t0[1], t0[3], t1[1], t1[3]};
; #pragma unroll
;     for (int j = 0; j < 4; ++j) { const float a = v0[j], b = v1[j]; v0[j] = a * c[j] - b * s[j]; v1[j] = b * c[j] + a * s[j]; }
; }
;     DI void operator()(const f32x4 (&acc)[2][2][4][2], const Unit& u, int wr, int wc, int fr, int fq) const {
;     ...
;                     } else if (colg >= C_RQ && colg < C_RV) {
;                         if (lat) rope4(v0, v1, (const float*)(ws + WS_TABR) + ((size_t)t * 64 + (((colg - C_RQ) & 127) >> 5) * 16 + 4 * fq) * 2);
	s_sub_u32 s97, s35, 0xd40
	s_and_b32 s97, s97, 0x7f
	s_lshr_b32 s97, s97, 5
	s_lshl_b32 s97, s97, 7
	s_sub_u32 s93, s27, 1
	s_lshl_b32 s93, s93, 17
	s_add_u32 s93, s93, s97
	v_lshlrev_b32_e32 v169, 5, v196
	v_lshl_add_u32 v158, v195, 9, v169
	v_add_u32_e32 v158, s93, v158
	v_add_u32_e32 v159, 0x2000, v158
	v_add_u32_e32 v160, 0x4000, v158
	v_add_u32_e32 v161, 0x6000, v158
	v_add_u32_e32 v162, 0x10000, v158
	v_add_u32_e32 v163, 0x12000, v158
	v_add_u32_e32 v164, 0x14000, v158
	v_add_u32_e32 v165, 0x16000, v158
	s_add_u32 s10, s50, 0x100000
	s_addc_u32 s11, s51, 0
	global_load_dwordx4 v[204:207], v158, s[10:11]
	global_load_dwordx4 v[208:211], v158, s[10:11] offset:16
	global_load_dwordx4 v[212:215], v159, s[10:11]
	global_load_dwordx4 v[216:219], v159, s[10:11] offset:16
	global_load_dwordx4 v[220:223], v160, s[10:11]
	global_load_dwordx4 v[224:227], v160, s[10:11] offset:16
	global_load_dwordx4 v[228:231], v161, s[10:11]
	global_load_dwordx4 v[232:235], v161, s[10:11] offset:16
	global_load_dwordx4 v[236:239], v162, s[10:11]
	global_load_dwordx4 v[240:243], v162, s[10:11] offset:16
	global_load_dwordx4 v[244:247], v163, s[10:11]
	global_load_dwordx4 v[248:251], v163, s[10:11] offset:16
	global_load_dwordx4 v[178:181], v164, s[10:11]
	global_load_dwordx4 v[182:185], v164, s[10:11] offset:16
	global_load_dwordx4 v[186:189], v165, s[10:11]
	global_load_dwordx4 v[190:193], v165, s[10:11] offset:16
	s_waitcnt vmcnt(0)
	v_mul_f32_e32 v169, v116, v205
	v_mul_f32_e32 v116, v116, v204
	v_fma_f32 v116, -v112, v205, v116
	v_fma_f32 v112, v112, v204, v169
	v_mul_f32_e32 v169, v117, v207
	v_mul_f32_e32 v117, v117, v206
	v_fma_f32 v117, -v113, v207, v117
	v_fma_f32 v113, v113, v206, v169
	v_mul_f32_e32 v169, v118, v209
	v_mul_f32_e32 v118, v118, v208
	v_fma_f32 v118, -v114, v209, v118
	v_fma_f32 v114, v114, v208, v169
	v_mul_f32_e32 v169, v119, v211
	v_mul_f32_e32 v119, v119, v210
	v_fma_f32 v119, -v115, v211, v119
	v_fma_f32 v115, v115, v210, v169
	v_mul_f32_e32 v169, v100, v213
	v_mul_f32_e32 v100, v100, v212
	v_fma_f32 v100, -v96, v213, v100
	v_fma_f32 v96, v96, v212, v169
	v_mul_f32_e32 v169, v101, v215
	v_mul_f32_e32 v101, v101, v214
	v_fma_f32 v101, -v97, v215, v101
	v_fma_f32 v97, v97, v214, v169
	v_mul_f32_e32 v169, v102, v217
	v_mul_f32_e32 v102, v102, v216
	v_fma_f32 v102, -v98, v217, v102
	v_fma_f32 v98, v98, v216, v169
	v_mul_f32_e32 v169, v103, v219
	v_mul_f32_e32 v103, v103, v218
	v_fma_f32 v103, -v99, v219, v103
	v_fma_f32 v99, v99, v218, v169
	v_mul_f32_e32 v169, v84, v221
	v_mul_f32_e32 v84, v84, v220
	v_fma_f32 v84, -v80, v221, v84
	v_fma_f32 v80, v80, v220, v169
	v_mul_f32_e32 v169, v85, v223
	v_mul_f32_e32 v85, v85, v222
	v_fma_f32 v85, -v81, v223, v85
	v_fma_f32 v81, v81, v222, v169
	v_mul_f32_e32 v169, v86, v225
	v_mul_f32_e32 v86, v86, v224
	v_fma_f32 v86, -v82, v225, v86
	v_fma_f32 v82, v82, v224, v169
	v_mul_f32_e32 v169, v87, v227
	v_mul_f32_e32 v87, v87, v226
	v_fma_f32 v87, -v83, v227, v87
	v_fma_f32 v83, v83, v226, v169
	v_mul_f32_e32 v169, v68, v229
	v_mul_f32_e32 v68, v68, v228
	v_fma_f32 v68, -v64, v229, v68
	v_fma_f32 v64, v64, v228, v169
	v_mul_f32_e32 v169, v69, v231
	v_mul_f32_e32 v69, v69, v230
	v_fma_f32 v69, -v65, v231, v69
	v_fma_f32 v65, v65, v230, v169
	v_mul_f32_e32 v169, v70, v233
	v_mul_f32_e32 v70, v70, v232
	v_fma_f32 v70, -v66, v233, v70
	v_fma_f32 v66, v66, v232, v169
	v_mul_f32_e32 v169, v71, v235
	v_mul_f32_e32 v71, v71, v234
	v_fma_f32 v71, -v67, v235, v71
	v_fma_f32 v67, v67, v234, v169
	v_mul_f32_e32 v169, v52, v237
	v_mul_f32_e32 v52, v52, v236
	v_fma_f32 v52, -v48, v237, v52
	v_fma_f32 v48, v48, v236, v169
	v_mul_f32_e32 v169, v53, v239
	v_mul_f32_e32 v53, v53, v238
	v_fma_f32 v53, -v49, v239, v53
	v_fma_f32 v49, v49, v238, v169
	v_mul_f32_e32 v169, v54, v241
	v_mul_f32_e32 v54, v54, v240
	v_fma_f32 v54, -v50, v241, v54
	v_fma_f32 v50, v50, v240, v169
	v_mul_f32_e32 v169, v55, v243
	v_mul_f32_e32 v55, v55, v242
	v_fma_f32 v55, -v51, v243, v55
	v_fma_f32 v51, v51, v242, v169
	v_mul_f32_e32 v169, v36, v245
	v_mul_f32_e32 v36, v36, v244
	v_fma_f32 v36, -v32, v245, v36
	v_fma_f32 v32, v32, v244, v169
	v_mul_f32_e32 v169, v37, v247
	v_mul_f32_e32 v37, v37, v246
	v_fma_f32 v37, -v33, v247, v37
	v_fma_f32 v33, v33, v246, v169
	v_mul_f32_e32 v169, v38, v249
	v_mul_f32_e32 v38, v38, v248
	v_fma_f32 v38, -v34, v249, v38
	v_fma_f32 v34, v34, v248, v169
	v_mul_f32_e32 v169, v39, v251
	v_mul_f32_e32 v39, v39, v250
	v_fma_f32 v39, -v35, v251, v39
	v_fma_f32 v35, v35, v250, v169
	v_mul_f32_e32 v169, v20, v179
	v_mul_f32_e32 v20, v20, v178
	v_fma_f32 v20, -v16, v179, v20
	v_fma_f32 v16, v16, v178, v169
	v_mul_f32_e32 v169, v21, v181
	v_mul_f32_e32 v21, v21, v180
	v_fma_f32 v21, -v17, v181, v21
	v_fma_f32 v17, v17, v180, v169
	v_mul_f32_e32 v169, v22, v183
	v_mul_f32_e32 v22, v22, v182
	v_fma_f32 v22, -v18, v183, v22
	v_fma_f32 v18, v18, v182, v169
	v_mul_f32_e32 v169, v23, v185
	v_mul_f32_e32 v23, v23, v184
	v_fma_f32 v23, -v19, v185, v23
	v_fma_f32 v19, v19, v184, v169
	v_mul_f32_e32 v169, v4, v187
	v_mul_f32_e32 v4, v4, v186
	v_fma_f32 v4, -v0, v187, v4
	v_fma_f32 v0, v0, v186, v169
	v_mul_f32_e32 v169, v5, v189
	v_mul_f32_e32 v5, v5, v188
	v_fma_f32 v5, -v1, v189, v5
	v_fma_f32 v1, v1, v188, v169
	v_mul_f32_e32 v169, v6, v191
	v_mul_f32_e32 v6, v6, v190
	v_fma_f32 v6, -v2, v191, v6
	v_fma_f32 v2, v2, v190, v169
	v_mul_f32_e32 v169, v7, v193
	v_mul_f32_e32 v7, v7, v192
	v_fma_f32 v7, -v3, v193, v7
	v_fma_f32 v3, v3, v192, v169
; #define LAS __attribute__((address_space(3)))
; DI unsigned cvt_pk_bf16(float lo, float hi) { unsigned r; asm volatile("v_cvt_pk_bf16_f32 %0, %1, %2" : "=v"(r) : "v"(lo), "v"(hi)); return r; }
; DI void st_bf16x4(bf16_t* p, f32x4 v) { u32x2 w; w.x = cvt_pk_bf16(v[0], v[1]); w.y = cvt_pk_bf16(v[2], v[3]); *(u32x2*)p = w; }
; DI void st_tr16x32(LAS unsigned char* area, bf16_t* dst_f0_t0  , f32x4 v0, f32x4 v1, int fr, int fq, int lane) {
;     const unsigned p01 = cvt_pk_bf16(v0[0], v0[1]), p23 = cvt_pk_bf16(v0[2], v0[3]), q01 = cvt_pk_bf16(v1[0], v1[1]), q23 = cvt_pk_bf16(v1[2], v1[3]);
;     LAS bf16_t* w = (LAS bf16_t*)(area + (4 * fq) * 32 + fr * 2);
;     w[0 * 16] = (bf16_t)(p01 & 0xffffu); w[1 * 16] = (bf16_t)(p01 >> 16); w[2 * 16] = (bf16_t)(p23 & 0xffffu); w[3 * 16] = (bf16_t)(p23 >> 16);
;     w[16 * 16] = (bf16_t)(q01 & 0xffffu); w[17 * 16] = (bf16_t)(q01 >> 16); w[18 * 16] = (bf16_t)(q23 & 0xffffu); w[19 * 16] = (bf16_t)(q23 >> 16);
;     asm volatile("s_waitcnt lgkmcnt(0)" ::: "memory");
;     const u32x4 row = *(const LAS u32x4*)(area + (lane >> 1) * 32 + (lane & 1) * 16);
;     asm volatile("" ::: "memory");
;     *(u32x4*)(dst_f0_t0 + (size_t)(lane >> 1) * RB + (lane & 1) * 8) = row;
; }
;     DI void operator()(const f32x4 (&acc)[2][2][4][2], const Unit& u, int wr, int wc, int fr, int fq) const {
;     ...
;                         if (colg >= C_RK) {
;                             v0 *= 0.08838834764831845f; v1 *= 0.08838834764831845f;
;                             st_tr16x32(spare + (wr * 4 + wc) * 1024, (bf16_t*)(ws + WS_KTR) + ((size_t)b * 640 + (colg - C_RK)) * RB + (r - fr), v0, v1, fr, fq, fq * 16 + fr);
;                         }
;                         st_bf16x4(P + (size_t)row * INP + c0, v0); st_bf16x4(P + (size_t)row * INP + c0 + 16, v1);
.Lip0_nr1:
	s_cmp_eq_u32 s92, 3
	s_cbranch_scc0 .Lip0_k1_plain
	s_mov_b32 s96, 0x3db504f3
	v_mul_f32_e32 v116, s96, v116
	v_mul_f32_e32 v117, s96, v117
	v_mul_f32_e32 v118, s96, v118
	v_mul_f32_e32 v119, s96, v119
	v_mul_f32_e32 v112, s96, v112
	v_mul_f32_e32 v113, s96, v113
	v_mul_f32_e32 v114, s96, v114
	v_mul_f32_e32 v115, s96, v115
	v_mul_f32_e32 v100, s96, v100
	v_mul_f32_e32 v101, s96, v101
	v_mul_f32_e32 v102, s96, v102
	v_mul_f32_e32 v103, s96, v103
	v_mul_f32_e32 v96, s96, v96
	v_mul_f32_e32 v97, s96, v97
	v_mul_f32_e32 v98, s96, v98
	v_mul_f32_e32 v99, s96, v99
	v_mul_f32_e32 v84, s96, v84
	v_mul_f32_e32 v85, s96, v85
	v_mul_f32_e32 v86, s96, v86
	v_mul_f32_e32 v87, s96, v87
	v_mul_f32_e32 v80, s96, v80
	v_mul_f32_e32 v81, s96, v81
	v_mul_f32_e32 v82, s96, v82
	v_mul_f32_e32 v83, s96, v83
	v_mul_f32_e32 v68, s96, v68
	v_mul_f32_e32 v69, s96, v69
	v_mul_f32_e32 v70, s96, v70
	v_mul_f32_e32 v71, s96, v71
	v_mul_f32_e32 v64, s96, v64
	v_mul_f32_e32 v65, s96, v65
	v_mul_f32_e32 v66, s96, v66
	v_mul_f32_e32 v67, s96, v67
	v_mul_f32_e32 v52, s96, v52
	v_mul_f32_e32 v53, s96, v53
	v_mul_f32_e32 v54, s96, v54
	v_mul_f32_e32 v55, s96, v55
	v_mul_f32_e32 v48, s96, v48
	v_mul_f32_e32 v49, s96, v49
	v_mul_f32_e32 v50, s96, v50
	v_mul_f32_e32 v51, s96, v51
	v_mul_f32_e32 v36, s96, v36
	v_mul_f32_e32 v37, s96, v37
	v_mul_f32_e32 v38, s96, v38
	v_mul_f32_e32 v39, s96, v39
	v_mul_f32_e32 v32, s96, v32
	v_mul_f32_e32 v33, s96, v33
	v_mul_f32_e32 v34, s96, v34
	v_mul_f32_e32 v35, s96, v35
	v_mul_f32_e32 v20, s96, v20
	v_mul_f32_e32 v21, s96, v21
	v_mul_f32_e32 v22, s96, v22
	v_mul_f32_e32 v23, s96, v23
	v_mul_f32_e32 v16, s96, v16
	v_mul_f32_e32 v17, s96, v17
	v_mul_f32_e32 v18, s96, v18
	v_mul_f32_e32 v19, s96, v19
	v_mul_f32_e32 v4, s96, v4
	v_mul_f32_e32 v5, s96, v5
	v_mul_f32_e32 v6, s96, v6
	v_mul_f32_e32 v7, s96, v7
	v_mul_f32_e32 v0, s96, v0
	v_mul_f32_e32 v1, s96, v1
	v_mul_f32_e32 v2, s96, v2
	v_mul_f32_e32 v3, s96, v3
	s_mul_i32 s93, s32, 640
	s_add_u32 s93, s93, s35
	s_sub_u32 s93, s93, 0xfc0
	s_mul_i32 s93, s93, 0x900
	s_lshl_b32 s96, s27, 8
	s_add_u32 s93, s93, s96
	s_lshl_b32 s93, s93, 1
	s_add_u32 s10, s50, 0x19860000
	s_addc_u32 s11, s51, 0
	s_add_u32 s10, s10, s93
	s_addc_u32 s11, s11, 0
	v_cvt_pk_bf16_f32 v236, v116, v117
	v_cvt_pk_bf16_f32 v237, v118, v119
	v_cvt_pk_bf16_f32 v238, v112, v113
	v_cvt_pk_bf16_f32 v239, v114, v115
	ds_write_b16 v167, v236 offset:0
	ds_write_b16_d16_hi v167, v236 offset:32
	ds_write_b16 v167, v237 offset:64
	ds_write_b16_d16_hi v167, v237 offset:96
	ds_write_b16 v167, v238 offset:512
	ds_write_b16_d16_hi v167, v238 offset:544
	ds_write_b16 v167, v239 offset:576
	ds_write_b16_d16_hi v167, v239 offset:608
	ds_read_b128 v[204:207], v168
	v_cvt_pk_bf16_f32 v240, v100, v101
	v_cvt_pk_bf16_f32 v241, v102, v103
	v_cvt_pk_bf16_f32 v242, v96, v97
	v_cvt_pk_bf16_f32 v243, v98, v99
	ds_write_b16 v167, v240 offset:0
	ds_write_b16_d16_hi v167, v240 offset:32
	ds_write_b16 v167, v241 offset:64
	ds_write_b16_d16_hi v167, v241 offset:96
	ds_write_b16 v167, v242 offset:512
	ds_write_b16_d16_hi v167, v242 offset:544
	ds_write_b16 v167, v243 offset:576
	ds_write_b16_d16_hi v167, v243 offset:608
	ds_read_b128 v[208:211], v168
	s_waitcnt lgkmcnt(9)
	global_store_dwordx4 v166, v[204:207], s[10:11] offset:0
	v_cvt_pk_bf16_f32 v236, v84, v85
	v_cvt_pk_bf16_f32 v237, v86, v87
	v_cvt_pk_bf16_f32 v238, v80, v81
	v_cvt_pk_bf16_f32 v239, v82, v83
	ds_write_b16 v167, v236 offset:0
	ds_write_b16_d16_hi v167, v236 offset:32
	ds_write_b16 v167, v237 offset:64
	ds_write_b16_d16_hi v167, v237 offset:96
	ds_write_b16 v167, v238 offset:512
	ds_write_b16_d16_hi v167, v238 offset:544
	ds_write_b16 v167, v239 offset:576
	ds_write_b16_d16_hi v167, v239 offset:608
	ds_read_b128 v[204:207], v168
	s_waitcnt lgkmcnt(9)
	global_store_dwordx4 v166, v[208:211], s[10:11] offset:32
	v_cvt_pk_bf16_f32 v240, v68, v69
	v_cvt_pk_bf16_f32 v241, v70, v71
	v_cvt_pk_bf16_f32 v242, v64, v65
	v_cvt_pk_bf16_f32 v243, v66, v67
	ds_write_b16 v167, v240 offset:0
	ds_write_b16_d16_hi v167, v240 offset:32
	ds_write_b16 v167, v241 offset:64
	ds_write_b16_d16_hi v167, v241 offset:96
	ds_write_b16 v167, v242 offset:512
	ds_write_b16_d16_hi v167, v242 offset:544
	ds_write_b16 v167, v243 offset:576
	ds_write_b16_d16_hi v167, v243 offset:608
	ds_read_b128 v[208:211], v168
	s_waitcnt lgkmcnt(9)
	global_store_dwordx4 v166, v[204:207], s[10:11] offset:64
	v_cvt_pk_bf16_f32 v236, v52, v53
	v_cvt_pk_bf16_f32 v237, v54, v55
	v_cvt_pk_bf16_f32 v238, v48, v49
	v_cvt_pk_bf16_f32 v239, v50, v51
	ds_write_b16 v167, v236 offset:0
	ds_write_b16_d16_hi v167, v236 offset:32
	ds_write_b16 v167, v237 offset:64
	ds_write_b16_d16_hi v167, v237 offset:96
	ds_write_b16 v167, v238 offset:512
	ds_write_b16_d16_hi v167, v238 offset:544
	ds_write_b16 v167, v239 offset:576
	ds_write_b16_d16_hi v167, v239 offset:608
	ds_read_b128 v[204:207], v168
	s_waitcnt lgkmcnt(9)
	global_store_dwordx4 v166, v[208:211], s[10:11] offset:96
	v_cvt_pk_bf16_f32 v240, v36, v37
	v_cvt_pk_bf16_f32 v241, v38, v39
	v_cvt_pk_bf16_f32 v242, v32, v33
	v_cvt_pk_bf16_f32 v243, v34, v35
	ds_write_b16 v167, v240 offset:0
	ds_write_b16_d16_hi v167, v240 offset:32
	ds_write_b16 v167, v241 offset:64
	ds_write_b16_d16_hi v167, v241 offset:96
	ds_write_b16 v167, v242 offset:512
	ds_write_b16_d16_hi v167, v242 offset:544
	ds_write_b16 v167, v243 offset:576
	ds_write_b16_d16_hi v167, v243 offset:608
	ds_read_b128 v[208:211], v168
	s_waitcnt lgkmcnt(9)
	global_store_dwordx4 v166, v[204:207], s[10:11] offset:256
	v_cvt_pk_bf16_f32 v236, v20, v21
	v_cvt_pk_bf16_f32 v237, v22, v23
	v_cvt_pk_bf16_f32 v238, v16, v17
	v_cvt_pk_bf16_f32 v239, v18, v19
	ds_write_b16 v167, v236 offset:0
	ds_write_b16_d16_hi v167, v236 offset:32
	ds_write_b16 v167, v237 offset:64
	ds_write_b16_d16_hi v167, v237 offset:96
	ds_write_b16 v167, v238 offset:512
	ds_write_b16_d16_hi v167, v238 offset:544
	ds_write_b16 v167, v239 offset:576
	ds_write_b16_d16_hi v167, v239 offset:608
	ds_read_b128 v[204:207], v168
	s_waitcnt lgkmcnt(9)
	global_store_dwordx4 v166, v[208:211], s[10:11] offset:288
	v_cvt_pk_bf16_f32 v240, v4, v5
	v_cvt_pk_bf16_f32 v241, v6, v7
	v_cvt_pk_bf16_f32 v242, v0, v1
	v_cvt_pk_bf16_f32 v243, v2, v3
	ds_write_b16 v167, v240 offset:0
	ds_write_b16_d16_hi v167, v240 offset:32
	ds_write_b16 v167, v241 offset:64
	ds_write_b16_d16_hi v167, v241 offset:96
	ds_write_b16 v167, v242 offset:512
	ds_write_b16_d16_hi v167, v242 offset:544
	ds_write_b16 v167, v243 offset:576
	ds_write_b16_d16_hi v167, v243 offset:608
	ds_read_b128 v[208:211], v168
	s_waitcnt lgkmcnt(9)
	global_store_dwordx4 v166, v[204:207], s[10:11] offset:320
	s_waitcnt lgkmcnt(0)
	global_store_dwordx4 v166, v[208:211], s[10:11] offset:352
	s_nop 1
; #define LAS __attribute__((address_space(3)))
; DI unsigned cvt_pk_bf16(float lo, float hi) { unsigned r; asm volatile("v_cvt_pk_bf16_f32 %0, %1, %2" : "=v"(r) : "v"(lo), "v"(hi)); return r; }
; DI void st_bf16x4(bf16_t* p, f32x4 v) { u32x2 w; w.x = cvt_pk_bf16(v[0], v[1]); w.y = cvt_pk_bf16(v[2], v[3]); *(u32x2*)p = w; }
; DI void st_tr16x32(LAS unsigned char* area, bf16_t* dst_f0_t0  , f32x4 v0, f32x4 v1, int fr, int fq, int lane) {
;     const unsigned p01 = cvt_pk_bf16(v0[0], v0[1]), p23 = cvt_pk_bf16(v0[2], v0[3]), q01 = cvt_pk_bf16(v1[0], v1[1]), q23 = cvt_pk_bf16(v1[2], v1[3]);
;     LAS bf16_t* w = (LAS bf16_t*)(area + (4 * fq) * 32 + fr * 2);
;     w[0 * 16] = (bf16_t)(p01 & 0xffffu); w[1 * 16] = (bf16_t)(p01 >> 16); w[2 * 16] = (bf16_t)(p23 & 0xffffu); w[3 * 16] = (bf16_t)(p23 >> 16);
;     w[16 * 16] = (bf16_t)(q01 & 0xffffu); w[17 * 16] = (bf16_t)(q01 >> 16); w[18 * 16] = (bf16_t)(q23 & 0xffffu); w[19 * 16] = (bf16_t)(q23 >> 16);
;     asm volatile("s_waitcnt lgkmcnt(0)" ::: "memory");
;     const u32x4 row = *(const LAS u32x4*)(area + (lane >> 1) * 32 + (lane & 1) * 16);
;     asm volatile("" ::: "memory");
;     *(u32x4*)(dst_f0_t0 + (size_t)(lane >> 1) * RB + (lane & 1) * 8) = row;
; }
;     DI void operator()(const f32x4 (&acc)[2][2][4][2], const Unit& u, int wr, int wc, int fr, int fq) const {
;     ...
;                         st_bf16x4(P + (size_t)row * INP + c0, v0); st_bf16x4(P + (size_t)row * INP + c0 + 16, v1);
;                     } else {
;                         if (colg >= C_CQ && colg < C_KPE) {
;                             float ss = v0[0] * v0[0] + v0[1] * v0[1] + v0[2] * v0[2] + v0[3] * v0[3] + v1[0] * v1[0] + v1[1] * v1[1] + v1[2] * v1[2] + v1[3] * v1[3];
;                             ss += __shfl_xor(ss, 16); ss += __shfl_xor(ss, 32);
;                             if (fq == 0) ((float*)(ws + WS_SSQ))[(size_t)row * 32 + ((colg - C_CQ) >> 5)] = ss;
;                         }
;                         st_bf16x4(P + (size_t)row * INP + c0, v0); st_bf16x4(P + (size_t)row * INP + c0 + 16, v1);
.Lip0_k1_plain:
	s_mul_i32 s93, s8, 0x300000
	s_add_u32 s2, s50, 0x113a0000
	s_addc_u32 s3, s51, 0
	s_add_u32 s2, s2, s93
	s_addc_u32 s3, s3, 0
	s_lshl_b32 s93, s35, 1
	s_add_u32 s2, s2, s93
	s_addc_u32 s3, s3, 0
	v_cvt_pk_bf16_f32 v116, v116, v117
	v_cvt_pk_bf16_f32 v117, v118, v119
	global_store_dwordx2 v150, v[116:117], s[2:3] offset:0
	v_cvt_pk_bf16_f32 v112, v112, v113
	v_cvt_pk_bf16_f32 v113, v114, v115
	global_store_dwordx2 v150, v[112:113], s[2:3] offset:32
	v_cvt_pk_bf16_f32 v100, v100, v101
	v_cvt_pk_bf16_f32 v101, v102, v103
	global_store_dwordx2 v151, v[100:101], s[2:3] offset:0
	v_cvt_pk_bf16_f32 v96, v96, v97
	v_cvt_pk_bf16_f32 v97, v98, v99
	global_store_dwordx2 v151, v[96:97], s[2:3] offset:32
	v_cvt_pk_bf16_f32 v84, v84, v85
	v_cvt_pk_bf16_f32 v85, v86, v87
	global_store_dwordx2 v152, v[84:85], s[2:3] offset:0
	v_cvt_pk_bf16_f32 v80, v80, v81
	v_cvt_pk_bf16_f32 v81, v82, v83
	global_store_dwordx2 v152, v[80:81], s[2:3] offset:32
	v_cvt_pk_bf16_f32 v68, v68, v69
	v_cvt_pk_bf16_f32 v69, v70, v71
	global_store_dwordx2 v153, v[68:69], s[2:3] offset:0
	v_cvt_pk_bf16_f32 v64, v64, v65
	v_cvt_pk_bf16_f32 v65, v66, v67
	global_store_dwordx2 v153, v[64:65], s[2:3] offset:32
	v_cvt_pk_bf16_f32 v52, v52, v53
	v_cvt_pk_bf16_f32 v53, v54, v55
	global_store_dwordx2 v154, v[52:53], s[2:3] offset:0
	v_cvt_pk_bf16_f32 v48, v48, v49
	v_cvt_pk_bf16_f32 v49, v50, v51
	global_store_dwordx2 v154, v[48:49], s[2:3] offset:32
	v_cvt_pk_bf16_f32 v36, v36, v37
	v_cvt_pk_bf16_f32 v37, v38, v39
	global_store_dwordx2 v155, v[36:37], s[2:3] offset:0
	v_cvt_pk_bf16_f32 v32, v32, v33
	v_cvt_pk_bf16_f32 v33, v34, v35
	global_store_dwordx2 v155, v[32:33], s[2:3] offset:32
	v_cvt_pk_bf16_f32 v20, v20, v21
	v_cvt_pk_bf16_f32 v21, v22, v23
	global_store_dwordx2 v156, v[20:21], s[2:3] offset:0
	v_cvt_pk_bf16_f32 v16, v16, v17
	v_cvt_pk_bf16_f32 v17, v18, v19
	global_store_dwordx2 v156, v[16:17], s[2:3] offset:32
	v_cvt_pk_bf16_f32 v4, v4, v5
	v_cvt_pk_bf16_f32 v5, v6, v7
	global_store_dwordx2 v157, v[4:5], s[2:3] offset:0
	v_cvt_pk_bf16_f32 v0, v0, v1
	v_cvt_pk_bf16_f32 v1, v2, v3
	global_store_dwordx2 v157, v[0:1], s[2:3] offset:32
	s_branch .Lip0_k1_end
.Lip0_k1_nav:
	s_mul_i32 s93, s32, 768
	s_add_u32 s93, s93, s35
	s_sub_u32 s93, s93, 0x600
	s_mul_i32 s93, s93, 0x900
	s_lshl_b32 s96, s27, 8
	s_add_u32 s93, s93, s96
	s_lshl_b32 s93, s93, 1
	s_add_u32 s10, s50, 0x17fa0000
	s_addc_u32 s11, s51, 0
	s_add_u32 s10, s10, s93
	s_addc_u32 s11, s11, 0
	v_cvt_pk_bf16_f32 v236, v116, v117
	v_cvt_pk_bf16_f32 v237, v118, v119
	v_cvt_pk_bf16_f32 v238, v112, v113
	v_cvt_pk_bf16_f32 v239, v114, v115
	ds_write_b16 v167, v236 offset:0
	ds_write_b16_d16_hi v167, v236 offset:32
	ds_write_b16 v167, v237 offset:64
	ds_write_b16_d16_hi v167, v237 offset:96
	ds_write_b16 v167, v238 offset:512
	ds_write_b16_d16_hi v167, v238 offset:544
	ds_write_b16 v167, v239 offset:576
	ds_write_b16_d16_hi v167, v239 offset:608
	ds_read_b128 v[204:207], v168
	v_cvt_pk_bf16_f32 v240, v100, v101
	v_cvt_pk_bf16_f32 v241, v102, v103
	v_cvt_pk_bf16_f32 v242, v96, v97
	v_cvt_pk_bf16_f32 v243, v98, v99
	ds_write_b16 v167, v240 offset:0
	ds_write_b16_d16_hi v167, v240 offset:32
	ds_write_b16 v167, v241 offset:64
	ds_write_b16_d16_hi v167, v241 offset:96
	ds_write_b16 v167, v242 offset:512
	ds_write_b16_d16_hi v167, v242 offset:544
	ds_write_b16 v167, v243 offset:576
	ds_write_b16_d16_hi v167, v243 offset:608
	ds_read_b128 v[208:211], v168
	s_waitcnt lgkmcnt(9)
	global_store_dwordx4 v166, v[204:207], s[10:11] offset:0
	v_cvt_pk_bf16_f32 v236, v84, v85
	v_cvt_pk_bf16_f32 v237, v86, v87
	v_cvt_pk_bf16_f32 v238, v80, v81
	v_cvt_pk_bf16_f32 v239, v82, v83
	ds_write_b16 v167, v236 offset:0
	ds_write_b16_d16_hi v167, v236 offset:32
	ds_write_b16 v167, v237 offset:64
	ds_write_b16_d16_hi v167, v237 offset:96
	ds_write_b16 v167, v238 offset:512
	ds_write_b16_d16_hi v167, v238 offset:544
	ds_write_b16 v167, v239 offset:576
	ds_write_b16_d16_hi v167, v239 offset:608
	ds_read_b128 v[204:207], v168
	s_waitcnt lgkmcnt(9)
	global_store_dwordx4 v166, v[208:211], s[10:11] offset:32
	v_cvt_pk_bf16_f32 v240, v68, v69
	v_cvt_pk_bf16_f32 v241, v70, v71
	v_cvt_pk_bf16_f32 v242, v64, v65
	v_cvt_pk_bf16_f32 v243, v66, v67
	ds_write_b16 v167, v240 offset:0
	ds_write_b16_d16_hi v167, v240 offset:32
	ds_write_b16 v167, v241 offset:64
	ds_write_b16_d16_hi v167, v241 offset:96
	ds_write_b16 v167, v242 offset:512
	ds_write_b16_d16_hi v167, v242 offset:544
	ds_write_b16 v167, v243 offset:576
	ds_write_b16_d16_hi v167, v243 offset:608
	ds_read_b128 v[208:211], v168
	s_waitcnt lgkmcnt(9)
	global_store_dwordx4 v166, v[204:207], s[10:11] offset:64
	v_cvt_pk_bf16_f32 v236, v52, v53
	v_cvt_pk_bf16_f32 v237, v54, v55
	v_cvt_pk_bf16_f32 v238, v48, v49
	v_cvt_pk_bf16_f32 v239, v50, v51
	ds_write_b16 v167, v236 offset:0
	ds_write_b16_d16_hi v167, v236 offset:32
	ds_write_b16 v167, v237 offset:64
	ds_write_b16_d16_hi v167, v237 offset:96
	ds_write_b16 v167, v238 offset:512
	ds_write_b16_d16_hi v167, v238 offset:544
	ds_write_b16 v167, v239 offset:576
	ds_write_b16_d16_hi v167, v239 offset:608
	ds_read_b128 v[204:207], v168
	s_waitcnt lgkmcnt(9)
	global_store_dwordx4 v166, v[208:211], s[10:11] offset:96
	v_cvt_pk_bf16_f32 v240, v36, v37
	v_cvt_pk_bf16_f32 v241, v38, v39
	v_cvt_pk_bf16_f32 v242, v32, v33
	v_cvt_pk_bf16_f32 v243, v34, v35
	ds_write_b16 v167, v240 offset:0
	ds_write_b16_d16_hi v167, v240 offset:32
	ds_write_b16 v167, v241 offset:64
	ds_write_b16_d16_hi v167, v241 offset:96
	ds_write_b16 v167, v242 offset:512
	ds_write_b16_d16_hi v167, v242 offset:544
	ds_write_b16 v167, v243 offset:576
	ds_write_b16_d16_hi v167, v243 offset:608
	ds_read_b128 v[208:211], v168
	s_waitcnt lgkmcnt(9)
	global_store_dwordx4 v166, v[204:207], s[10:11] offset:256
	v_cvt_pk_bf16_f32 v236, v20, v21
	v_cvt_pk_bf16_f32 v237, v22, v23
	v_cvt_pk_bf16_f32 v238, v16, v17
	v_cvt_pk_bf16_f32 v239, v18, v19
	ds_write_b16 v167, v236 offset:0
	ds_write_b16_d16_hi v167, v236 offset:32
	ds_write_b16 v167, v237 offset:64
	ds_write_b16_d16_hi v167, v237 offset:96
	ds_write_b16 v167, v238 offset:512
	ds_write_b16_d16_hi v167, v238 offset:544
	ds_write_b16 v167, v239 offset:576
	ds_write_b16_d16_hi v167, v239 offset:608
	ds_read_b128 v[204:207], v168
	s_waitcnt lgkmcnt(9)
	global_store_dwordx4 v166, v[208:211], s[10:11] offset:288
	v_cvt_pk_bf16_f32 v240, v4, v5
	v_cvt_pk_bf16_f32 v241, v6, v7
	v_cvt_pk_bf16_f32 v242, v0, v1
	v_cvt_pk_bf16_f32 v243, v2, v3
	ds_write_b16 v167, v240 offset:0
	ds_write_b16_d16_hi v167, v240 offset:32
	ds_write_b16 v167, v241 offset:64
	ds_write_b16_d16_hi v167, v241 offset:96
	ds_write_b16 v167, v242 offset:512
	ds_write_b16_d16_hi v167, v242 offset:544
	ds_write_b16 v167, v243 offset:576
	ds_write_b16_d16_hi v167, v243 offset:608
	ds_read_b128 v[208:211], v168
	s_waitcnt lgkmcnt(9)
	global_store_dwordx4 v166, v[204:207], s[10:11] offset:320
	s_waitcnt lgkmcnt(0)
	global_store_dwordx4 v166, v[208:211], s[10:11] offset:352
	s_nop 1
	s_branch .Lip0_k1_end
; #define LAS __attribute__((address_space(3)))
; DI unsigned cvt_pk_bf16(float lo, float hi) { unsigned r; asm volatile("v_cvt_pk_bf16_f32 %0, %1, %2" : "=v"(r) : "v"(lo), "v"(hi)); return r; }
; DI void st_tr16x32(LAS unsigned char* area, bf16_t* dst_f0_t0  , f32x4 v0, f32x4 v1, int fr, int fq, int lane) {
;     const unsigned p01 = cvt_pk_bf16(v0[0], v0[1]), p23 = cvt_pk_bf16(v0[2], v0[3]), q01 = cvt_pk_bf16(v1[0], v1[1]), q23 = cvt_pk_bf16(v1[2], v1[3]);
;     LAS bf16_t* w = (LAS bf16_t*)(area + (4 * fq) * 32 + fr * 2);
;     w[0 * 16] = (bf16_t)(p01 & 0xffffu); w[1 * 16] = (bf16_t)(p01 >> 16); w[2 * 16] = (bf16_t)(p23 & 0xffffu); w[3 * 16] = (bf16_t)(p23 >> 16);
;     w[16 * 16] = (bf16_t)(q01 & 0xffffu); w[17 * 16] = (bf16_t)(q01 >> 16); w[18 * 16] = (bf16_t)(q23 & 0xffffu); w[19 * 16] = (bf16_t)(q23 >> 16);
;     asm volatile("s_waitcnt lgkmcnt(0)" ::: "memory");
;     const u32x4 row = *(const LAS u32x4*)(area + (lane >> 1) * 32 + (lane & 1) * 16);
;     asm volatile("" ::: "memory");
;     *(u32x4*)(dst_f0_t0 + (size_t)(lane >> 1) * RB + (lane & 1) * 8) = row;
; }
;     DI void operator()(const f32x4 (&acc)[2][2][4][2], const Unit& u, int wr, int wc, int fr, int fq) const {
;     ...
;                     } else if (colg >= C_RV && colg < C_RG) {
;                         st_tr16x32(spare + (wr * 4 + wc) * 1024, (bf16_t*)(ws + WS_VTR) + ((size_t)b * 640 + (colg - C_RV)) * RB + (r - fr), v0, v1, fr, fq, fq * 16 + fr);
.Lip0_k1_rv:
	s_mul_i32 s93, s32, 640
	s_add_u32 s93, s93, s35
	s_sub_u32 s93, s93, 0x1240
	s_mul_i32 s93, s93, 0x900
	s_lshl_b32 s96, s27, 8
	s_add_u32 s93, s93, s96
	s_lshl_b32 s93, s93, 1
	s_add_u32 s10, s50, 0x18d20000
	s_addc_u32 s11, s51, 0
	s_add_u32 s10, s10, s93
	s_addc_u32 s11, s11, 0
	v_cvt_pk_bf16_f32 v236, v116, v117
	v_cvt_pk_bf16_f32 v237, v118, v119
	v_cvt_pk_bf16_f32 v238, v112, v113
	v_cvt_pk_bf16_f32 v239, v114, v115
	ds_write_b16 v167, v236 offset:0
	ds_write_b16_d16_hi v167, v236 offset:32
	ds_write_b16 v167, v237 offset:64
	ds_write_b16_d16_hi v167, v237 offset:96
	ds_write_b16 v167, v238 offset:512
	ds_write_b16_d16_hi v167, v238 offset:544
	ds_write_b16 v167, v239 offset:576
	ds_write_b16_d16_hi v167, v239 offset:608
	ds_read_b128 v[204:207], v168
	v_cvt_pk_bf16_f32 v240, v100, v101
	v_cvt_pk_bf16_f32 v241, v102, v103
	v_cvt_pk_bf16_f32 v242, v96, v97
	v_cvt_pk_bf16_f32 v243, v98, v99
	ds_write_b16 v167, v240 offset:0
	ds_write_b16_d16_hi v167, v240 offset:32
	ds_write_b16 v167, v241 offset:64
	ds_write_b16_d16_hi v167, v241 offset:96
	ds_write_b16 v167, v242 offset:512
	ds_write_b16_d16_hi v167, v242 offset:544
	ds_write_b16 v167, v243 offset:576
	ds_write_b16_d16_hi v167, v243 offset:608
	ds_read_b128 v[208:211], v168
	s_waitcnt lgkmcnt(9)
	global_store_dwordx4 v166, v[204:207], s[10:11] offset:0
	v_cvt_pk_bf16_f32 v236, v84, v85
	v_cvt_pk_bf16_f32 v237, v86, v87
	v_cvt_pk_bf16_f32 v238, v80, v81
	v_cvt_pk_bf16_f32 v239, v82, v83
	ds_write_b16 v167, v236 offset:0
	ds_write_b16_d16_hi v167, v236 offset:32
	ds_write_b16 v167, v237 offset:64
	ds_write_b16_d16_hi v167, v237 offset:96
	ds_write_b16 v167, v238 offset:512
	ds_write_b16_d16_hi v167, v238 offset:544
	ds_write_b16 v167, v239 offset:576
	ds_write_b16_d16_hi v167, v239 offset:608
	ds_read_b128 v[204:207], v168
	s_waitcnt lgkmcnt(9)
	global_store_dwordx4 v166, v[208:211], s[10:11] offset:32
	v_cvt_pk_bf16_f32 v240, v68, v69
	v_cvt_pk_bf16_f32 v241, v70, v71
	v_cvt_pk_bf16_f32 v242, v64, v65
	v_cvt_pk_bf16_f32 v243, v66, v67
	ds_write_b16 v167, v240 offset:0
	ds_write_b16_d16_hi v167, v240 offset:32
	ds_write_b16 v167, v241 offset:64
	ds_write_b16_d16_hi v167, v241 offset:96
	ds_write_b16 v167, v242 offset:512
	ds_write_b16_d16_hi v167, v242 offset:544
	ds_write_b16 v167, v243 offset:576
	ds_write_b16_d16_hi v167, v243 offset:608
	ds_read_b128 v[208:211], v168
	s_waitcnt lgkmcnt(9)
	global_store_dwordx4 v166, v[204:207], s[10:11] offset:64
	v_cvt_pk_bf16_f32 v236, v52, v53
	v_cvt_pk_bf16_f32 v237, v54, v55
	v_cvt_pk_bf16_f32 v238, v48, v49
	v_cvt_pk_bf16_f32 v239, v50, v51
	ds_write_b16 v167, v236 offset:0
	ds_write_b16_d16_hi v167, v236 offset:32
	ds_write_b16 v167, v237 offset:64
	ds_write_b16_d16_hi v167, v237 offset:96
	ds_write_b16 v167, v238 offset:512
	ds_write_b16_d16_hi v167, v238 offset:544
	ds_write_b16 v167, v239 offset:576
	ds_write_b16_d16_hi v167, v239 offset:608
	ds_read_b128 v[204:207], v168
	s_waitcnt lgkmcnt(9)
	global_store_dwordx4 v166, v[208:211], s[10:11] offset:96
	v_cvt_pk_bf16_f32 v240, v36, v37
	v_cvt_pk_bf16_f32 v241, v38, v39
	v_cvt_pk_bf16_f32 v242, v32, v33
	v_cvt_pk_bf16_f32 v243, v34, v35
	ds_write_b16 v167, v240 offset:0
	ds_write_b16_d16_hi v167, v240 offset:32
	ds_write_b16 v167, v241 offset:64
	ds_write_b16_d16_hi v167, v241 offset:96
	ds_write_b16 v167, v242 offset:512
	ds_write_b16_d16_hi v167, v242 offset:544
	ds_write_b16 v167, v243 offset:576
	ds_write_b16_d16_hi v167, v243 offset:608
	ds_read_b128 v[208:211], v168
	s_waitcnt lgkmcnt(9)
	global_store_dwordx4 v166, v[204:207], s[10:11] offset:256
	v_cvt_pk_bf16_f32 v236, v20, v21
	v_cvt_pk_bf16_f32 v237, v22, v23
	v_cvt_pk_bf16_f32 v238, v16, v17
	v_cvt_pk_bf16_f32 v239, v18, v19
	ds_write_b16 v167, v236 offset:0
	ds_write_b16_d16_hi v167, v236 offset:32
	ds_write_b16 v167, v237 offset:64
	ds_write_b16_d16_hi v167, v237 offset:96
	ds_write_b16 v167, v238 offset:512
	ds_write_b16_d16_hi v167, v238 offset:544
	ds_write_b16 v167, v239 offset:576
	ds_write_b16_d16_hi v167, v239 offset:608
	ds_read_b128 v[204:207], v168
	s_waitcnt lgkmcnt(9)
	global_store_dwordx4 v166, v[208:211], s[10:11] offset:288
	v_cvt_pk_bf16_f32 v240, v4, v5
	v_cvt_pk_bf16_f32 v241, v6, v7
	v_cvt_pk_bf16_f32 v242, v0, v1
	v_cvt_pk_bf16_f32 v243, v2, v3
	ds_write_b16 v167, v240 offset:0
	ds_write_b16_d16_hi v167, v240 offset:32
	ds_write_b16 v167, v241 offset:64
	ds_write_b16_d16_hi v167, v241 offset:96
	ds_write_b16 v167, v242 offset:512
	ds_write_b16_d16_hi v167, v242 offset:544
	ds_write_b16 v167, v243 offset:576
	ds_write_b16_d16_hi v167, v243 offset:608
	ds_read_b128 v[208:211], v168
	s_waitcnt lgkmcnt(9)
	global_store_dwordx4 v166, v[204:207], s[10:11] offset:320
	s_waitcnt lgkmcnt(0)
	global_store_dwordx4 v166, v[208:211], s[10:11] offset:352
	s_nop 1
	s_branch .Lip0_k1_end
;     DI void operator()(const f32x4 (&acc)[2][2][4][2], const Unit& u, int wr, int wc, int fr, int fq) const {
;         bf16_t* P = (bf16_t*)(ws + WS_P);
;         const int b = u.pm / 9;
; #pragma unroll
;         for (int ai = 0; ai < 2; ++ai)
; #pragma unroll
;             for (int m = 0; m < 4; ++m) {
;                 const int row = u.pm * BM + ai * HALF + wr * 64 + m * 16 + fr;
;                 const int r = row - b * RB; const bool lat = r >= CL; const int t = r - CL;
; #pragma unroll
;                 for (int bj = 0; bj < 2; ++bj) {
;                     const int colg = u.pn * BM + bj * HALF + wc * 32;
;                     f32x4 v0 = acc[ai][bj][m][0], v1 = acc[ai][bj][m][1];
;                     const int c0 = colg + 4 * fq;
;                     if (colg >= INW) continue;
;                     if (colg >= C_NAV && colg < C_CQ) {
;                         st_tr16x32(spare + (wr * 4 + wc) * 1024, (bf16_t*)(ws + WS_VTNA) + ((size_t)b * 768 + (colg - C_NAV)) * RB + (r - fr), v0, v1, fr, fq, fq * 16 + fr);
;                     } else if (colg >= C_RV && colg < C_RG) {
;                         st_tr16x32(spare + (wr * 4 + wc) * 1024, (bf16_t*)(ws + WS_VTR) + ((size_t)b * 640 + (colg - C_RV)) * RB + (r - fr), v0, v1, fr, fq, fq * 16 + fr);
;                     } else if (colg >= C_KPE && colg < C_RQ) {
;                         if (lat) rope4(v0, v1, (const float*)(ws + WS_TABM) + ((size_t)t * 32 + ((colg - C_KPE) >> 5) * 16 + 4 * fq) * 2);
;                         bf16_t* kp = (bf16_t*)(ws + WS_KPE) + (size_t)row * 64 + (c0 - C_KPE);
;                         st_bf16x4(kp, v0); st_bf16x4(kp + 16, v1);
;                     } else if (colg >= C_RQ && colg < C_RV) {
;                         if (lat) rope4(v0, v1, (const float*)(ws + WS_TABR) + ((size_t)t * 64 + (((colg - C_RQ) & 127) >> 5) * 16 + 4 * fq) * 2);
;                         if (colg >= C_RK) {
;                             v0 *= 0.08838834764831845f; v1 *= 0.08838834764831845f;
;                             st_tr16x32(spare + (wr * 4 + wc) * 1024, (bf16_t*)(ws + WS_KTR) + ((size_t)b * 640 + (colg - C_RK)) * RB + (r - fr), v0, v1, fr, fq, fq * 16 + fr);
;                         }
;                         st_bf16x4(P + (size_t)row * INP + c0, v0); st_bf16x4(P + (size_t)row * INP + c0 + 16, v1);
;                     } else {
.Lip0_k1_ssq:
	v_xor_b32_e32 v198, 16, v197
	v_lshlrev_b32_e32 v198, 2, v198
	v_xor_b32_e32 v199, 32, v197
	v_lshlrev_b32_e32 v199, 2, v199
	v_mul_f32_e32 v158, v116, v116
	v_fmac_f32_e32 v158, v117, v117
	v_fmac_f32_e32 v158, v118, v118
	v_fmac_f32_e32 v158, v119, v119
	v_fmac_f32_e32 v158, v112, v112
	v_fmac_f32_e32 v158, v113, v113
	v_fmac_f32_e32 v158, v114, v114
	v_fmac_f32_e32 v158, v115, v115
	v_mul_f32_e32 v159, v100, v100
	v_fmac_f32_e32 v159, v101, v101
	v_fmac_f32_e32 v159, v102, v102
	v_fmac_f32_e32 v159, v103, v103
	v_fmac_f32_e32 v159, v96, v96
	v_fmac_f32_e32 v159, v97, v97
	v_fmac_f32_e32 v159, v98, v98
	v_fmac_f32_e32 v159, v99, v99
	v_mul_f32_e32 v160, v84, v84
	v_fmac_f32_e32 v160, v85, v85
	v_fmac_f32_e32 v160, v86, v86
	v_fmac_f32_e32 v160, v87, v87
	v_fmac_f32_e32 v160, v80, v80
	v_fmac_f32_e32 v160, v81, v81
	v_fmac_f32_e32 v160, v82, v82
	v_fmac_f32_e32 v160, v83, v83
	v_mul_f32_e32 v161, v68, v68
	v_fmac_f32_e32 v161, v69, v69
	v_fmac_f32_e32 v161, v70, v70
	v_fmac_f32_e32 v161, v71, v71
	v_fmac_f32_e32 v161, v64, v64
	v_fmac_f32_e32 v161, v65, v65
	v_fmac_f32_e32 v161, v66, v66
	v_fmac_f32_e32 v161, v67, v67
	v_mul_f32_e32 v162, v52, v52
	v_fmac_f32_e32 v162, v53, v53
	v_fmac_f32_e32 v162, v54, v54
	v_fmac_f32_e32 v162, v55, v55
	v_fmac_f32_e32 v162, v48, v48
	v_fmac_f32_e32 v162, v49, v49
	v_fmac_f32_e32 v162, v50, v50
	v_fmac_f32_e32 v162, v51, v51
	v_mul_f32_e32 v163, v36, v36
	v_fmac_f32_e32 v163, v37, v37
	v_fmac_f32_e32 v163, v38, v38
	v_fmac_f32_e32 v163, v39, v39
	v_fmac_f32_e32 v163, v32, v32
	v_fmac_f32_e32 v163, v33, v33
	v_fmac_f32_e32 v163, v34, v34
	v_fmac_f32_e32 v163, v35, v35
	v_mul_f32_e32 v164, v20, v20
	v_fmac_f32_e32 v164, v21, v21
	v_fmac_f32_e32 v164, v22, v22
	v_fmac_f32_e32 v164, v23, v23
	v_fmac_f32_e32 v164, v16, v16
	v_fmac_f32_e32 v164, v17, v17
	v_fmac_f32_e32 v164, v18, v18
	v_fmac_f32_e32 v164, v19, v19
	v_mul_f32_e32 v165, v4, v4
	v_fmac_f32_e32 v165, v5, v5
	v_fmac_f32_e32 v165, v6, v6
	v_fmac_f32_e32 v165, v7, v7
	v_fmac_f32_e32 v165, v0, v0
	v_fmac_f32_e32 v165, v1, v1
	v_fmac_f32_e32 v165, v2, v2
	v_fmac_f32_e32 v165, v3, v3
	ds_bpermute_b32 v204, v198, v158
	ds_bpermute_b32 v205, v198, v159
	ds_bpermute_b32 v206, v198, v160
	ds_bpermute_b32 v207, v198, v161
	ds_bpermute_b32 v208, v198, v162
	ds_bpermute_b32 v209, v198, v163
	ds_bpermute_b32 v210, v198, v164
	ds_bpermute_b32 v211, v198, v165
	s_waitcnt lgkmcnt(0)
	v_add_f32_e32 v158, v158, v204
	v_add_f32_e32 v159, v159, v205
	v_add_f32_e32 v160, v160, v206
	v_add_f32_e32 v161, v161, v207
	v_add_f32_e32 v162, v162, v208
	v_add_f32_e32 v163, v163, v209
	v_add_f32_e32 v164, v164, v210
	v_add_f32_e32 v165, v165, v211
	ds_bpermute_b32 v204, v199, v158
	ds_bpermute_b32 v205, v199, v159
	ds_bpermute_b32 v206, v199, v160
	ds_bpermute_b32 v207, v199, v161
	ds_bpermute_b32 v208, v199, v162
	ds_bpermute_b32 v209, v199, v163
	ds_bpermute_b32 v210, v199, v164
	ds_bpermute_b32 v211, v199, v165
	s_waitcnt lgkmcnt(0)
	v_add_f32_e32 v158, v158, v204
	v_add_f32_e32 v159, v159, v205
	v_add_f32_e32 v160, v160, v206
	v_add_f32_e32 v161, v161, v207
	v_add_f32_e32 v162, v162, v208
	v_add_f32_e32 v163, v163, v209
	v_add_f32_e32 v164, v164, v210
	v_add_f32_e32 v165, v165, v211
	s_lshl_b32 s93, s8, 15
	s_add_u32 s10, s50, 0x200000
	s_addc_u32 s11, s51, 0
	s_add_u32 s10, s10, s93
	s_addc_u32 s11, s11, 0
	s_sub_u32 s93, s35, 0x900
	s_lshr_b32 s93, s93, 5
	s_lshl_b32 s93, s93, 2
	s_add_u32 s10, s10, s93
	s_addc_u32 s11, s11, 0
	v_lshlrev_b32_e32 v212, 7, v195
	v_add_u32_e32 v213, 0x800, v212
	v_add_u32_e32 v214, 0x1000, v212
	v_add_u32_e32 v215, 0x1800, v212
	v_add_u32_e32 v216, 0x4000, v212
	v_add_u32_e32 v217, 0x4800, v212
	v_add_u32_e32 v218, 0x5000, v212
	v_add_u32_e32 v219, 0x5800, v212
	v_cmp_eq_u32_e64 s[2:3], 0, v196
	s_mov_b64 exec, s[2:3]
	global_store_dword v212, v158, s[10:11]
	global_store_dword v213, v159, s[10:11]
	global_store_dword v214, v160, s[10:11]
	global_store_dword v215, v161, s[10:11]
	global_store_dword v216, v162, s[10:11]
	global_store_dword v217, v163, s[10:11]
	global_store_dword v218, v164, s[10:11]
	global_store_dword v219, v165, s[10:11]
	s_mov_b64 exec, -1
	s_branch .Lip0_k1_plain
.Lip0_k1_end:
	s_sub_u32 s35, s35, 0x80
	s_branch .LBB0_530
.Lip0_old:
	s_mul_hi_i32 s2, s8, 0x38e38e39
	s_lshr_b32 s3, s2, 31
	s_ashr_i32 s2, s2, 1
	s_add_i32 s37, s2, s3
	v_lshl_add_u32 v152, s8, 8, v139
	s_mul_i32 s2, s37, 0xfffff700
	s_lshl_b32 s96, s0, 8
	v_add_u32_e32 v154, s2, v152
	v_mov_b64_e32 v[150:151], s[16:17]
	s_or_b32 s56, s96, s75
	v_cmp_lt_i32_e64 s[8:9], s87, v154
	v_add_u32_e32 v132, 0xffffff00, v154
	v_ashrrev_i32_e32 v153, 31, v152
	v_mad_i64_i32 v[156:157], s[10:11], v152, s89, v[150:151]
	v_sub_u32_e32 v154, v154, v137
	s_cmpk_lt_i32 s56, 0x1740
	s_mul_hi_i32 s92, s37, 0x280
	s_mul_i32 s93, s37, 0x280
	s_mul_hi_i32 s35, s37, 0x300
	s_mulk_i32 s37, 0x300
	v_lshlrev_b64 v[160:161], 7, v[152:153]
	v_lshlrev_b64 v[158:159], 9, v[132:133]
	v_ashrrev_i32_e32 v155, 31, v154
	s_cselect_b64 s[10:11], -1, 0
	s_cmpk_gt_i32 s56, 0x173f
	v_or_b32_e32 v150, s56, v134
	s_cbranch_scc1 .LBB0_561
	s_add_i32 s0, s96, 0xfffffa00
	s_cmpk_gt_u32 s0, 0x2ff
	s_mov_b64 s[12:13], -1
	s_cbranch_scc0 .LBB0_559
	s_add_i32 s3, s56, 0xffffedc0
	s_cmpk_gt_u32 s3, 0x27f
	s_cbranch_scc0 .LBB0_556
	s_and_b32 s0, s56, 0xffffff40
	s_cmpk_lg_i32 s0, 0xd00
	s_cbranch_scc0 .LBB0_551
	s_add_i32 s0, s56, 0xfffff2c0
	s_cmpk_gt_u32 s0, 0x4ff
	s_cbranch_scc0 .LBB0_545
	s_add_i32 s0, s96, 0xfffff700
	s_cmpk_gt_u32 s0, 0x3ff
	s_cbranch_scc1 .LBB0_544
	v_mul_f32_e32 v151, v125, v125
	v_fmac_f32_e32 v151, v124, v124
	v_fmac_f32_e32 v151, v126, v126
	v_fmac_f32_e32 v151, v127, v127
	v_and_b32_e32 v162, 64, v177
	v_fmac_f32_e32 v151, v120, v120
	v_xor_b32_e32 v153, 16, v177
	v_add_u32_e32 v162, 64, v162
	v_fmac_f32_e32 v151, v121, v121
	v_cmp_lt_i32_e32 vcc, v153, v162
	v_fmac_f32_e32 v151, v122, v122
	v_fmac_f32_e32 v151, v123, v123
	v_cndmask_b32_e32 v153, v177, v153, vcc
	v_lshlrev_b32_e32 v153, 2, v153
	ds_bpermute_b32 v153, v153, v151
	s_waitcnt lgkmcnt(0)
	v_add_f32_e32 v151, v151, v153
	v_xor_b32_e32 v153, 32, v177
	v_cmp_lt_i32_e32 vcc, v153, v162
	s_nop 1
	v_cndmask_b32_e32 v153, v177, v153, vcc
	v_lshlrev_b32_e32 v153, 2, v153
	ds_bpermute_b32 v153, v153, v151
	s_and_saveexec_b64 s[12:13], s[4:5]
	s_cbranch_execz .LBB0_543
	s_add_i32 s0, s56, 0xfffff700
	v_lshl_add_u64 v[162:163], s[18:19], 0, v[160:161]
	s_lshr_b32 s0, s0, 3
	v_lshl_add_u64 v[162:163], v[162:163], 0, s[0:1]
	s_waitcnt lgkmcnt(0)
	v_add_f32_e32 v151, v151, v153
	flat_store_dword v[162:163], v151

; #define G_STAGE(bufoff, gbase, voff) do { _Pragma("unroll") for (int _i = 0; _i < 2; ++_i) \
;         __builtin_amdgcn_global_load_lds((const unsigned*)((const char*)(gbase) + (voff)[_i]), (LAS unsigned*)(lds + (bufoff) + ldsw + _i * 8192), 16, 0, 0); } while (0)
; #define G_LDA(dst, b, h) do { _Pragma("unroll") for (int m = 0; m < 4; ++m) _Pragma("unroll") for (int k = 0; k < 2; ++k) dst[m][k] = *(const LAS bf16x8*)(lds + G_SA(b, h) + aoff + m * 2048 + k * 1024); } while (0)
; #define G_LDB(dst, b, h) do { _Pragma("unroll") for (int n = 0; n < 2; ++n) _Pragma("unroll") for (int k = 0; k < 2; ++k) dst[n][k] = *(const LAS bf16x8*)(lds + G_SB(b, h) + boff + n * 2048 + k * 1024); } while (0)
; #define G_MMA(ai, bj, At, Bt_) do { __builtin_amdgcn_s_setprio(1); _Pragma("unroll") for (int m = 0; m < 4; ++m) _Pragma("unroll") for (int n = 0; n < 2; ++n) _Pragma("unroll") for (int k = 0; k < 2; ++k) \
;         acc[ai][bj][m][n] = __builtin_amdgcn_mfma_f32_16x16x32_bf16(Bt_[n][k], At[m][k], acc[ai][bj][m][n], 0, 0, 0); __builtin_amdgcn_s_setprio(0); } while (0)
; #define G_WAIT_V(n) asm volatile("s_waitcnt vmcnt(" #n ")" ::: "memory")
; #define G_WAIT_L(n) asm volatile("s_waitcnt lgkmcnt(" #n ")" ::: "memory")
; #define G_BAR __builtin_amdgcn_s_barrier()
; #define G_SCHED __builtin_amdgcn_sched_barrier(0)
; template <class Epi, bool PERMROWS = false>
; DI void gemm_phase(LAS unsigned char* lds, const bf16_t* A, int lda, const bf16_t* Bt, int K, const Sched& S, const Epi& E) {
;     ...
;             G_LDB(B0, 0, 0); G_SCHED; G_LDA(At, 0, 0); G_STAGE(G_SA(1, 1), a1 + hstepA, voffA);
;             G_WAIT_L(8); G_BAR; G_WAIT_L(0); G_MMA(0, 0, At, B0); G_BAR; G_SCHED;
;             G_LDB(B1, 0, 1); G_STAGE(G_SB(0, 0), b2, voffB);
;             G_BAR; G_WAIT_L(0); G_MMA(0, 1, At, B1); G_BAR;
;             G_LDA(At, 0, 1); G_STAGE(G_SA(0, 0), a2, voffA);
;             G_BAR; G_WAIT_L(0); G_MMA(1, 0, At, B0); G_BAR; G_SCHED;
;             G_STAGE(G_SB(0, 1), b2 + hstepB, voffB);
;             G_WAIT_V(6); G_BAR; G_MMA(1, 1, At, B1); G_BAR;
.LBB0_1981:
	s_waitcnt lgkmcnt(0)
	ds_read_b128 v[150:153], v174
	ds_read_b128 v[154:157], v174 offset:1024
	ds_read_b128 v[158:161], v174 offset:2048
	ds_read_b128 v[162:165], v174 offset:3072
	s_add_u32 s14, s12, 0xfff80080
	s_addc_u32 s15, s13, -1
	s_cmp_eq_u32 s43, 28
	s_cselect_b32 s77, s11, s15
	s_cselect_b32 s76, s20, s14
	s_cselect_b32 s15, s21, s42
	s_cselect_b32 s14, s22, s27
	v_lshl_add_u64 v[208:209], s[12:13], 0, v[144:145]
	s_add_i32 m0, s86, 0xc000
	ds_read_b128 v[166:169], v175
	ds_read_b128 v[178:181], v175 offset:1024
	ds_read_b128 v[182:185], v175 offset:2048
	ds_read_b128 v[186:189], v175 offset:3072
	ds_read_b128 v[190:193], v175 offset:4096
	ds_read_b128 v[194:197], v175 offset:5120
	ds_read_b128 v[198:201], v175 offset:6144
	ds_read_b128 v[204:207], v175 offset:7168
	global_load_lds_dwordx4 v[208:209], off
	v_lshl_add_u64 v[208:209], s[12:13], 0, v[142:143]
	s_add_i32 m0, s86, 0xe000
	s_nop 0
	global_load_lds_dwordx4 v[208:209], off
	s_waitcnt lgkmcnt(8)
	s_barrier
	s_waitcnt lgkmcnt(0)
	s_setprio 1
	s_waitcnt lgkmcnt(0)
	v_mfma_f32_16x16x32_bf16 v[124:127], v[150:153], v[166:169], v[124:127]
	v_mfma_f32_16x16x32_bf16 v[120:123], v[158:161], v[166:169], v[120:123]
	v_mfma_f32_16x16x32_bf16 v[108:111], v[150:153], v[182:185], v[108:111]
	v_mfma_f32_16x16x32_bf16 v[104:107], v[158:161], v[182:185], v[104:107]
	v_mfma_f32_16x16x32_bf16 v[92:95], v[150:153], v[190:193], v[92:95]
	v_mfma_f32_16x16x32_bf16 v[88:91], v[158:161], v[190:193], v[88:91]
	v_mfma_f32_16x16x32_bf16 v[76:79], v[150:153], v[198:201], v[76:79]
	v_mfma_f32_16x16x32_bf16 v[72:75], v[158:161], v[198:201], v[72:75]
	v_mfma_f32_16x16x32_bf16 v[124:127], v[154:157], v[178:181], v[124:127]
	v_mfma_f32_16x16x32_bf16 v[120:123], v[162:165], v[178:181], v[120:123]
	v_mfma_f32_16x16x32_bf16 v[108:111], v[154:157], v[186:189], v[108:111]
	v_mfma_f32_16x16x32_bf16 v[104:107], v[162:165], v[186:189], v[104:107]
	v_mfma_f32_16x16x32_bf16 v[92:95], v[154:157], v[194:197], v[92:95]
	v_mfma_f32_16x16x32_bf16 v[88:91], v[162:165], v[194:197], v[88:91]
	v_mfma_f32_16x16x32_bf16 v[76:79], v[154:157], v[204:207], v[76:79]
	v_mfma_f32_16x16x32_bf16 v[72:75], v[162:165], v[204:207], v[72:75]
	s_setprio 0
	s_barrier
	s_add_i32 s28, s6, s83
	v_lshl_add_u64 v[224:225], s[14:15], 0, v[128:129]
	s_mov_b32 m0, s28
	ds_read_b128 v[208:211], v176
	ds_read_b128 v[212:215], v176 offset:1024
	ds_read_b128 v[216:219], v176 offset:2048
	ds_read_b128 v[220:223], v176 offset:3072
	global_load_lds_dwordx4 v[224:225], off
	v_lshl_add_u64 v[226:227], s[14:15], 0, v[130:131]
	s_add_i32 m0, s28, 0x2000
	s_nop 0
	global_load_lds_dwordx4 v[226:227], off
	s_barrier
	s_waitcnt lgkmcnt(0)
	s_setprio 1
	s_waitcnt lgkmcnt(0)
	v_mfma_f32_16x16x32_bf16 v[116:119], v[208:211], v[166:169], v[116:119]
	v_mfma_f32_16x16x32_bf16 v[112:115], v[216:219], v[166:169], v[112:115]
	v_mfma_f32_16x16x32_bf16 v[100:103], v[208:211], v[182:185], v[100:103]
	v_mfma_f32_16x16x32_bf16 v[96:99], v[216:219], v[182:185], v[96:99]
	v_mfma_f32_16x16x32_bf16 v[84:87], v[208:211], v[190:193], v[84:87]
	v_mfma_f32_16x16x32_bf16 v[80:83], v[216:219], v[190:193], v[80:83]
	v_mfma_f32_16x16x32_bf16 v[68:71], v[208:211], v[198:201], v[68:71]
	v_mfma_f32_16x16x32_bf16 v[64:67], v[216:219], v[198:201], v[64:67]
	v_mfma_f32_16x16x32_bf16 v[116:119], v[212:215], v[178:181], v[116:119]
	v_mfma_f32_16x16x32_bf16 v[112:115], v[220:223], v[178:181], v[112:115]
	v_mfma_f32_16x16x32_bf16 v[100:103], v[212:215], v[186:189], v[100:103]
	v_mfma_f32_16x16x32_bf16 v[96:99], v[220:223], v[186:189], v[96:99]
	v_mfma_f32_16x16x32_bf16 v[84:87], v[212:215], v[194:197], v[84:87]
	v_mfma_f32_16x16x32_bf16 v[80:83], v[220:223], v[194:197], v[80:83]
	v_mfma_f32_16x16x32_bf16 v[68:71], v[212:215], v[204:207], v[68:71]
	v_mfma_f32_16x16x32_bf16 v[64:67], v[220:223], v[204:207], v[64:67]
	s_setprio 0
	s_mov_b32 m0, s86
	v_lshl_add_u64 v[228:229], s[76:77], 0, v[128:129]
	s_barrier
	ds_read_b128 v[166:169], v175 offset:16384
	ds_read_b128 v[178:181], v175 offset:17408
	ds_read_b128 v[182:185], v175 offset:18432
	ds_read_b128 v[186:189], v175 offset:19456
	ds_read_b128 v[190:193], v175 offset:20480
	ds_read_b128 v[194:197], v175 offset:21504
	ds_read_b128 v[198:201], v175 offset:22528
	ds_read_b128 v[204:207], v175 offset:23552
	global_load_lds_dwordx4 v[228:229], off
	v_lshl_add_u64 v[230:231], s[76:77], 0, v[130:131]
	s_mov_b32 m0, s87
	s_nop 0
	global_load_lds_dwordx4 v[230:231], off
	s_barrier
	s_waitcnt lgkmcnt(0)
	s_setprio 1
	s_waitcnt lgkmcnt(0)
	v_mfma_f32_16x16x32_bf16 v[60:63], v[150:153], v[166:169], v[60:63]
	v_mfma_f32_16x16x32_bf16 v[56:59], v[158:161], v[166:169], v[56:59]
	v_mfma_f32_16x16x32_bf16 v[44:47], v[150:153], v[182:185], v[44:47]
	v_mfma_f32_16x16x32_bf16 v[40:43], v[158:161], v[182:185], v[40:43]
	v_mfma_f32_16x16x32_bf16 v[28:31], v[150:153], v[190:193], v[28:31]
	v_mfma_f32_16x16x32_bf16 v[24:27], v[158:161], v[190:193], v[24:27]
	v_mfma_f32_16x16x32_bf16 v[12:15], v[150:153], v[198:201], v[12:15]
	v_mfma_f32_16x16x32_bf16 v[8:11], v[158:161], v[198:201], v[8:11]
	v_mfma_f32_16x16x32_bf16 v[60:63], v[154:157], v[178:181], v[60:63]
	v_mfma_f32_16x16x32_bf16 v[56:59], v[162:165], v[178:181], v[56:59]
	v_mfma_f32_16x16x32_bf16 v[44:47], v[154:157], v[186:189], v[44:47]
	v_mfma_f32_16x16x32_bf16 v[40:43], v[162:165], v[186:189], v[40:43]
	v_mfma_f32_16x16x32_bf16 v[28:31], v[154:157], v[194:197], v[28:31]
	v_mfma_f32_16x16x32_bf16 v[24:27], v[162:165], v[194:197], v[24:27]
	v_mfma_f32_16x16x32_bf16 v[12:15], v[154:157], v[204:207], v[12:15]
	v_mfma_f32_16x16x32_bf16 v[8:11], v[162:165], v[204:207], v[8:11]
	s_setprio 0
	s_barrier
; #define G_STAGE(bufoff, gbase, voff) do { _Pragma("unroll") for (int _i = 0; _i < 2; ++_i) \
;         __builtin_amdgcn_global_load_lds((const unsigned*)((const char*)(gbase) + (voff)[_i]), (LAS unsigned*)(lds + (bufoff) + ldsw + _i * 8192), 16, 0, 0); } while (0)
; #define G_LDA(dst, b, h) do { _Pragma("unroll") for (int m = 0; m < 4; ++m) _Pragma("unroll") for (int k = 0; k < 2; ++k) dst[m][k] = *(const LAS bf16x8*)(lds + G_SA(b, h) + aoff + m * 2048 + k * 1024); } while (0)
; #define G_LDB(dst, b, h) do { _Pragma("unroll") for (int n = 0; n < 2; ++n) _Pragma("unroll") for (int k = 0; k < 2; ++k) dst[n][k] = *(const LAS bf16x8*)(lds + G_SB(b, h) + boff + n * 2048 + k * 1024); } while (0)
; #define G_MMA(ai, bj, At, Bt_) do { __builtin_amdgcn_s_setprio(1); _Pragma("unroll") for (int m = 0; m < 4; ++m) _Pragma("unroll") for (int n = 0; n < 2; ++n) _Pragma("unroll") for (int k = 0; k < 2; ++k) \
;         acc[ai][bj][m][n] = __builtin_amdgcn_mfma_f32_16x16x32_bf16(Bt_[n][k], At[m][k], acc[ai][bj][m][n], 0, 0, 0); __builtin_amdgcn_s_setprio(0); } while (0)
; #define G_WAIT_V(n) asm volatile("s_waitcnt vmcnt(" #n ")" ::: "memory")
; #define G_WAIT_L(n) asm volatile("s_waitcnt lgkmcnt(" #n ")" ::: "memory")
; #define G_BAR __builtin_amdgcn_s_barrier()
; #define G_SCHED __builtin_amdgcn_sched_barrier(0)
; template <class Epi, bool PERMROWS = false>
; DI void gemm_phase(LAS unsigned char* lds, const bf16_t* A, int lda, const bf16_t* Bt, int K, const Sched& S, const Epi& E) {
;     ...
;             G_STAGE(G_SB(0, 1), b2 + hstepB, voffB);
;             G_WAIT_V(6); G_BAR; G_MMA(1, 1, At, B1); G_BAR;
;             G_LDB(B0, 1, 0); G_SCHED; G_LDA(At, 1, 0); G_STAGE(G_SA(0, 1), a2 + hstepA, voffA);
;             G_WAIT_L(8); G_BAR; G_WAIT_L(0); G_MMA(0, 0, At, B0); G_BAR; G_SCHED;
;             G_LDB(B1, 1, 1); G_STAGE(G_SB(1, 0), b3, voffB);
;             G_BAR; G_WAIT_L(0); G_MMA(0, 1, At, B1); G_BAR;
;             G_LDA(At, 1, 1); G_STAGE(G_SA(1, 0), a3, voffA);
;             G_BAR; G_WAIT_L(0); G_MMA(1, 0, At, B0); G_BAR; G_SCHED;
	s_add_u32 s28, s14, 0x80000
	s_addc_u32 s29, s15, 0
	s_add_i32 s54, s7, s83
	v_lshl_add_u64 v[150:151], s[28:29], 0, v[128:129]
	s_mov_b32 m0, s54
	s_nop 0
	global_load_lds_dwordx4 v[150:151], off
	v_lshl_add_u64 v[150:151], s[28:29], 0, v[130:131]
	s_add_i32 m0, s54, 0x2000
	s_nop 0
	global_load_lds_dwordx4 v[150:151], off
	s_waitcnt vmcnt(6)
	s_barrier
	s_setprio 1
	v_mfma_f32_16x16x32_bf16 v[52:55], v[208:211], v[166:169], v[52:55]
	v_mfma_f32_16x16x32_bf16 v[48:51], v[216:219], v[166:169], v[48:51]
	v_mfma_f32_16x16x32_bf16 v[36:39], v[208:211], v[182:185], v[36:39]
	v_mfma_f32_16x16x32_bf16 v[32:35], v[216:219], v[182:185], v[32:35]
	v_mfma_f32_16x16x32_bf16 v[20:23], v[208:211], v[190:193], v[20:23]
	v_mfma_f32_16x16x32_bf16 v[16:19], v[216:219], v[190:193], v[16:19]
	v_mfma_f32_16x16x32_bf16 v[4:7], v[208:211], v[198:201], v[4:7]
	v_mfma_f32_16x16x32_bf16 v[0:3], v[216:219], v[198:201], v[0:3]
	v_mfma_f32_16x16x32_bf16 v[52:55], v[212:215], v[178:181], v[52:55]
	v_mfma_f32_16x16x32_bf16 v[48:51], v[220:223], v[178:181], v[48:51]
	v_mfma_f32_16x16x32_bf16 v[36:39], v[212:215], v[186:189], v[36:39]
	v_mfma_f32_16x16x32_bf16 v[32:35], v[220:223], v[186:189], v[32:35]
	v_mfma_f32_16x16x32_bf16 v[20:23], v[212:215], v[194:197], v[20:23]
	v_mfma_f32_16x16x32_bf16 v[16:19], v[220:223], v[194:197], v[16:19]
	v_mfma_f32_16x16x32_bf16 v[4:7], v[212:215], v[204:207], v[4:7]
	v_mfma_f32_16x16x32_bf16 v[0:3], v[220:223], v[204:207], v[0:3]
	s_setprio 0
	s_add_i32 s54, 0, 0x18000
	v_add_u32_e32 v132, s54, v170
	s_barrier
	ds_read_b128 v[150:153], v132
	ds_read_b128 v[154:157], v132 offset:1024
	ds_read_b128 v[158:161], v132 offset:2048
	ds_read_b128 v[162:165], v132 offset:3072
	s_add_u32 s28, s76, 0x80000
	s_addc_u32 s29, s77, 0
	s_mov_b32 m0, s94
	v_lshl_add_u64 v[208:209], s[28:29], 0, v[128:129]
	ds_read_b128 v[166:169], v175 offset:32768
	ds_read_b128 v[178:181], v175 offset:33792
	ds_read_b128 v[182:185], v175 offset:34816
	ds_read_b128 v[186:189], v175 offset:35840
	ds_read_b128 v[190:193], v175 offset:36864
	ds_read_b128 v[194:197], v175 offset:37888
	ds_read_b128 v[198:201], v175 offset:38912
	ds_read_b128 v[204:207], v175 offset:39936
	global_load_lds_dwordx4 v[208:209], off
	v_lshl_add_u64 v[208:209], s[28:29], 0, v[130:131]
	s_mov_b32 m0, s95
	s_nop 0
	global_load_lds_dwordx4 v[208:209], off
	s_waitcnt lgkmcnt(8)
	s_barrier
	s_waitcnt lgkmcnt(0)
	s_setprio 1
	s_waitcnt lgkmcnt(0)
	v_mfma_f32_16x16x32_bf16 v[124:127], v[150:153], v[166:169], v[124:127]
	v_mfma_f32_16x16x32_bf16 v[120:123], v[158:161], v[166:169], v[120:123]
	v_mfma_f32_16x16x32_bf16 v[108:111], v[150:153], v[182:185], v[108:111]
	v_mfma_f32_16x16x32_bf16 v[104:107], v[158:161], v[182:185], v[104:107]
	v_mfma_f32_16x16x32_bf16 v[92:95], v[150:153], v[190:193], v[92:95]
	v_mfma_f32_16x16x32_bf16 v[88:91], v[158:161], v[190:193], v[88:91]
	v_mfma_f32_16x16x32_bf16 v[76:79], v[150:153], v[198:201], v[76:79]
	v_mfma_f32_16x16x32_bf16 v[72:75], v[158:161], v[198:201], v[72:75]
	v_mfma_f32_16x16x32_bf16 v[124:127], v[154:157], v[178:181], v[124:127]
	v_mfma_f32_16x16x32_bf16 v[120:123], v[162:165], v[178:181], v[120:123]
	v_mfma_f32_16x16x32_bf16 v[108:111], v[154:157], v[186:189], v[108:111]
	v_mfma_f32_16x16x32_bf16 v[104:107], v[162:165], v[186:189], v[104:107]
	v_mfma_f32_16x16x32_bf16 v[92:95], v[154:157], v[194:197], v[92:95]
	v_mfma_f32_16x16x32_bf16 v[88:91], v[162:165], v[194:197], v[88:91]
	v_mfma_f32_16x16x32_bf16 v[76:79], v[154:157], v[204:207], v[76:79]
	v_mfma_f32_16x16x32_bf16 v[72:75], v[162:165], v[204:207], v[72:75]
	s_setprio 0
	s_barrier
	s_add_i32 s28, 0, 0x1c000
	s_add_i32 s29, s54, s83
	v_add_u32_e32 v132, s28, v170
	v_lshl_add_u64 v[224:225], v[224:225], 0, s[16:17]
	s_mov_b32 m0, s29
	ds_read_b128 v[208:211], v132
	ds_read_b128 v[212:215], v132 offset:1024
	ds_read_b128 v[216:219], v132 offset:2048
	ds_read_b128 v[220:223], v132 offset:3072
	global_load_lds_dwordx4 v[224:225], off
	v_lshl_add_u64 v[224:225], v[226:227], 0, s[16:17]
	s_add_i32 m0, s29, 0x2000
	s_nop 0
	global_load_lds_dwordx4 v[224:225], off
	s_barrier
	s_waitcnt lgkmcnt(0)
	s_setprio 1
	s_waitcnt lgkmcnt(0)
	v_mfma_f32_16x16x32_bf16 v[116:119], v[208:211], v[166:169], v[116:119]
	v_mfma_f32_16x16x32_bf16 v[112:115], v[216:219], v[166:169], v[112:115]
	v_mfma_f32_16x16x32_bf16 v[100:103], v[208:211], v[182:185], v[100:103]
	v_mfma_f32_16x16x32_bf16 v[96:99], v[216:219], v[182:185], v[96:99]
	v_mfma_f32_16x16x32_bf16 v[84:87], v[208:211], v[190:193], v[84:87]
	v_mfma_f32_16x16x32_bf16 v[80:83], v[216:219], v[190:193], v[80:83]
	v_mfma_f32_16x16x32_bf16 v[68:71], v[208:211], v[198:201], v[68:71]
	v_mfma_f32_16x16x32_bf16 v[64:67], v[216:219], v[198:201], v[64:67]
	v_mfma_f32_16x16x32_bf16 v[116:119], v[212:215], v[178:181], v[116:119]
	v_mfma_f32_16x16x32_bf16 v[112:115], v[220:223], v[178:181], v[112:115]
	v_mfma_f32_16x16x32_bf16 v[100:103], v[212:215], v[186:189], v[100:103]
	v_mfma_f32_16x16x32_bf16 v[96:99], v[220:223], v[186:189], v[96:99]
	v_mfma_f32_16x16x32_bf16 v[84:87], v[212:215], v[194:197], v[84:87]
	v_mfma_f32_16x16x32_bf16 v[80:83], v[220:223], v[194:197], v[80:83]
	v_mfma_f32_16x16x32_bf16 v[68:71], v[212:215], v[204:207], v[68:71]
	v_mfma_f32_16x16x32_bf16 v[64:67], v[220:223], v[204:207], v[64:67]
	s_setprio 0
	s_mov_b32 m0, s97
	v_lshl_add_u64 v[224:225], v[228:229], 0, s[16:17]
	s_barrier
	ds_read_b128 v[166:169], v175 offset:49152
	ds_read_b128 v[178:181], v175 offset:50176
	ds_read_b128 v[182:185], v175 offset:51200
	ds_read_b128 v[186:189], v175 offset:52224
	ds_read_b128 v[190:193], v175 offset:53248
	ds_read_b128 v[194:197], v175 offset:54272
	ds_read_b128 v[198:201], v175 offset:55296
	ds_read_b128 v[204:207], v175 offset:56320
	global_load_lds_dwordx4 v[224:225], off
	v_lshl_add_u64 v[224:225], v[230:231], 0, s[16:17]
	s_mov_b32 m0, s36
	s_nop 0
	global_load_lds_dwordx4 v[224:225], off
	s_barrier
; #define G_STAGE(bufoff, gbase, voff) do { _Pragma("unroll") for (int _i = 0; _i < 2; ++_i) \
;         __builtin_amdgcn_global_load_lds((const unsigned*)((const char*)(gbase) + (voff)[_i]), (LAS unsigned*)(lds + (bufoff) + ldsw + _i * 8192), 16, 0, 0); } while (0)
; #define G_LDA(dst, b, h) do { _Pragma("unroll") for (int m = 0; m < 4; ++m) _Pragma("unroll") for (int k = 0; k < 2; ++k) dst[m][k] = *(const LAS bf16x8*)(lds + G_SA(b, h) + aoff + m * 2048 + k * 1024); } while (0)
; #define G_LDB(dst, b, h) do { _Pragma("unroll") for (int n = 0; n < 2; ++n) _Pragma("unroll") for (int k = 0; k < 2; ++k) dst[n][k] = *(const LAS bf16x8*)(lds + G_SB(b, h) + boff + n * 2048 + k * 1024); } while (0)
; #define G_BAR __builtin_amdgcn_s_barrier()
; template <class Epi, bool PERMROWS = false>
; DI void gemm_phase(LAS unsigned char* lds, const bf16_t* A, int lda, const bf16_t* Bt, int K, const Sched& S, const Epi& E) {
;     ...
;             G_WAIT_V(6); G_BAR; G_MMA(1, 1, At, B1); G_BAR;
;             G_LDB(B0, 1, 0); G_SCHED; G_LDA(At, 1, 0); G_STAGE(G_SA(0, 1), a2 + hstepA, voffA);
;             G_WAIT_L(8); G_BAR; G_WAIT_L(0); G_MMA(0, 0, At, B0); G_BAR; G_SCHED;
;             G_LDB(B1, 1, 1); G_STAGE(G_SB(1, 0), b3, voffB);
;             G_BAR; G_WAIT_L(0); G_MMA(0, 1, At, B1); G_BAR;
;             G_LDA(At, 1, 1); G_STAGE(G_SA(1, 0), a3, voffA);
;             G_BAR; G_WAIT_L(0); G_MMA(1, 0, At, B0); G_BAR; G_SCHED;
;             G_STAGE(G_SB(1, 1), b3 + hstepB, voffB);
;             G_WAIT_V(6); G_BAR; G_MMA(1, 1, At, B1); G_BAR;
;     DI void operator()(const f32x4 (&acc)[2][2][4][2], const Unit& u, int wr, int wc, int fr, int fq) const {
;         bf16_t* P = (bf16_t*)(ws + WS_P);
;         const int b = u.pm / 9;
; #pragma unroll
;         for (int ai = 0; ai < 2; ++ai)
; #pragma unroll
;             for (int m = 0; m < 4; ++m) {
;                 const int row = u.pm * BM + ai * HALF + wr * 64 + m * 16 + fr;
;                 const int r = row - b * RB; const bool lat = r >= CL; const int t = r - CL;
; #pragma unroll
;                 for (int bj = 0; bj < 2; ++bj) {
;                     const int colg = u.pn * BM + bj * HALF + wc * 32;
;                     f32x4 v0 = acc[ai][bj][m][0], v1 = acc[ai][bj][m][1];
;                     const int c0 = colg + 4 * fq;
;                     if (colg >= INW) continue;
;                     if (colg >= C_NAV && colg < C_CQ) {
	s_waitcnt lgkmcnt(0)
	s_setprio 1
	s_waitcnt lgkmcnt(0)
	v_mfma_f32_16x16x32_bf16 v[60:63], v[150:153], v[166:169], v[60:63]
	v_mfma_f32_16x16x32_bf16 v[56:59], v[158:161], v[166:169], v[56:59]
	v_mfma_f32_16x16x32_bf16 v[44:47], v[150:153], v[182:185], v[44:47]
	v_mfma_f32_16x16x32_bf16 v[40:43], v[158:161], v[182:185], v[40:43]
	v_mfma_f32_16x16x32_bf16 v[28:31], v[150:153], v[190:193], v[28:31]
	v_mfma_f32_16x16x32_bf16 v[24:27], v[158:161], v[190:193], v[24:27]
	v_mfma_f32_16x16x32_bf16 v[12:15], v[150:153], v[198:201], v[12:15]
	v_mfma_f32_16x16x32_bf16 v[8:11], v[158:161], v[198:201], v[8:11]
	v_mfma_f32_16x16x32_bf16 v[60:63], v[154:157], v[178:181], v[60:63]
	v_mfma_f32_16x16x32_bf16 v[56:59], v[162:165], v[178:181], v[56:59]
	v_mfma_f32_16x16x32_bf16 v[44:47], v[154:157], v[186:189], v[44:47]
	v_mfma_f32_16x16x32_bf16 v[40:43], v[162:165], v[186:189], v[40:43]
	v_mfma_f32_16x16x32_bf16 v[28:31], v[154:157], v[194:197], v[28:31]
	v_mfma_f32_16x16x32_bf16 v[24:27], v[162:165], v[194:197], v[24:27]
	v_mfma_f32_16x16x32_bf16 v[12:15], v[154:157], v[204:207], v[12:15]
	v_mfma_f32_16x16x32_bf16 v[8:11], v[162:165], v[204:207], v[8:11]
	s_setprio 0
	s_barrier
	s_add_u32 s14, s14, 0x80080
	s_addc_u32 s15, s15, 0
	s_add_i32 s28, s28, s83
	v_lshl_add_u64 v[150:151], s[14:15], 0, v[128:129]
	s_mov_b32 m0, s28
	s_nop 0
	global_load_lds_dwordx4 v[150:151], off
	v_lshl_add_u64 v[150:151], s[14:15], 0, v[130:131]
	s_add_i32 m0, s28, 0x2000
	s_nop 0
	global_load_lds_dwordx4 v[150:151], off
	s_waitcnt vmcnt(6)
	s_barrier
	s_setprio 1
	v_mfma_f32_16x16x32_bf16 v[52:55], v[208:211], v[166:169], v[52:55]
	v_mfma_f32_16x16x32_bf16 v[48:51], v[216:219], v[166:169], v[48:51]
	v_mfma_f32_16x16x32_bf16 v[36:39], v[208:211], v[182:185], v[36:39]
	v_mfma_f32_16x16x32_bf16 v[32:35], v[216:219], v[182:185], v[32:35]
	v_mfma_f32_16x16x32_bf16 v[20:23], v[208:211], v[190:193], v[20:23]
	v_mfma_f32_16x16x32_bf16 v[16:19], v[216:219], v[190:193], v[16:19]
	v_mfma_f32_16x16x32_bf16 v[4:7], v[208:211], v[198:201], v[4:7]
	v_mfma_f32_16x16x32_bf16 v[0:3], v[216:219], v[198:201], v[0:3]
	v_mfma_f32_16x16x32_bf16 v[52:55], v[212:215], v[178:181], v[52:55]
	v_mfma_f32_16x16x32_bf16 v[48:51], v[220:223], v[178:181], v[48:51]
	v_mfma_f32_16x16x32_bf16 v[36:39], v[212:215], v[186:189], v[36:39]
	v_mfma_f32_16x16x32_bf16 v[32:35], v[220:223], v[186:189], v[32:35]
	v_mfma_f32_16x16x32_bf16 v[20:23], v[212:215], v[194:197], v[20:23]
	v_mfma_f32_16x16x32_bf16 v[16:19], v[220:223], v[194:197], v[16:19]
	v_mfma_f32_16x16x32_bf16 v[4:7], v[212:215], v[204:207], v[4:7]
	v_mfma_f32_16x16x32_bf16 v[0:3], v[220:223], v[204:207], v[0:3]
	s_setprio 0
	s_add_i32 s43, s43, 2
	s_add_u32 s27, s27, 0x100
	s_addc_u32 s42, s42, 0
	s_add_u32 s12, s12, 0x100
	s_addc_u32 s13, s13, 0
	s_cmp_gt_u32 s43, 29
	s_barrier
	s_cbranch_scc0 .LBB0_1981
	v_bfe_u32 v194, v202, 6, 2
	v_and_b32_e32 v169, 15, v202
	v_readfirstlane_b32 s11, v194
	s_lshl_b32 s29, s0, 8
	s_lshl_b32 s54, s11, 5
	s_add_u32 s29, s29, s54
	s_mov_b32 s32, 1
	s_cmpk_lt_u32 s29, 0x600
	s_cbranch_scc1 .Lip1_c0_d
	s_mov_b32 s32, 4
	s_cmpk_lt_u32 s29, 0x900
	s_cbranch_scc1 .Lip1_c0_d
	s_mov_b32 s32, 6
	s_cmpk_lt_u32 s29, 0xd00
	s_cbranch_scc1 .Lip1_c0_d
	s_cmpk_lt_u32 s29, 0xd40
	s_cbranch_scc1 .Lip1_old
	s_mov_b32 s32, 2
	s_cmpk_lt_u32 s29, 0xfc0
	s_cbranch_scc1 .Lip1_c0_d
	s_mov_b32 s32, 3
	s_cmpk_lt_u32 s29, 0x1240
	s_cbranch_scc1 .Lip1_c0_d
	s_mov_b32 s32, 5
	s_cmpk_lt_u32 s29, 0x14c0
	s_cbranch_scc1 .Lip1_c0_d
	s_mov_b32 s32, 1
	s_cmpk_lt_u32 s29, 0x1740
	s_cbranch_scc1 .Lip1_c0_d
	s_mov_b32 s32, 0
.Lip1_c0_d:
	s_add_u32 s29, s29, 0x80
	s_mov_b32 s43, 1
	s_cmpk_lt_u32 s29, 0x600
	s_cbranch_scc1 .Lip1_c1_d
	s_mov_b32 s43, 4
	s_cmpk_lt_u32 s29, 0x900
	s_cbranch_scc1 .Lip1_c1_d
	s_mov_b32 s43, 6
	s_cmpk_lt_u32 s29, 0xd00
	s_cbranch_scc1 .Lip1_c1_d
	s_cmpk_lt_u32 s29, 0xd40
	s_cbranch_scc1 .Lip1_old
	s_mov_b32 s43, 2
	s_cmpk_lt_u32 s29, 0xfc0
	s_cbranch_scc1 .Lip1_c1_d
	s_mov_b32 s43, 3
	s_cmpk_lt_u32 s29, 0x1240
	s_cbranch_scc1 .Lip1_c1_d
	s_mov_b32 s43, 5
	s_cmpk_lt_u32 s29, 0x14c0
	s_cbranch_scc1 .Lip1_c1_d
	s_mov_b32 s43, 1
	s_cmpk_lt_u32 s29, 0x1740
	s_cbranch_scc1 .Lip1_c1_d
	s_mov_b32 s43, 0
.Lip1_c1_d:
	s_sub_u32 s29, s29, 0x80
	v_bfe_u32 v194, v202, 8, 1
	v_lshl_add_u32 v195, v194, 6, v169
	v_bfe_u32 v196, v202, 4, 2
	v_and_b32_e32 v197, 63, v202
	s_mul_i32 s27, s10, 57
	s_lshr_b32 s27, s27, 9
	s_mul_i32 s54, s27, 9
	s_sub_u32 s22, s10, s54
	v_mul_u32_u24_e32 v169, 0x3000, v195
	v_lshl_add_u32 v150, v196, 3, v169
	v_add_u32_e32 v151, 0x30000, v150
	v_add_u32_e32 v152, 0x60000, v150
	v_add_u32_e32 v153, 0x90000, v150
	v_add_u32_e32 v154, 0x180000, v150
	v_add_u32_e32 v155, 0x1b0000, v150
	v_add_u32_e32 v156, 0x1e0000, v150
	v_add_u32_e32 v157, 0x210000, v150
	v_lshrrev_b32_e32 v169, 6, v202
	v_lshlrev_b32_e32 v169, 10, v169
	v_add_u32_e32 v169, 0x20000, v169
	v_and_b32_e32 v194, 15, v202
	v_lshl_add_u32 v167, v196, 7, v169
	v_lshl_add_u32 v167, v194, 1, v167
	v_lshrrev_b32_e32 v194, 1, v197
	v_lshl_add_u32 v168, v194, 5, v169
	v_and_b32_e32 v169, 1, v197
	v_lshl_add_u32 v168, v169, 4, v168
	v_mul_u32_u24_e32 v166, 0x1200, v194
	v_lshl_add_u32 v166, v169, 4, v166
	v_bfe_u32 v169, v202, 8, 1
	v_lshl_add_u32 v166, v169, 7, v166
	s_cmp_eq_u32 s32, 0
	s_cbranch_scc1 .Lip1_k0_end
	s_cmp_eq_u32 s32, 1
	s_cbranch_scc1 .Lip1_k0_plain
	s_cmp_eq_u32 s32, 4
	s_cbranch_scc1 .Lip1_k0_nav
	s_cmp_eq_u32 s32, 5
	s_cbranch_scc1 .Lip1_k0_rv
	s_cmp_eq_u32 s32, 6
	s_cbranch_scc1 .Lip1_k0_ssq
	s_cmp_eq_u32 s22, 0
	s_cbranch_scc1 .Lip1_nr0
; DI void rope4(f32x4& v0, f32x4& v1, const float* tab  ) {
;     const f32x4 t0 = *(const f32x4*)tab, t1 = *(const f32x4*)(tab + 4);
;     const float c[4] = {t0[0], t0[2], t1[0], t1[2]}, s[4] = {t0[1], t0[3], t1[1], t1[3]};
; #pragma unroll
;     for (int j = 0; j < 4; ++j) { const float a = v0[j], b = v1[j]; v0[j] = a * c[j] - b * s[j]; v1[j] = b * c[j] + a * s[j]; }
; }
;     DI void operator()(const f32x4 (&acc)[2][2][4][2], const Unit& u, int wr, int wc, int fr, int fq) const {
;     ...
;                     } else if (colg >= C_RQ && colg < C_RV) {
;                         if (lat) rope4(v0, v1, (const float*)(ws + WS_TABR) + ((size_t)t * 64 + (((colg - C_RQ) & 127) >> 5) * 16 + 4 * fq) * 2);
	s_sub_u32 s69, s29, 0xd40
	s_and_b32 s69, s69, 0x7f
	s_lshr_b32 s69, s69, 5
	s_lshl_b32 s69, s69, 7
	s_sub_u32 s54, s22, 1
	s_lshl_b32 s54, s54, 17
	s_add_u32 s54, s54, s69
	v_lshlrev_b32_e32 v169, 5, v196
	v_lshl_add_u32 v158, v195, 9, v169
	v_add_u32_e32 v158, s54, v158
	v_add_u32_e32 v159, 0x2000, v158
	v_add_u32_e32 v160, 0x4000, v158
	v_add_u32_e32 v161, 0x6000, v158
	v_add_u32_e32 v162, 0x10000, v158
	v_add_u32_e32 v163, 0x12000, v158
	v_add_u32_e32 v164, 0x14000, v158
	v_add_u32_e32 v165, 0x16000, v158
	s_add_u32 s14, s50, 0x100000
	s_addc_u32 s15, s51, 0
	global_load_dwordx4 v[204:207], v158, s[14:15]
	global_load_dwordx4 v[208:211], v158, s[14:15] offset:16
	global_load_dwordx4 v[212:215], v159, s[14:15]
	global_load_dwordx4 v[216:219], v159, s[14:15] offset:16
	global_load_dwordx4 v[220:223], v160, s[14:15]
	global_load_dwordx4 v[224:227], v160, s[14:15] offset:16
	global_load_dwordx4 v[228:231], v161, s[14:15]
	global_load_dwordx4 v[232:235], v161, s[14:15] offset:16
	global_load_dwordx4 v[236:239], v162, s[14:15]
	global_load_dwordx4 v[240:243], v162, s[14:15] offset:16
	global_load_dwordx4 v[244:247], v163, s[14:15]
	global_load_dwordx4 v[248:251], v163, s[14:15] offset:16
	global_load_dwordx4 v[178:181], v164, s[14:15]
	global_load_dwordx4 v[182:185], v164, s[14:15] offset:16
	global_load_dwordx4 v[186:189], v165, s[14:15]
	global_load_dwordx4 v[190:193], v165, s[14:15] offset:16
	s_waitcnt vmcnt(0)
	v_mul_f32_e32 v169, v124, v205
	v_mul_f32_e32 v124, v124, v204
	v_fma_f32 v124, -v120, v205, v124
	v_fma_f32 v120, v120, v204, v169
	v_mul_f32_e32 v169, v125, v207
	v_mul_f32_e32 v125, v125, v206
	v_fma_f32 v125, -v121, v207, v125
	v_fma_f32 v121, v121, v206, v169
	v_mul_f32_e32 v169, v126, v209
	v_mul_f32_e32 v126, v126, v208
	v_fma_f32 v126, -v122, v209, v126
	v_fma_f32 v122, v122, v208, v169
	v_mul_f32_e32 v169, v127, v211
	v_mul_f32_e32 v127, v127, v210
	v_fma_f32 v127, -v123, v211, v127
	v_fma_f32 v123, v123, v210, v169
	v_mul_f32_e32 v169, v108, v213
	v_mul_f32_e32 v108, v108, v212
	v_fma_f32 v108, -v104, v213, v108
	v_fma_f32 v104, v104, v212, v169
	v_mul_f32_e32 v169, v109, v215
	v_mul_f32_e32 v109, v109, v214
	v_fma_f32 v109, -v105, v215, v109
	v_fma_f32 v105, v105, v214, v169
	v_mul_f32_e32 v169, v110, v217
	v_mul_f32_e32 v110, v110, v216
	v_fma_f32 v110, -v106, v217, v110
	v_fma_f32 v106, v106, v216, v169
	v_mul_f32_e32 v169, v111, v219
	v_mul_f32_e32 v111, v111, v218
	v_fma_f32 v111, -v107, v219, v111
	v_fma_f32 v107, v107, v218, v169
	v_mul_f32_e32 v169, v92, v221
	v_mul_f32_e32 v92, v92, v220
	v_fma_f32 v92, -v88, v221, v92
	v_fma_f32 v88, v88, v220, v169
	v_mul_f32_e32 v169, v93, v223
	v_mul_f32_e32 v93, v93, v222
	v_fma_f32 v93, -v89, v223, v93
	v_fma_f32 v89, v89, v222, v169
	v_mul_f32_e32 v169, v94, v225
	v_mul_f32_e32 v94, v94, v224
	v_fma_f32 v94, -v90, v225, v94
	v_fma_f32 v90, v90, v224, v169
	v_mul_f32_e32 v169, v95, v227
	v_mul_f32_e32 v95, v95, v226
	v_fma_f32 v95, -v91, v227, v95
	v_fma_f32 v91, v91, v226, v169
	v_mul_f32_e32 v169, v76, v229
	v_mul_f32_e32 v76, v76, v228
	v_fma_f32 v76, -v72, v229, v76
	v_fma_f32 v72, v72, v228, v169
	v_mul_f32_e32 v169, v77, v231
	v_mul_f32_e32 v77, v77, v230
	v_fma_f32 v77, -v73, v231, v77
	v_fma_f32 v73, v73, v230, v169
	v_mul_f32_e32 v169, v78, v233
	v_mul_f32_e32 v78, v78, v232
	v_fma_f32 v78, -v74, v233, v78
	v_fma_f32 v74, v74, v232, v169
	v_mul_f32_e32 v169, v79, v235
	v_mul_f32_e32 v79, v79, v234
	v_fma_f32 v79, -v75, v235, v79
	v_fma_f32 v75, v75, v234, v169
	v_mul_f32_e32 v169, v60, v237
	v_mul_f32_e32 v60, v60, v236
	v_fma_f32 v60, -v56, v237, v60
	v_fma_f32 v56, v56, v236, v169
	v_mul_f32_e32 v169, v61, v239
	v_mul_f32_e32 v61, v61, v238
	v_fma_f32 v61, -v57, v239, v61
	v_fma_f32 v57, v57, v238, v169
	v_mul_f32_e32 v169, v62, v241
	v_mul_f32_e32 v62, v62, v240
	v_fma_f32 v62, -v58, v241, v62
	v_fma_f32 v58, v58, v240, v169
	v_mul_f32_e32 v169, v63, v243
	v_mul_f32_e32 v63, v63, v242
	v_fma_f32 v63, -v59, v243, v63
	v_fma_f32 v59, v59, v242, v169
	v_mul_f32_e32 v169, v44, v245
	v_mul_f32_e32 v44, v44, v244
	v_fma_f32 v44, -v40, v245, v44
	v_fma_f32 v40, v40, v244, v169
	v_mul_f32_e32 v169, v45, v247
	v_mul_f32_e32 v45, v45, v246
	v_fma_f32 v45, -v41, v247, v45
	v_fma_f32 v41, v41, v246, v169
	v_mul_f32_e32 v169, v46, v249
	v_mul_f32_e32 v46, v46, v248
	v_fma_f32 v46, -v42, v249, v46
	v_fma_f32 v42, v42, v248, v169
	v_mul_f32_e32 v169, v47, v251
	v_mul_f32_e32 v47, v47, v250
	v_fma_f32 v47, -v43, v251, v47
	v_fma_f32 v43, v43, v250, v169
	v_mul_f32_e32 v169, v28, v179
	v_mul_f32_e32 v28, v28, v178
	v_fma_f32 v28, -v24, v179, v28
	v_fma_f32 v24, v24, v178, v169
	v_mul_f32_e32 v169, v29, v181
	v_mul_f32_e32 v29, v29, v180
	v_fma_f32 v29, -v25, v181, v29
	v_fma_f32 v25, v25, v180, v169
	v_mul_f32_e32 v169, v30, v183
	v_mul_f32_e32 v30, v30, v182
	v_fma_f32 v30, -v26, v183, v30
	v_fma_f32 v26, v26, v182, v169
	v_mul_f32_e32 v169, v31, v185
	v_mul_f32_e32 v31, v31, v184
	v_fma_f32 v31, -v27, v185, v31
	v_fma_f32 v27, v27, v184, v169
	v_mul_f32_e32 v169, v12, v187
	v_mul_f32_e32 v12, v12, v186
	v_fma_f32 v12, -v8, v187, v12
	v_fma_f32 v8, v8, v186, v169
	v_mul_f32_e32 v169, v13, v189
	v_mul_f32_e32 v13, v13, v188
	v_fma_f32 v13, -v9, v189, v13
	v_fma_f32 v9, v9, v188, v169
	v_mul_f32_e32 v169, v14, v191
	v_mul_f32_e32 v14, v14, v190
	v_fma_f32 v14, -v10, v191, v14
	v_fma_f32 v10, v10, v190, v169
	v_mul_f32_e32 v169, v15, v193
	v_mul_f32_e32 v15, v15, v192
	v_fma_f32 v15, -v11, v193, v15
	v_fma_f32 v11, v11, v192, v169
; #define LAS __attribute__((address_space(3)))
; DI unsigned cvt_pk_bf16(float lo, float hi) { unsigned r; asm volatile("v_cvt_pk_bf16_f32 %0, %1, %2" : "=v"(r) : "v"(lo), "v"(hi)); return r; }
; DI void st_bf16x4(bf16_t* p, f32x4 v) { u32x2 w; w.x = cvt_pk_bf16(v[0], v[1]); w.y = cvt_pk_bf16(v[2], v[3]); *(u32x2*)p = w; }
; DI void st_tr16x32(LAS unsigned char* area, bf16_t* dst_f0_t0  , f32x4 v0, f32x4 v1, int fr, int fq, int lane) {
;     const unsigned p01 = cvt_pk_bf16(v0[0], v0[1]), p23 = cvt_pk_bf16(v0[2], v0[3]), q01 = cvt_pk_bf16(v1[0], v1[1]), q23 = cvt_pk_bf16(v1[2], v1[3]);
;     LAS bf16_t* w = (LAS bf16_t*)(area + (4 * fq) * 32 + fr * 2);
;     w[0 * 16] = (bf16_t)(p01 & 0xffffu); w[1 * 16] = (bf16_t)(p01 >> 16); w[2 * 16] = (bf16_t)(p23 & 0xffffu); w[3 * 16] = (bf16_t)(p23 >> 16);
;     w[16 * 16] = (bf16_t)(q01 & 0xffffu); w[17 * 16] = (bf16_t)(q01 >> 16); w[18 * 16] = (bf16_t)(q23 & 0xffffu); w[19 * 16] = (bf16_t)(q23 >> 16);
;     asm volatile("s_waitcnt lgkmcnt(0)" ::: "memory");
;     const u32x4 row = *(const LAS u32x4*)(area + (lane >> 1) * 32 + (lane & 1) * 16);
;     asm volatile("" ::: "memory");
;     *(u32x4*)(dst_f0_t0 + (size_t)(lane >> 1) * RB + (lane & 1) * 8) = row;
; }
;     DI void operator()(const f32x4 (&acc)[2][2][4][2], const Unit& u, int wr, int wc, int fr, int fq) const {
;     ...
;                         if (colg >= C_RK) {
;                             v0 *= 0.08838834764831845f; v1 *= 0.08838834764831845f;
;                             st_tr16x32(spare + (wr * 4 + wc) * 1024, (bf16_t*)(ws + WS_KTR) + ((size_t)b * 640 + (colg - C_RK)) * RB + (r - fr), v0, v1, fr, fq, fq * 16 + fr);
;                         }
;                         st_bf16x4(P + (size_t)row * INP + c0, v0); st_bf16x4(P + (size_t)row * INP + c0 + 16, v1);
.Lip1_nr0:
	s_cmp_eq_u32 s32, 3
	s_cbranch_scc0 .Lip1_k0_plain
	s_mov_b32 s63, 0x3db504f3
	v_mul_f32_e32 v124, s63, v124
	v_mul_f32_e32 v125, s63, v125
	v_mul_f32_e32 v126, s63, v126
	v_mul_f32_e32 v127, s63, v127
	v_mul_f32_e32 v120, s63, v120
	v_mul_f32_e32 v121, s63, v121
	v_mul_f32_e32 v122, s63, v122
	v_mul_f32_e32 v123, s63, v123
	v_mul_f32_e32 v108, s63, v108
	v_mul_f32_e32 v109, s63, v109
	v_mul_f32_e32 v110, s63, v110
	v_mul_f32_e32 v111, s63, v111
	v_mul_f32_e32 v104, s63, v104
	v_mul_f32_e32 v105, s63, v105
	v_mul_f32_e32 v106, s63, v106
	v_mul_f32_e32 v107, s63, v107
	v_mul_f32_e32 v92, s63, v92
	v_mul_f32_e32 v93, s63, v93
	v_mul_f32_e32 v94, s63, v94
	v_mul_f32_e32 v95, s63, v95
	v_mul_f32_e32 v88, s63, v88
	v_mul_f32_e32 v89, s63, v89
	v_mul_f32_e32 v90, s63, v90
	v_mul_f32_e32 v91, s63, v91
	v_mul_f32_e32 v76, s63, v76
	v_mul_f32_e32 v77, s63, v77
	v_mul_f32_e32 v78, s63, v78
	v_mul_f32_e32 v79, s63, v79
	v_mul_f32_e32 v72, s63, v72
	v_mul_f32_e32 v73, s63, v73
	v_mul_f32_e32 v74, s63, v74
	v_mul_f32_e32 v75, s63, v75
	v_mul_f32_e32 v60, s63, v60
	v_mul_f32_e32 v61, s63, v61
	v_mul_f32_e32 v62, s63, v62
	v_mul_f32_e32 v63, s63, v63
	v_mul_f32_e32 v56, s63, v56
	v_mul_f32_e32 v57, s63, v57
	v_mul_f32_e32 v58, s63, v58
	v_mul_f32_e32 v59, s63, v59
	v_mul_f32_e32 v44, s63, v44
	v_mul_f32_e32 v45, s63, v45
	v_mul_f32_e32 v46, s63, v46
	v_mul_f32_e32 v47, s63, v47
	v_mul_f32_e32 v40, s63, v40
	v_mul_f32_e32 v41, s63, v41
	v_mul_f32_e32 v42, s63, v42
	v_mul_f32_e32 v43, s63, v43
	v_mul_f32_e32 v28, s63, v28
	v_mul_f32_e32 v29, s63, v29
	v_mul_f32_e32 v30, s63, v30
	v_mul_f32_e32 v31, s63, v31
	v_mul_f32_e32 v24, s63, v24
	v_mul_f32_e32 v25, s63, v25
	v_mul_f32_e32 v26, s63, v26
	v_mul_f32_e32 v27, s63, v27
	v_mul_f32_e32 v12, s63, v12
	v_mul_f32_e32 v13, s63, v13
	v_mul_f32_e32 v14, s63, v14
	v_mul_f32_e32 v15, s63, v15
	v_mul_f32_e32 v8, s63, v8
	v_mul_f32_e32 v9, s63, v9
	v_mul_f32_e32 v10, s63, v10
	v_mul_f32_e32 v11, s63, v11
	s_mul_i32 s54, s27, 640
	s_add_u32 s54, s54, s29
	s_sub_u32 s54, s54, 0xfc0
	s_mul_i32 s54, s54, 0x900
	s_lshl_b32 s63, s22, 8
	s_add_u32 s54, s54, s63
	s_lshl_b32 s54, s54, 1
	s_add_u32 s14, s50, 0x19860000
	s_addc_u32 s15, s51, 0
	s_add_u32 s14, s14, s54
	s_addc_u32 s15, s15, 0
	v_cvt_pk_bf16_f32 v236, v124, v125
	v_cvt_pk_bf16_f32 v237, v126, v127
	v_cvt_pk_bf16_f32 v238, v120, v121
	v_cvt_pk_bf16_f32 v239, v122, v123
	ds_write_b16 v167, v236 offset:0
	ds_write_b16_d16_hi v167, v236 offset:32
	ds_write_b16 v167, v237 offset:64
	ds_write_b16_d16_hi v167, v237 offset:96
	ds_write_b16 v167, v238 offset:512
	ds_write_b16_d16_hi v167, v238 offset:544
	ds_write_b16 v167, v239 offset:576
	ds_write_b16_d16_hi v167, v239 offset:608
	ds_read_b128 v[204:207], v168
	v_cvt_pk_bf16_f32 v240, v108, v109
	v_cvt_pk_bf16_f32 v241, v110, v111
	v_cvt_pk_bf16_f32 v242, v104, v105
	v_cvt_pk_bf16_f32 v243, v106, v107
	ds_write_b16 v167, v240 offset:0
	ds_write_b16_d16_hi v167, v240 offset:32
	ds_write_b16 v167, v241 offset:64
	ds_write_b16_d16_hi v167, v241 offset:96
	ds_write_b16 v167, v242 offset:512
	ds_write_b16_d16_hi v167, v242 offset:544
	ds_write_b16 v167, v243 offset:576
	ds_write_b16_d16_hi v167, v243 offset:608
	ds_read_b128 v[208:211], v168
	s_waitcnt lgkmcnt(9)
	global_store_dwordx4 v166, v[204:207], s[14:15] offset:0
	v_cvt_pk_bf16_f32 v236, v92, v93
	v_cvt_pk_bf16_f32 v237, v94, v95
	v_cvt_pk_bf16_f32 v238, v88, v89
	v_cvt_pk_bf16_f32 v239, v90, v91
	ds_write_b16 v167, v236 offset:0
	ds_write_b16_d16_hi v167, v236 offset:32
	ds_write_b16 v167, v237 offset:64
	ds_write_b16_d16_hi v167, v237 offset:96
	ds_write_b16 v167, v238 offset:512
	ds_write_b16_d16_hi v167, v238 offset:544
	ds_write_b16 v167, v239 offset:576
	ds_write_b16_d16_hi v167, v239 offset:608
	ds_read_b128 v[204:207], v168
	s_waitcnt lgkmcnt(9)
	global_store_dwordx4 v166, v[208:211], s[14:15] offset:32
	v_cvt_pk_bf16_f32 v240, v76, v77
	v_cvt_pk_bf16_f32 v241, v78, v79
	v_cvt_pk_bf16_f32 v242, v72, v73
	v_cvt_pk_bf16_f32 v243, v74, v75
	ds_write_b16 v167, v240 offset:0
	ds_write_b16_d16_hi v167, v240 offset:32
	ds_write_b16 v167, v241 offset:64
	ds_write_b16_d16_hi v167, v241 offset:96
	ds_write_b16 v167, v242 offset:512
	ds_write_b16_d16_hi v167, v242 offset:544
	ds_write_b16 v167, v243 offset:576
	ds_write_b16_d16_hi v167, v243 offset:608
	ds_read_b128 v[208:211], v168
	s_waitcnt lgkmcnt(9)
	global_store_dwordx4 v166, v[204:207], s[14:15] offset:64
	v_cvt_pk_bf16_f32 v236, v60, v61
	v_cvt_pk_bf16_f32 v237, v62, v63
	v_cvt_pk_bf16_f32 v238, v56, v57
	v_cvt_pk_bf16_f32 v239, v58, v59
	ds_write_b16 v167, v236 offset:0
	ds_write_b16_d16_hi v167, v236 offset:32
	ds_write_b16 v167, v237 offset:64
	ds_write_b16_d16_hi v167, v237 offset:96
	ds_write_b16 v167, v238 offset:512
	ds_write_b16_d16_hi v167, v238 offset:544
	ds_write_b16 v167, v239 offset:576
	ds_write_b16_d16_hi v167, v239 offset:608
	ds_read_b128 v[204:207], v168
	s_waitcnt lgkmcnt(9)
	global_store_dwordx4 v166, v[208:211], s[14:15] offset:96
	v_cvt_pk_bf16_f32 v240, v44, v45
	v_cvt_pk_bf16_f32 v241, v46, v47
	v_cvt_pk_bf16_f32 v242, v40, v41
	v_cvt_pk_bf16_f32 v243, v42, v43
	ds_write_b16 v167, v240 offset:0
	ds_write_b16_d16_hi v167, v240 offset:32
	ds_write_b16 v167, v241 offset:64
	ds_write_b16_d16_hi v167, v241 offset:96
	ds_write_b16 v167, v242 offset:512
	ds_write_b16_d16_hi v167, v242 offset:544
	ds_write_b16 v167, v243 offset:576
	ds_write_b16_d16_hi v167, v243 offset:608
	ds_read_b128 v[208:211], v168
	s_waitcnt lgkmcnt(9)
	global_store_dwordx4 v166, v[204:207], s[14:15] offset:256
	v_cvt_pk_bf16_f32 v236, v28, v29
	v_cvt_pk_bf16_f32 v237, v30, v31
	v_cvt_pk_bf16_f32 v238, v24, v25
	v_cvt_pk_bf16_f32 v239, v26, v27
	ds_write_b16 v167, v236 offset:0
	ds_write_b16_d16_hi v167, v236 offset:32
	ds_write_b16 v167, v237 offset:64
	ds_write_b16_d16_hi v167, v237 offset:96
	ds_write_b16 v167, v238 offset:512
	ds_write_b16_d16_hi v167, v238 offset:544
	ds_write_b16 v167, v239 offset:576
	ds_write_b16_d16_hi v167, v239 offset:608
	ds_read_b128 v[204:207], v168
	s_waitcnt lgkmcnt(9)
	global_store_dwordx4 v166, v[208:211], s[14:15] offset:288
	v_cvt_pk_bf16_f32 v240, v12, v13
	v_cvt_pk_bf16_f32 v241, v14, v15
	v_cvt_pk_bf16_f32 v242, v8, v9
	v_cvt_pk_bf16_f32 v243, v10, v11
	ds_write_b16 v167, v240 offset:0
	ds_write_b16_d16_hi v167, v240 offset:32
	ds_write_b16 v167, v241 offset:64
	ds_write_b16_d16_hi v167, v241 offset:96
	ds_write_b16 v167, v242 offset:512
	ds_write_b16_d16_hi v167, v242 offset:544
	ds_write_b16 v167, v243 offset:576
	ds_write_b16_d16_hi v167, v243 offset:608
	ds_read_b128 v[208:211], v168
	s_waitcnt lgkmcnt(9)
	global_store_dwordx4 v166, v[204:207], s[14:15] offset:320
	s_waitcnt lgkmcnt(0)
	global_store_dwordx4 v166, v[208:211], s[14:15] offset:352
	s_nop 1
; DI void st_tr16x32(LAS unsigned char* area, bf16_t* dst_f0_t0  , f32x4 v0, f32x4 v1, int fr, int fq, int lane) {
;     const unsigned p01 = cvt_pk_bf16(v0[0], v0[1]), p23 = cvt_pk_bf16(v0[2], v0[3]), q01 = cvt_pk_bf16(v1[0], v1[1]), q23 = cvt_pk_bf16(v1[2], v1[3]);
;     LAS bf16_t* w = (LAS bf16_t*)(area + (4 * fq) * 32 + fr * 2);
;     w[0 * 16] = (bf16_t)(p01 & 0xffffu); w[1 * 16] = (bf16_t)(p01 >> 16); w[2 * 16] = (bf16_t)(p23 & 0xffffu); w[3 * 16] = (bf16_t)(p23 >> 16);
;     w[16 * 16] = (bf16_t)(q01 & 0xffffu); w[17 * 16] = (bf16_t)(q01 >> 16); w[18 * 16] = (bf16_t)(q23 & 0xffffu); w[19 * 16] = (bf16_t)(q23 >> 16);
;     asm volatile("s_waitcnt lgkmcnt(0)" ::: "memory");
;     const u32x4 row = *(const LAS u32x4*)(area + (lane >> 1) * 32 + (lane & 1) * 16);
;     asm volatile("" ::: "memory");
;     *(u32x4*)(dst_f0_t0 + (size_t)(lane >> 1) * RB + (lane & 1) * 8) = row;
; }
;     DI void operator()(const f32x4 (&acc)[2][2][4][2], const Unit& u, int wr, int wc, int fr, int fq) const {
;     ...
;                     if (colg >= C_NAV && colg < C_CQ) {
;                         st_tr16x32(spare + (wr * 4 + wc) * 1024, (bf16_t*)(ws + WS_VTNA) + ((size_t)b * 768 + (colg - C_NAV)) * RB + (r - fr), v0, v1, fr, fq, fq * 16 + fr);
;                     } else if (colg >= C_RV && colg < C_RG) {
;                         st_tr16x32(spare + (wr * 4 + wc) * 1024, (bf16_t*)(ws + WS_VTR) + ((size_t)b * 640 + (colg - C_RV)) * RB + (r - fr), v0, v1, fr, fq, fq * 16 + fr);
;                     } else if (colg >= C_KPE && colg < C_RQ) {
;                         if (lat) rope4(v0, v1, (const float*)(ws + WS_TABM) + ((size_t)t * 32 + ((colg - C_KPE) >> 5) * 16 + 4 * fq) * 2);
;                         bf16_t* kp = (bf16_t*)(ws + WS_KPE) + (size_t)row * 64 + (c0 - C_KPE);
;                         st_bf16x4(kp, v0); st_bf16x4(kp + 16, v1);
;                     } else if (colg >= C_RQ && colg < C_RV) {
;                         if (lat) rope4(v0, v1, (const float*)(ws + WS_TABR) + ((size_t)t * 64 + (((colg - C_RQ) & 127) >> 5) * 16 + 4 * fq) * 2);
;                         if (colg >= C_RK) {
;                             v0 *= 0.08838834764831845f; v1 *= 0.08838834764831845f;
;                             st_tr16x32(spare + (wr * 4 + wc) * 1024, (bf16_t*)(ws + WS_KTR) + ((size_t)b * 640 + (colg - C_RK)) * RB + (r - fr), v0, v1, fr, fq, fq * 16 + fr);
.Lip1_k0_plain:
	s_mul_i32 s54, s10, 0x300000
	s_add_u32 s12, s50, 0x113a0000
	s_addc_u32 s13, s51, 0
	s_add_u32 s12, s12, s54
	s_addc_u32 s13, s13, 0
	s_lshl_b32 s54, s29, 1
	s_add_u32 s12, s12, s54
	s_addc_u32 s13, s13, 0
	v_cvt_pk_bf16_f32 v124, v124, v125
	v_cvt_pk_bf16_f32 v125, v126, v127
	global_store_dwordx2 v150, v[124:125], s[12:13] offset:0
	v_cvt_pk_bf16_f32 v120, v120, v121
	v_cvt_pk_bf16_f32 v121, v122, v123
	global_store_dwordx2 v150, v[120:121], s[12:13] offset:32
	v_cvt_pk_bf16_f32 v108, v108, v109
	v_cvt_pk_bf16_f32 v109, v110, v111
	global_store_dwordx2 v151, v[108:109], s[12:13] offset:0
	v_cvt_pk_bf16_f32 v104, v104, v105
	v_cvt_pk_bf16_f32 v105, v106, v107
	global_store_dwordx2 v151, v[104:105], s[12:13] offset:32
	v_cvt_pk_bf16_f32 v92, v92, v93
	v_cvt_pk_bf16_f32 v93, v94, v95
	global_store_dwordx2 v152, v[92:93], s[12:13] offset:0
	v_cvt_pk_bf16_f32 v88, v88, v89
	v_cvt_pk_bf16_f32 v89, v90, v91
	global_store_dwordx2 v152, v[88:89], s[12:13] offset:32
	v_cvt_pk_bf16_f32 v76, v76, v77
	v_cvt_pk_bf16_f32 v77, v78, v79
	global_store_dwordx2 v153, v[76:77], s[12:13] offset:0
	v_cvt_pk_bf16_f32 v72, v72, v73
	v_cvt_pk_bf16_f32 v73, v74, v75
	global_store_dwordx2 v153, v[72:73], s[12:13] offset:32
	v_cvt_pk_bf16_f32 v60, v60, v61
	v_cvt_pk_bf16_f32 v61, v62, v63
	global_store_dwordx2 v154, v[60:61], s[12:13] offset:0
	v_cvt_pk_bf16_f32 v56, v56, v57
	v_cvt_pk_bf16_f32 v57, v58, v59
	global_store_dwordx2 v154, v[56:57], s[12:13] offset:32
	v_cvt_pk_bf16_f32 v44, v44, v45
	v_cvt_pk_bf16_f32 v45, v46, v47
	global_store_dwordx2 v155, v[44:45], s[12:13] offset:0
	v_cvt_pk_bf16_f32 v40, v40, v41
	v_cvt_pk_bf16_f32 v41, v42, v43
	global_store_dwordx2 v155, v[40:41], s[12:13] offset:32
	v_cvt_pk_bf16_f32 v28, v28, v29
	v_cvt_pk_bf16_f32 v29, v30, v31
	global_store_dwordx2 v156, v[28:29], s[12:13] offset:0
	v_cvt_pk_bf16_f32 v24, v24, v25
	v_cvt_pk_bf16_f32 v25, v26, v27
	global_store_dwordx2 v156, v[24:25], s[12:13] offset:32
	v_cvt_pk_bf16_f32 v12, v12, v13
	v_cvt_pk_bf16_f32 v13, v14, v15
	global_store_dwordx2 v157, v[12:13], s[12:13] offset:0
	v_cvt_pk_bf16_f32 v8, v8, v9
	v_cvt_pk_bf16_f32 v9, v10, v11
	global_store_dwordx2 v157, v[8:9], s[12:13] offset:32
	s_branch .Lip1_k0_end
.Lip1_k0_nav:
	s_mul_i32 s54, s27, 768
	s_add_u32 s54, s54, s29
	s_sub_u32 s54, s54, 0x600
	s_mul_i32 s54, s54, 0x900
	s_lshl_b32 s63, s22, 8
	s_add_u32 s54, s54, s63
	s_lshl_b32 s54, s54, 1
	s_add_u32 s14, s50, 0x17fa0000
	s_addc_u32 s15, s51, 0
	s_add_u32 s14, s14, s54
	s_addc_u32 s15, s15, 0
	v_cvt_pk_bf16_f32 v236, v124, v125
	v_cvt_pk_bf16_f32 v237, v126, v127
	v_cvt_pk_bf16_f32 v238, v120, v121
	v_cvt_pk_bf16_f32 v239, v122, v123
	ds_write_b16 v167, v236 offset:0
	ds_write_b16_d16_hi v167, v236 offset:32
	ds_write_b16 v167, v237 offset:64
	ds_write_b16_d16_hi v167, v237 offset:96
	ds_write_b16 v167, v238 offset:512
	ds_write_b16_d16_hi v167, v238 offset:544
	ds_write_b16 v167, v239 offset:576
	ds_write_b16_d16_hi v167, v239 offset:608
	ds_read_b128 v[204:207], v168
	v_cvt_pk_bf16_f32 v240, v108, v109
	v_cvt_pk_bf16_f32 v241, v110, v111
	v_cvt_pk_bf16_f32 v242, v104, v105
	v_cvt_pk_bf16_f32 v243, v106, v107
	ds_write_b16 v167, v240 offset:0
	ds_write_b16_d16_hi v167, v240 offset:32
	ds_write_b16 v167, v241 offset:64
	ds_write_b16_d16_hi v167, v241 offset:96
	ds_write_b16 v167, v242 offset:512
	ds_write_b16_d16_hi v167, v242 offset:544
	ds_write_b16 v167, v243 offset:576
	ds_write_b16_d16_hi v167, v243 offset:608
	ds_read_b128 v[208:211], v168
	s_waitcnt lgkmcnt(9)
	global_store_dwordx4 v166, v[204:207], s[14:15] offset:0
	v_cvt_pk_bf16_f32 v236, v92, v93
	v_cvt_pk_bf16_f32 v237, v94, v95
	v_cvt_pk_bf16_f32 v238, v88, v89
	v_cvt_pk_bf16_f32 v239, v90, v91
	ds_write_b16 v167, v236 offset:0
	ds_write_b16_d16_hi v167, v236 offset:32
	ds_write_b16 v167, v237 offset:64
	ds_write_b16_d16_hi v167, v237 offset:96
	ds_write_b16 v167, v238 offset:512
	ds_write_b16_d16_hi v167, v238 offset:544
	ds_write_b16 v167, v239 offset:576
	ds_write_b16_d16_hi v167, v239 offset:608
	ds_read_b128 v[204:207], v168
	s_waitcnt lgkmcnt(9)
	global_store_dwordx4 v166, v[208:211], s[14:15] offset:32
	v_cvt_pk_bf16_f32 v240, v76, v77
	v_cvt_pk_bf16_f32 v241, v78, v79
	v_cvt_pk_bf16_f32 v242, v72, v73
	v_cvt_pk_bf16_f32 v243, v74, v75
	ds_write_b16 v167, v240 offset:0
	ds_write_b16_d16_hi v167, v240 offset:32
	ds_write_b16 v167, v241 offset:64
	ds_write_b16_d16_hi v167, v241 offset:96
	ds_write_b16 v167, v242 offset:512
	ds_write_b16_d16_hi v167, v242 offset:544
	ds_write_b16 v167, v243 offset:576
	ds_write_b16_d16_hi v167, v243 offset:608
	ds_read_b128 v[208:211], v168
	s_waitcnt lgkmcnt(9)
	global_store_dwordx4 v166, v[204:207], s[14:15] offset:64
	v_cvt_pk_bf16_f32 v236, v60, v61
	v_cvt_pk_bf16_f32 v237, v62, v63
	v_cvt_pk_bf16_f32 v238, v56, v57
	v_cvt_pk_bf16_f32 v239, v58, v59
	ds_write_b16 v167, v236 offset:0
	ds_write_b16_d16_hi v167, v236 offset:32
	ds_write_b16 v167, v237 offset:64
	ds_write_b16_d16_hi v167, v237 offset:96
	ds_write_b16 v167, v238 offset:512
	ds_write_b16_d16_hi v167, v238 offset:544
	ds_write_b16 v167, v239 offset:576
	ds_write_b16_d16_hi v167, v239 offset:608
	ds_read_b128 v[204:207], v168
	s_waitcnt lgkmcnt(9)
	global_store_dwordx4 v166, v[208:211], s[14:15] offset:96
	v_cvt_pk_bf16_f32 v240, v44, v45
	v_cvt_pk_bf16_f32 v241, v46, v47
	v_cvt_pk_bf16_f32 v242, v40, v41
	v_cvt_pk_bf16_f32 v243, v42, v43
	ds_write_b16 v167, v240 offset:0
	ds_write_b16_d16_hi v167, v240 offset:32
	ds_write_b16 v167, v241 offset:64
	ds_write_b16_d16_hi v167, v241 offset:96
	ds_write_b16 v167, v242 offset:512
	ds_write_b16_d16_hi v167, v242 offset:544
	ds_write_b16 v167, v243 offset:576
	ds_write_b16_d16_hi v167, v243 offset:608
	ds_read_b128 v[208:211], v168
	s_waitcnt lgkmcnt(9)
	global_store_dwordx4 v166, v[204:207], s[14:15] offset:256
	v_cvt_pk_bf16_f32 v236, v28, v29
	v_cvt_pk_bf16_f32 v237, v30, v31
	v_cvt_pk_bf16_f32 v238, v24, v25
	v_cvt_pk_bf16_f32 v239, v26, v27
	ds_write_b16 v167, v236 offset:0
	ds_write_b16_d16_hi v167, v236 offset:32
	ds_write_b16 v167, v237 offset:64
	ds_write_b16_d16_hi v167, v237 offset:96
	ds_write_b16 v167, v238 offset:512
	ds_write_b16_d16_hi v167, v238 offset:544
	ds_write_b16 v167, v239 offset:576
	ds_write_b16_d16_hi v167, v239 offset:608
	ds_read_b128 v[204:207], v168
	s_waitcnt lgkmcnt(9)
	global_store_dwordx4 v166, v[208:211], s[14:15] offset:288
	v_cvt_pk_bf16_f32 v240, v12, v13
	v_cvt_pk_bf16_f32 v241, v14, v15
	v_cvt_pk_bf16_f32 v242, v8, v9
	v_cvt_pk_bf16_f32 v243, v10, v11
	ds_write_b16 v167, v240 offset:0
	ds_write_b16_d16_hi v167, v240 offset:32
	ds_write_b16 v167, v241 offset:64
	ds_write_b16_d16_hi v167, v241 offset:96
	ds_write_b16 v167, v242 offset:512
	ds_write_b16_d16_hi v167, v242 offset:544
	ds_write_b16 v167, v243 offset:576
	ds_write_b16_d16_hi v167, v243 offset:608
	ds_read_b128 v[208:211], v168
	s_waitcnt lgkmcnt(9)
	global_store_dwordx4 v166, v[204:207], s[14:15] offset:320
	s_waitcnt lgkmcnt(0)
	global_store_dwordx4 v166, v[208:211], s[14:15] offset:352
	s_nop 1
	s_branch .Lip1_k0_end
; #define LAS __attribute__((address_space(3)))
; DI unsigned cvt_pk_bf16(float lo, float hi) { unsigned r; asm volatile("v_cvt_pk_bf16_f32 %0, %1, %2" : "=v"(r) : "v"(lo), "v"(hi)); return r; }
; DI void st_tr16x32(LAS unsigned char* area, bf16_t* dst_f0_t0  , f32x4 v0, f32x4 v1, int fr, int fq, int lane) {
;     const unsigned p01 = cvt_pk_bf16(v0[0], v0[1]), p23 = cvt_pk_bf16(v0[2], v0[3]), q01 = cvt_pk_bf16(v1[0], v1[1]), q23 = cvt_pk_bf16(v1[2], v1[3]);
;     LAS bf16_t* w = (LAS bf16_t*)(area + (4 * fq) * 32 + fr * 2);
;     w[0 * 16] = (bf16_t)(p01 & 0xffffu); w[1 * 16] = (bf16_t)(p01 >> 16); w[2 * 16] = (bf16_t)(p23 & 0xffffu); w[3 * 16] = (bf16_t)(p23 >> 16);
;     w[16 * 16] = (bf16_t)(q01 & 0xffffu); w[17 * 16] = (bf16_t)(q01 >> 16); w[18 * 16] = (bf16_t)(q23 & 0xffffu); w[19 * 16] = (bf16_t)(q23 >> 16);
;     asm volatile("s_waitcnt lgkmcnt(0)" ::: "memory");
;     const u32x4 row = *(const LAS u32x4*)(area + (lane >> 1) * 32 + (lane & 1) * 16);
;     asm volatile("" ::: "memory");
;     *(u32x4*)(dst_f0_t0 + (size_t)(lane >> 1) * RB + (lane & 1) * 8) = row;
; }
;     DI void operator()(const f32x4 (&acc)[2][2][4][2], const Unit& u, int wr, int wc, int fr, int fq) const {
;     ...
;                     } else if (colg >= C_RV && colg < C_RG) {
;                         st_tr16x32(spare + (wr * 4 + wc) * 1024, (bf16_t*)(ws + WS_VTR) + ((size_t)b * 640 + (colg - C_RV)) * RB + (r - fr), v0, v1, fr, fq, fq * 16 + fr);
.Lip1_k0_rv:
	s_mul_i32 s54, s27, 640
	s_add_u32 s54, s54, s29
	s_sub_u32 s54, s54, 0x1240
	s_mul_i32 s54, s54, 0x900
	s_lshl_b32 s63, s22, 8
	s_add_u32 s54, s54, s63
	s_lshl_b32 s54, s54, 1
	s_add_u32 s14, s50, 0x18d20000
	s_addc_u32 s15, s51, 0
	s_add_u32 s14, s14, s54
	s_addc_u32 s15, s15, 0
	v_cvt_pk_bf16_f32 v236, v124, v125
	v_cvt_pk_bf16_f32 v237, v126, v127
	v_cvt_pk_bf16_f32 v238, v120, v121
	v_cvt_pk_bf16_f32 v239, v122, v123
	ds_write_b16 v167, v236 offset:0
	ds_write_b16_d16_hi v167, v236 offset:32
	ds_write_b16 v167, v237 offset:64
	ds_write_b16_d16_hi v167, v237 offset:96
	ds_write_b16 v167, v238 offset:512
	ds_write_b16_d16_hi v167, v238 offset:544
	ds_write_b16 v167, v239 offset:576
	ds_write_b16_d16_hi v167, v239 offset:608
	ds_read_b128 v[204:207], v168
	v_cvt_pk_bf16_f32 v240, v108, v109
	v_cvt_pk_bf16_f32 v241, v110, v111
	v_cvt_pk_bf16_f32 v242, v104, v105
	v_cvt_pk_bf16_f32 v243, v106, v107
	ds_write_b16 v167, v240 offset:0
	ds_write_b16_d16_hi v167, v240 offset:32
	ds_write_b16 v167, v241 offset:64
	ds_write_b16_d16_hi v167, v241 offset:96
	ds_write_b16 v167, v242 offset:512
	ds_write_b16_d16_hi v167, v242 offset:544
	ds_write_b16 v167, v243 offset:576
	ds_write_b16_d16_hi v167, v243 offset:608
	ds_read_b128 v[208:211], v168
	s_waitcnt lgkmcnt(9)
	global_store_dwordx4 v166, v[204:207], s[14:15] offset:0
	v_cvt_pk_bf16_f32 v236, v92, v93
	v_cvt_pk_bf16_f32 v237, v94, v95
	v_cvt_pk_bf16_f32 v238, v88, v89
	v_cvt_pk_bf16_f32 v239, v90, v91
	ds_write_b16 v167, v236 offset:0
	ds_write_b16_d16_hi v167, v236 offset:32
	ds_write_b16 v167, v237 offset:64
	ds_write_b16_d16_hi v167, v237 offset:96
	ds_write_b16 v167, v238 offset:512
	ds_write_b16_d16_hi v167, v238 offset:544
	ds_write_b16 v167, v239 offset:576
	ds_write_b16_d16_hi v167, v239 offset:608
	ds_read_b128 v[204:207], v168
	s_waitcnt lgkmcnt(9)
	global_store_dwordx4 v166, v[208:211], s[14:15] offset:32
	v_cvt_pk_bf16_f32 v240, v76, v77
	v_cvt_pk_bf16_f32 v241, v78, v79
	v_cvt_pk_bf16_f32 v242, v72, v73
	v_cvt_pk_bf16_f32 v243, v74, v75
	ds_write_b16 v167, v240 offset:0
	ds_write_b16_d16_hi v167, v240 offset:32
	ds_write_b16 v167, v241 offset:64
	ds_write_b16_d16_hi v167, v241 offset:96
	ds_write_b16 v167, v242 offset:512
	ds_write_b16_d16_hi v167, v242 offset:544
	ds_write_b16 v167, v243 offset:576
	ds_write_b16_d16_hi v167, v243 offset:608
	ds_read_b128 v[208:211], v168
	s_waitcnt lgkmcnt(9)
	global_store_dwordx4 v166, v[204:207], s[14:15] offset:64
	v_cvt_pk_bf16_f32 v236, v60, v61
	v_cvt_pk_bf16_f32 v237, v62, v63
	v_cvt_pk_bf16_f32 v238, v56, v57
	v_cvt_pk_bf16_f32 v239, v58, v59
	ds_write_b16 v167, v236 offset:0
	ds_write_b16_d16_hi v167, v236 offset:32
	ds_write_b16 v167, v237 offset:64
	ds_write_b16_d16_hi v167, v237 offset:96
	ds_write_b16 v167, v238 offset:512
	ds_write_b16_d16_hi v167, v238 offset:544
	ds_write_b16 v167, v239 offset:576
	ds_write_b16_d16_hi v167, v239 offset:608
	ds_read_b128 v[204:207], v168
	s_waitcnt lgkmcnt(9)
	global_store_dwordx4 v166, v[208:211], s[14:15] offset:96
	v_cvt_pk_bf16_f32 v240, v44, v45
	v_cvt_pk_bf16_f32 v241, v46, v47
	v_cvt_pk_bf16_f32 v242, v40, v41
	v_cvt_pk_bf16_f32 v243, v42, v43
	ds_write_b16 v167, v240 offset:0
	ds_write_b16_d16_hi v167, v240 offset:32
	ds_write_b16 v167, v241 offset:64
	ds_write_b16_d16_hi v167, v241 offset:96
	ds_write_b16 v167, v242 offset:512
	ds_write_b16_d16_hi v167, v242 offset:544
	ds_write_b16 v167, v243 offset:576
	ds_write_b16_d16_hi v167, v243 offset:608
	ds_read_b128 v[208:211], v168
	s_waitcnt lgkmcnt(9)
	global_store_dwordx4 v166, v[204:207], s[14:15] offset:256
	v_cvt_pk_bf16_f32 v236, v28, v29
	v_cvt_pk_bf16_f32 v237, v30, v31
	v_cvt_pk_bf16_f32 v238, v24, v25
	v_cvt_pk_bf16_f32 v239, v26, v27
	ds_write_b16 v167, v236 offset:0
	ds_write_b16_d16_hi v167, v236 offset:32
	ds_write_b16 v167, v237 offset:64
	ds_write_b16_d16_hi v167, v237 offset:96
	ds_write_b16 v167, v238 offset:512
	ds_write_b16_d16_hi v167, v238 offset:544
	ds_write_b16 v167, v239 offset:576
	ds_write_b16_d16_hi v167, v239 offset:608
	ds_read_b128 v[204:207], v168
	s_waitcnt lgkmcnt(9)
	global_store_dwordx4 v166, v[208:211], s[14:15] offset:288
	v_cvt_pk_bf16_f32 v240, v12, v13
	v_cvt_pk_bf16_f32 v241, v14, v15
	v_cvt_pk_bf16_f32 v242, v8, v9
	v_cvt_pk_bf16_f32 v243, v10, v11
	ds_write_b16 v167, v240 offset:0
	ds_write_b16_d16_hi v167, v240 offset:32
	ds_write_b16 v167, v241 offset:64
	ds_write_b16_d16_hi v167, v241 offset:96
	ds_write_b16 v167, v242 offset:512
	ds_write_b16_d16_hi v167, v242 offset:544
	ds_write_b16 v167, v243 offset:576
	ds_write_b16_d16_hi v167, v243 offset:608
	ds_read_b128 v[208:211], v168
	s_waitcnt lgkmcnt(9)
	global_store_dwordx4 v166, v[204:207], s[14:15] offset:320
	s_waitcnt lgkmcnt(0)
	global_store_dwordx4 v166, v[208:211], s[14:15] offset:352
	s_nop 1
	s_branch .Lip1_k0_end
; DI void st_bf16x4(bf16_t* p, f32x4 v) { u32x2 w; w.x = cvt_pk_bf16(v[0], v[1]); w.y = cvt_pk_bf16(v[2], v[3]); *(u32x2*)p = w; }
;     DI void operator()(const f32x4 (&acc)[2][2][4][2], const Unit& u, int wr, int wc, int fr, int fq) const {
;     ...
;                         if (colg >= C_CQ && colg < C_KPE) {
;                             float ss = v0[0] * v0[0] + v0[1] * v0[1] + v0[2] * v0[2] + v0[3] * v0[3] + v1[0] * v1[0] + v1[1] * v1[1] + v1[2] * v1[2] + v1[3] * v1[3];
;                             ss += __shfl_xor(ss, 16); ss += __shfl_xor(ss, 32);
;                             if (fq == 0) ((float*)(ws + WS_SSQ))[(size_t)row * 32 + ((colg - C_CQ) >> 5)] = ss;
;                         }
;                         st_bf16x4(P + (size_t)row * INP + c0, v0); st_bf16x4(P + (size_t)row * INP + c0 + 16, v1);
.Lip1_k0_ssq:
	v_xor_b32_e32 v198, 16, v197
	v_lshlrev_b32_e32 v198, 2, v198
	v_xor_b32_e32 v199, 32, v197
	v_lshlrev_b32_e32 v199, 2, v199
	v_mul_f32_e32 v158, v124, v124
	v_fmac_f32_e32 v158, v125, v125
	v_fmac_f32_e32 v158, v126, v126
	v_fmac_f32_e32 v158, v127, v127
	v_fmac_f32_e32 v158, v120, v120
	v_fmac_f32_e32 v158, v121, v121
	v_fmac_f32_e32 v158, v122, v122
	v_fmac_f32_e32 v158, v123, v123
	v_mul_f32_e32 v159, v108, v108
	v_fmac_f32_e32 v159, v109, v109
	v_fmac_f32_e32 v159, v110, v110
	v_fmac_f32_e32 v159, v111, v111
	v_fmac_f32_e32 v159, v104, v104
	v_fmac_f32_e32 v159, v105, v105
	v_fmac_f32_e32 v159, v106, v106
	v_fmac_f32_e32 v159, v107, v107
	v_mul_f32_e32 v160, v92, v92
	v_fmac_f32_e32 v160, v93, v93
	v_fmac_f32_e32 v160, v94, v94
	v_fmac_f32_e32 v160, v95, v95
	v_fmac_f32_e32 v160, v88, v88
	v_fmac_f32_e32 v160, v89, v89
	v_fmac_f32_e32 v160, v90, v90
	v_fmac_f32_e32 v160, v91, v91
	v_mul_f32_e32 v161, v76, v76
	v_fmac_f32_e32 v161, v77, v77
	v_fmac_f32_e32 v161, v78, v78
	v_fmac_f32_e32 v161, v79, v79
	v_fmac_f32_e32 v161, v72, v72
	v_fmac_f32_e32 v161, v73, v73
	v_fmac_f32_e32 v161, v74, v74
	v_fmac_f32_e32 v161, v75, v75
	v_mul_f32_e32 v162, v60, v60
	v_fmac_f32_e32 v162, v61, v61
	v_fmac_f32_e32 v162, v62, v62
	v_fmac_f32_e32 v162, v63, v63
	v_fmac_f32_e32 v162, v56, v56
	v_fmac_f32_e32 v162, v57, v57
	v_fmac_f32_e32 v162, v58, v58
	v_fmac_f32_e32 v162, v59, v59
	v_mul_f32_e32 v163, v44, v44
	v_fmac_f32_e32 v163, v45, v45
	v_fmac_f32_e32 v163, v46, v46
	v_fmac_f32_e32 v163, v47, v47
	v_fmac_f32_e32 v163, v40, v40
	v_fmac_f32_e32 v163, v41, v41
	v_fmac_f32_e32 v163, v42, v42
	v_fmac_f32_e32 v163, v43, v43
	v_mul_f32_e32 v164, v28, v28
	v_fmac_f32_e32 v164, v29, v29
	v_fmac_f32_e32 v164, v30, v30
	v_fmac_f32_e32 v164, v31, v31
	v_fmac_f32_e32 v164, v24, v24
	v_fmac_f32_e32 v164, v25, v25
	v_fmac_f32_e32 v164, v26, v26
	v_fmac_f32_e32 v164, v27, v27
	v_mul_f32_e32 v165, v12, v12
	v_fmac_f32_e32 v165, v13, v13
	v_fmac_f32_e32 v165, v14, v14
	v_fmac_f32_e32 v165, v15, v15
	v_fmac_f32_e32 v165, v8, v8
	v_fmac_f32_e32 v165, v9, v9
	v_fmac_f32_e32 v165, v10, v10
	v_fmac_f32_e32 v165, v11, v11
	ds_bpermute_b32 v204, v198, v158
	ds_bpermute_b32 v205, v198, v159
	ds_bpermute_b32 v206, v198, v160
	ds_bpermute_b32 v207, v198, v161
	ds_bpermute_b32 v208, v198, v162
	ds_bpermute_b32 v209, v198, v163
	ds_bpermute_b32 v210, v198, v164
	ds_bpermute_b32 v211, v198, v165
	s_waitcnt lgkmcnt(0)
	v_add_f32_e32 v158, v158, v204
	v_add_f32_e32 v159, v159, v205
	v_add_f32_e32 v160, v160, v206
	v_add_f32_e32 v161, v161, v207
	v_add_f32_e32 v162, v162, v208
	v_add_f32_e32 v163, v163, v209
	v_add_f32_e32 v164, v164, v210
	v_add_f32_e32 v165, v165, v211
	ds_bpermute_b32 v204, v199, v158
	ds_bpermute_b32 v205, v199, v159
	ds_bpermute_b32 v206, v199, v160
	ds_bpermute_b32 v207, v199, v161
	ds_bpermute_b32 v208, v199, v162
	ds_bpermute_b32 v209, v199, v163
	ds_bpermute_b32 v210, v199, v164
	ds_bpermute_b32 v211, v199, v165
	s_waitcnt lgkmcnt(0)
	v_add_f32_e32 v158, v158, v204
	v_add_f32_e32 v159, v159, v205
	v_add_f32_e32 v160, v160, v206
	v_add_f32_e32 v161, v161, v207
	v_add_f32_e32 v162, v162, v208
	v_add_f32_e32 v163, v163, v209
	v_add_f32_e32 v164, v164, v210
	v_add_f32_e32 v165, v165, v211
	s_lshl_b32 s54, s10, 15
	s_add_u32 s14, s50, 0x200000
	s_addc_u32 s15, s51, 0
	s_add_u32 s14, s14, s54
	s_addc_u32 s15, s15, 0
	s_sub_u32 s54, s29, 0x900
	s_lshr_b32 s54, s54, 5
	s_lshl_b32 s54, s54, 2
	s_add_u32 s14, s14, s54
	s_addc_u32 s15, s15, 0
	v_lshlrev_b32_e32 v212, 7, v195
	v_add_u32_e32 v213, 0x800, v212
	v_add_u32_e32 v214, 0x1000, v212
	v_add_u32_e32 v215, 0x1800, v212
	v_add_u32_e32 v216, 0x4000, v212
	v_add_u32_e32 v217, 0x4800, v212
	v_add_u32_e32 v218, 0x5000, v212
	v_add_u32_e32 v219, 0x5800, v212
	v_cmp_eq_u32_e64 s[12:13], 0, v196
	s_mov_b64 exec, s[12:13]
	global_store_dword v212, v158, s[14:15]
	global_store_dword v213, v159, s[14:15]
	global_store_dword v214, v160, s[14:15]
	global_store_dword v215, v161, s[14:15]
	global_store_dword v216, v162, s[14:15]
	global_store_dword v217, v163, s[14:15]
	global_store_dword v218, v164, s[14:15]
	global_store_dword v219, v165, s[14:15]
	s_mov_b64 exec, -1
	s_branch .Lip1_k0_plain
.Lip1_k0_end:
	s_add_u32 s29, s29, 0x80
	s_cmp_eq_u32 s43, 0
	s_cbranch_scc1 .Lip1_k1_end
	s_cmp_eq_u32 s43, 1
	s_cbranch_scc1 .Lip1_k1_plain
	s_cmp_eq_u32 s43, 4
	s_cbranch_scc1 .Lip1_k1_nav
	s_cmp_eq_u32 s43, 5
	s_cbranch_scc1 .Lip1_k1_rv
	s_cmp_eq_u32 s43, 6
	s_cbranch_scc1 .Lip1_k1_ssq
	s_cmp_eq_u32 s22, 0
	s_cbranch_scc1 .Lip1_nr1
; DI void rope4(f32x4& v0, f32x4& v1, const float* tab  ) {
;     const f32x4 t0 = *(const f32x4*)tab, t1 = *(const f32x4*)(tab + 4);
;     const float c[4] = {t0[0], t0[2], t1[0], t1[2]}, s[4] = {t0[1], t0[3], t1[1], t1[3]};
; #pragma unroll
;     for (int j = 0; j < 4; ++j) { const float a = v0[j], b = v1[j]; v0[j] = a * c[j] - b * s[j]; v1[j] = b * c[j] + a * s[j]; }
; }
;     DI void operator()(const f32x4 (&acc)[2][2][4][2], const Unit& u, int wr, int wc, int fr, int fq) const {
;     ...
;                     } else if (colg >= C_RQ && colg < C_RV) {
;                         if (lat) rope4(v0, v1, (const float*)(ws + WS_TABR) + ((size_t)t * 64 + (((colg - C_RQ) & 127) >> 5) * 16 + 4 * fq) * 2);
	s_sub_u32 s69, s29, 0xd40
	s_and_b32 s69, s69, 0x7f
	s_lshr_b32 s69, s69, 5
	s_lshl_b32 s69, s69, 7
	s_sub_u32 s54, s22, 1
	s_lshl_b32 s54, s54, 17
	s_add_u32 s54, s54, s69
	v_lshlrev_b32_e32 v169, 5, v196
	v_lshl_add_u32 v158, v195, 9, v169
	v_add_u32_e32 v158, s54, v158
	v_add_u32_e32 v159, 0x2000, v158
	v_add_u32_e32 v160, 0x4000, v158
	v_add_u32_e32 v161, 0x6000, v158
	v_add_u32_e32 v162, 0x10000, v158
	v_add_u32_e32 v163, 0x12000, v158
	v_add_u32_e32 v164, 0x14000, v158
	v_add_u32_e32 v165, 0x16000, v158
	s_add_u32 s14, s50, 0x100000
	s_addc_u32 s15, s51, 0
	global_load_dwordx4 v[204:207], v158, s[14:15]
	global_load_dwordx4 v[208:211], v158, s[14:15] offset:16
	global_load_dwordx4 v[212:215], v159, s[14:15]
	global_load_dwordx4 v[216:219], v159, s[14:15] offset:16
	global_load_dwordx4 v[220:223], v160, s[14:15]
	global_load_dwordx4 v[224:227], v160, s[14:15] offset:16
	global_load_dwordx4 v[228:231], v161, s[14:15]
	global_load_dwordx4 v[232:235], v161, s[14:15] offset:16
	global_load_dwordx4 v[236:239], v162, s[14:15]
	global_load_dwordx4 v[240:243], v162, s[14:15] offset:16
	global_load_dwordx4 v[244:247], v163, s[14:15]
	global_load_dwordx4 v[248:251], v163, s[14:15] offset:16
	global_load_dwordx4 v[178:181], v164, s[14:15]
	global_load_dwordx4 v[182:185], v164, s[14:15] offset:16
	global_load_dwordx4 v[186:189], v165, s[14:15]
	global_load_dwordx4 v[190:193], v165, s[14:15] offset:16
	s_waitcnt vmcnt(0)
	v_mul_f32_e32 v169, v116, v205
	v_mul_f32_e32 v116, v116, v204
	v_fma_f32 v116, -v112, v205, v116
	v_fma_f32 v112, v112, v204, v169
	v_mul_f32_e32 v169, v117, v207
	v_mul_f32_e32 v117, v117, v206
	v_fma_f32 v117, -v113, v207, v117
	v_fma_f32 v113, v113, v206, v169
	v_mul_f32_e32 v169, v118, v209
	v_mul_f32_e32 v118, v118, v208
	v_fma_f32 v118, -v114, v209, v118
	v_fma_f32 v114, v114, v208, v169
	v_mul_f32_e32 v169, v119, v211
	v_mul_f32_e32 v119, v119, v210
	v_fma_f32 v119, -v115, v211, v119
	v_fma_f32 v115, v115, v210, v169
	v_mul_f32_e32 v169, v100, v213
	v_mul_f32_e32 v100, v100, v212
	v_fma_f32 v100, -v96, v213, v100
	v_fma_f32 v96, v96, v212, v169
	v_mul_f32_e32 v169, v101, v215
	v_mul_f32_e32 v101, v101, v214
	v_fma_f32 v101, -v97, v215, v101
	v_fma_f32 v97, v97, v214, v169
	v_mul_f32_e32 v169, v102, v217
	v_mul_f32_e32 v102, v102, v216
	v_fma_f32 v102, -v98, v217, v102
	v_fma_f32 v98, v98, v216, v169
	v_mul_f32_e32 v169, v103, v219
	v_mul_f32_e32 v103, v103, v218
	v_fma_f32 v103, -v99, v219, v103
	v_fma_f32 v99, v99, v218, v169
	v_mul_f32_e32 v169, v84, v221
	v_mul_f32_e32 v84, v84, v220
	v_fma_f32 v84, -v80, v221, v84
	v_fma_f32 v80, v80, v220, v169
	v_mul_f32_e32 v169, v85, v223
	v_mul_f32_e32 v85, v85, v222
	v_fma_f32 v85, -v81, v223, v85
	v_fma_f32 v81, v81, v222, v169
	v_mul_f32_e32 v169, v86, v225
	v_mul_f32_e32 v86, v86, v224
	v_fma_f32 v86, -v82, v225, v86
	v_fma_f32 v82, v82, v224, v169
	v_mul_f32_e32 v169, v87, v227
	v_mul_f32_e32 v87, v87, v226
	v_fma_f32 v87, -v83, v227, v87
	v_fma_f32 v83, v83, v226, v169
	v_mul_f32_e32 v169, v68, v229
	v_mul_f32_e32 v68, v68, v228
	v_fma_f32 v68, -v64, v229, v68
	v_fma_f32 v64, v64, v228, v169
	v_mul_f32_e32 v169, v69, v231
	v_mul_f32_e32 v69, v69, v230
	v_fma_f32 v69, -v65, v231, v69
	v_fma_f32 v65, v65, v230, v169
	v_mul_f32_e32 v169, v70, v233
	v_mul_f32_e32 v70, v70, v232
	v_fma_f32 v70, -v66, v233, v70
	v_fma_f32 v66, v66, v232, v169
	v_mul_f32_e32 v169, v71, v235
	v_mul_f32_e32 v71, v71, v234
	v_fma_f32 v71, -v67, v235, v71
	v_fma_f32 v67, v67, v234, v169
	v_mul_f32_e32 v169, v52, v237
	v_mul_f32_e32 v52, v52, v236
	v_fma_f32 v52, -v48, v237, v52
	v_fma_f32 v48, v48, v236, v169
	v_mul_f32_e32 v169, v53, v239
	v_mul_f32_e32 v53, v53, v238
	v_fma_f32 v53, -v49, v239, v53
	v_fma_f32 v49, v49, v238, v169
	v_mul_f32_e32 v169, v54, v241
	v_mul_f32_e32 v54, v54, v240
	v_fma_f32 v54, -v50, v241, v54
	v_fma_f32 v50, v50, v240, v169
	v_mul_f32_e32 v169, v55, v243
	v_mul_f32_e32 v55, v55, v242
	v_fma_f32 v55, -v51, v243, v55
	v_fma_f32 v51, v51, v242, v169
	v_mul_f32_e32 v169, v36, v245
	v_mul_f32_e32 v36, v36, v244
	v_fma_f32 v36, -v32, v245, v36
	v_fma_f32 v32, v32, v244, v169
	v_mul_f32_e32 v169, v37, v247
	v_mul_f32_e32 v37, v37, v246
	v_fma_f32 v37, -v33, v247, v37
	v_fma_f32 v33, v33, v246, v169
	v_mul_f32_e32 v169, v38, v249
	v_mul_f32_e32 v38, v38, v248
	v_fma_f32 v38, -v34, v249, v38
	v_fma_f32 v34, v34, v248, v169
	v_mul_f32_e32 v169, v39, v251
	v_mul_f32_e32 v39, v39, v250
	v_fma_f32 v39, -v35, v251, v39
	v_fma_f32 v35, v35, v250, v169
	v_mul_f32_e32 v169, v20, v179
	v_mul_f32_e32 v20, v20, v178
	v_fma_f32 v20, -v16, v179, v20
	v_fma_f32 v16, v16, v178, v169
	v_mul_f32_e32 v169, v21, v181
	v_mul_f32_e32 v21, v21, v180
	v_fma_f32 v21, -v17, v181, v21
	v_fma_f32 v17, v17, v180, v169
	v_mul_f32_e32 v169, v22, v183
	v_mul_f32_e32 v22, v22, v182
	v_fma_f32 v22, -v18, v183, v22
	v_fma_f32 v18, v18, v182, v169
	v_mul_f32_e32 v169, v23, v185
	v_mul_f32_e32 v23, v23, v184
	v_fma_f32 v23, -v19, v185, v23
	v_fma_f32 v19, v19, v184, v169
	v_mul_f32_e32 v169, v4, v187
	v_mul_f32_e32 v4, v4, v186
	v_fma_f32 v4, -v0, v187, v4
	v_fma_f32 v0, v0, v186, v169
	v_mul_f32_e32 v169, v5, v189
	v_mul_f32_e32 v5, v5, v188
	v_fma_f32 v5, -v1, v189, v5
	v_fma_f32 v1, v1, v188, v169
	v_mul_f32_e32 v169, v6, v191
	v_mul_f32_e32 v6, v6, v190
	v_fma_f32 v6, -v2, v191, v6
	v_fma_f32 v2, v2, v190, v169
	v_mul_f32_e32 v169, v7, v193
	v_mul_f32_e32 v7, v7, v192
	v_fma_f32 v7, -v3, v193, v7
	v_fma_f32 v3, v3, v192, v169
; #define LAS __attribute__((address_space(3)))
; DI unsigned cvt_pk_bf16(float lo, float hi) { unsigned r; asm volatile("v_cvt_pk_bf16_f32 %0, %1, %2" : "=v"(r) : "v"(lo), "v"(hi)); return r; }
; DI void st_bf16x4(bf16_t* p, f32x4 v) { u32x2 w; w.x = cvt_pk_bf16(v[0], v[1]); w.y = cvt_pk_bf16(v[2], v[3]); *(u32x2*)p = w; }
; DI void st_tr16x32(LAS unsigned char* area, bf16_t* dst_f0_t0  , f32x4 v0, f32x4 v1, int fr, int fq, int lane) {
;     const unsigned p01 = cvt_pk_bf16(v0[0], v0[1]), p23 = cvt_pk_bf16(v0[2], v0[3]), q01 = cvt_pk_bf16(v1[0], v1[1]), q23 = cvt_pk_bf16(v1[2], v1[3]);
;     LAS bf16_t* w = (LAS bf16_t*)(area + (4 * fq) * 32 + fr * 2);
;     w[0 * 16] = (bf16_t)(p01 & 0xffffu); w[1 * 16] = (bf16_t)(p01 >> 16); w[2 * 16] = (bf16_t)(p23 & 0xffffu); w[3 * 16] = (bf16_t)(p23 >> 16);
;     w[16 * 16] = (bf16_t)(q01 & 0xffffu); w[17 * 16] = (bf16_t)(q01 >> 16); w[18 * 16] = (bf16_t)(q23 & 0xffffu); w[19 * 16] = (bf16_t)(q23 >> 16);
;     asm volatile("s_waitcnt lgkmcnt(0)" ::: "memory");
;     const u32x4 row = *(const LAS u32x4*)(area + (lane >> 1) * 32 + (lane & 1) * 16);
;     asm volatile("" ::: "memory");
;     *(u32x4*)(dst_f0_t0 + (size_t)(lane >> 1) * RB + (lane & 1) * 8) = row;
; }
;     DI void operator()(const f32x4 (&acc)[2][2][4][2], const Unit& u, int wr, int wc, int fr, int fq) const {
;     ...
;                     } else if (colg >= C_RQ && colg < C_RV) {
;                         if (lat) rope4(v0, v1, (const float*)(ws + WS_TABR) + ((size_t)t * 64 + (((colg - C_RQ) & 127) >> 5) * 16 + 4 * fq) * 2);
;                         if (colg >= C_RK) {
;                             v0 *= 0.08838834764831845f; v1 *= 0.08838834764831845f;
;                             st_tr16x32(spare + (wr * 4 + wc) * 1024, (bf16_t*)(ws + WS_KTR) + ((size_t)b * 640 + (colg - C_RK)) * RB + (r - fr), v0, v1, fr, fq, fq * 16 + fr);
;                         }
;                         st_bf16x4(P + (size_t)row * INP + c0, v0); st_bf16x4(P + (size_t)row * INP + c0 + 16, v1);
.Lip1_nr1:
	s_cmp_eq_u32 s43, 3
	s_cbranch_scc0 .Lip1_k1_plain
	s_mov_b32 s63, 0x3db504f3
	v_mul_f32_e32 v116, s63, v116
	v_mul_f32_e32 v117, s63, v117
	v_mul_f32_e32 v118, s63, v118
	v_mul_f32_e32 v119, s63, v119
	v_mul_f32_e32 v112, s63, v112
	v_mul_f32_e32 v113, s63, v113
	v_mul_f32_e32 v114, s63, v114
	v_mul_f32_e32 v115, s63, v115
	v_mul_f32_e32 v100, s63, v100
	v_mul_f32_e32 v101, s63, v101
	v_mul_f32_e32 v102, s63, v102
	v_mul_f32_e32 v103, s63, v103
	v_mul_f32_e32 v96, s63, v96
	v_mul_f32_e32 v97, s63, v97
	v_mul_f32_e32 v98, s63, v98
	v_mul_f32_e32 v99, s63, v99
	v_mul_f32_e32 v84, s63, v84
	v_mul_f32_e32 v85, s63, v85
	v_mul_f32_e32 v86, s63, v86
	v_mul_f32_e32 v87, s63, v87
	v_mul_f32_e32 v80, s63, v80
	v_mul_f32_e32 v81, s63, v81
	v_mul_f32_e32 v82, s63, v82
	v_mul_f32_e32 v83, s63, v83
	v_mul_f32_e32 v68, s63, v68
	v_mul_f32_e32 v69, s63, v69
	v_mul_f32_e32 v70, s63, v70
	v_mul_f32_e32 v71, s63, v71
	v_mul_f32_e32 v64, s63, v64
	v_mul_f32_e32 v65, s63, v65
	v_mul_f32_e32 v66, s63, v66
	v_mul_f32_e32 v67, s63, v67
	v_mul_f32_e32 v52, s63, v52
	v_mul_f32_e32 v53, s63, v53
	v_mul_f32_e32 v54, s63, v54
	v_mul_f32_e32 v55, s63, v55
	v_mul_f32_e32 v48, s63, v48
	v_mul_f32_e32 v49, s63, v49
	v_mul_f32_e32 v50, s63, v50
	v_mul_f32_e32 v51, s63, v51
	v_mul_f32_e32 v36, s63, v36
	v_mul_f32_e32 v37, s63, v37
	v_mul_f32_e32 v38, s63, v38
	v_mul_f32_e32 v39, s63, v39
	v_mul_f32_e32 v32, s63, v32
	v_mul_f32_e32 v33, s63, v33
	v_mul_f32_e32 v34, s63, v34
	v_mul_f32_e32 v35, s63, v35
	v_mul_f32_e32 v20, s63, v20
	v_mul_f32_e32 v21, s63, v21
	v_mul_f32_e32 v22, s63, v22
	v_mul_f32_e32 v23, s63, v23
	v_mul_f32_e32 v16, s63, v16
	v_mul_f32_e32 v17, s63, v17
	v_mul_f32_e32 v18, s63, v18
	v_mul_f32_e32 v19, s63, v19
	v_mul_f32_e32 v4, s63, v4
	v_mul_f32_e32 v5, s63, v5
	v_mul_f32_e32 v6, s63, v6
	v_mul_f32_e32 v7, s63, v7
	v_mul_f32_e32 v0, s63, v0
	v_mul_f32_e32 v1, s63, v1
	v_mul_f32_e32 v2, s63, v2
	v_mul_f32_e32 v3, s63, v3
	s_mul_i32 s54, s27, 640
	s_add_u32 s54, s54, s29
	s_sub_u32 s54, s54, 0xfc0
	s_mul_i32 s54, s54, 0x900
	s_lshl_b32 s63, s22, 8
	s_add_u32 s54, s54, s63
	s_lshl_b32 s54, s54, 1
	s_add_u32 s14, s50, 0x19860000
	s_addc_u32 s15, s51, 0
	s_add_u32 s14, s14, s54
	s_addc_u32 s15, s15, 0
	v_cvt_pk_bf16_f32 v236, v116, v117
	v_cvt_pk_bf16_f32 v237, v118, v119
	v_cvt_pk_bf16_f32 v238, v112, v113
	v_cvt_pk_bf16_f32 v239, v114, v115
	ds_write_b16 v167, v236 offset:0
	ds_write_b16_d16_hi v167, v236 offset:32
	ds_write_b16 v167, v237 offset:64
	ds_write_b16_d16_hi v167, v237 offset:96
	ds_write_b16 v167, v238 offset:512
	ds_write_b16_d16_hi v167, v238 offset:544
	ds_write_b16 v167, v239 offset:576
	ds_write_b16_d16_hi v167, v239 offset:608
	ds_read_b128 v[204:207], v168
	v_cvt_pk_bf16_f32 v240, v100, v101
	v_cvt_pk_bf16_f32 v241, v102, v103
	v_cvt_pk_bf16_f32 v242, v96, v97
	v_cvt_pk_bf16_f32 v243, v98, v99
	ds_write_b16 v167, v240 offset:0
	ds_write_b16_d16_hi v167, v240 offset:32
	ds_write_b16 v167, v241 offset:64
	ds_write_b16_d16_hi v167, v241 offset:96
	ds_write_b16 v167, v242 offset:512
	ds_write_b16_d16_hi v167, v242 offset:544
	ds_write_b16 v167, v243 offset:576
	ds_write_b16_d16_hi v167, v243 offset:608
	ds_read_b128 v[208:211], v168
	s_waitcnt lgkmcnt(9)
	global_store_dwordx4 v166, v[204:207], s[14:15] offset:0
	v_cvt_pk_bf16_f32 v236, v84, v85
	v_cvt_pk_bf16_f32 v237, v86, v87
	v_cvt_pk_bf16_f32 v238, v80, v81
	v_cvt_pk_bf16_f32 v239, v82, v83
	ds_write_b16 v167, v236 offset:0
	ds_write_b16_d16_hi v167, v236 offset:32
	ds_write_b16 v167, v237 offset:64
	ds_write_b16_d16_hi v167, v237 offset:96
	ds_write_b16 v167, v238 offset:512
	ds_write_b16_d16_hi v167, v238 offset:544
	ds_write_b16 v167, v239 offset:576
	ds_write_b16_d16_hi v167, v239 offset:608
	ds_read_b128 v[204:207], v168
	s_waitcnt lgkmcnt(9)
	global_store_dwordx4 v166, v[208:211], s[14:15] offset:32
	v_cvt_pk_bf16_f32 v240, v68, v69
	v_cvt_pk_bf16_f32 v241, v70, v71
	v_cvt_pk_bf16_f32 v242, v64, v65
	v_cvt_pk_bf16_f32 v243, v66, v67
	ds_write_b16 v167, v240 offset:0
	ds_write_b16_d16_hi v167, v240 offset:32
	ds_write_b16 v167, v241 offset:64
	ds_write_b16_d16_hi v167, v241 offset:96
	ds_write_b16 v167, v242 offset:512
	ds_write_b16_d16_hi v167, v242 offset:544
	ds_write_b16 v167, v243 offset:576
	ds_write_b16_d16_hi v167, v243 offset:608
	ds_read_b128 v[208:211], v168
	s_waitcnt lgkmcnt(9)
	global_store_dwordx4 v166, v[204:207], s[14:15] offset:64
	v_cvt_pk_bf16_f32 v236, v52, v53
	v_cvt_pk_bf16_f32 v237, v54, v55
	v_cvt_pk_bf16_f32 v238, v48, v49
	v_cvt_pk_bf16_f32 v239, v50, v51
	ds_write_b16 v167, v236 offset:0
	ds_write_b16_d16_hi v167, v236 offset:32
	ds_write_b16 v167, v237 offset:64
	ds_write_b16_d16_hi v167, v237 offset:96
	ds_write_b16 v167, v238 offset:512
	ds_write_b16_d16_hi v167, v238 offset:544
	ds_write_b16 v167, v239 offset:576
	ds_write_b16_d16_hi v167, v239 offset:608
	ds_read_b128 v[204:207], v168
	s_waitcnt lgkmcnt(9)
	global_store_dwordx4 v166, v[208:211], s[14:15] offset:96
	v_cvt_pk_bf16_f32 v240, v36, v37
	v_cvt_pk_bf16_f32 v241, v38, v39
	v_cvt_pk_bf16_f32 v242, v32, v33
	v_cvt_pk_bf16_f32 v243, v34, v35
	ds_write_b16 v167, v240 offset:0
	ds_write_b16_d16_hi v167, v240 offset:32
	ds_write_b16 v167, v241 offset:64
	ds_write_b16_d16_hi v167, v241 offset:96
	ds_write_b16 v167, v242 offset:512
	ds_write_b16_d16_hi v167, v242 offset:544
	ds_write_b16 v167, v243 offset:576
	ds_write_b16_d16_hi v167, v243 offset:608
	ds_read_b128 v[208:211], v168
	s_waitcnt lgkmcnt(9)
	global_store_dwordx4 v166, v[204:207], s[14:15] offset:256
	v_cvt_pk_bf16_f32 v236, v20, v21
	v_cvt_pk_bf16_f32 v237, v22, v23
	v_cvt_pk_bf16_f32 v238, v16, v17
	v_cvt_pk_bf16_f32 v239, v18, v19
	ds_write_b16 v167, v236 offset:0
	ds_write_b16_d16_hi v167, v236 offset:32
	ds_write_b16 v167, v237 offset:64
	ds_write_b16_d16_hi v167, v237 offset:96
	ds_write_b16 v167, v238 offset:512
	ds_write_b16_d16_hi v167, v238 offset:544
	ds_write_b16 v167, v239 offset:576
	ds_write_b16_d16_hi v167, v239 offset:608
	ds_read_b128 v[204:207], v168
	s_waitcnt lgkmcnt(9)
	global_store_dwordx4 v166, v[208:211], s[14:15] offset:288
	v_cvt_pk_bf16_f32 v240, v4, v5
	v_cvt_pk_bf16_f32 v241, v6, v7
	v_cvt_pk_bf16_f32 v242, v0, v1
	v_cvt_pk_bf16_f32 v243, v2, v3
	ds_write_b16 v167, v240 offset:0
	ds_write_b16_d16_hi v167, v240 offset:32
	ds_write_b16 v167, v241 offset:64
	ds_write_b16_d16_hi v167, v241 offset:96
	ds_write_b16 v167, v242 offset:512
	ds_write_b16_d16_hi v167, v242 offset:544
	ds_write_b16 v167, v243 offset:576
	ds_write_b16_d16_hi v167, v243 offset:608
	ds_read_b128 v[208:211], v168
	s_waitcnt lgkmcnt(9)
	global_store_dwordx4 v166, v[204:207], s[14:15] offset:320
	s_waitcnt lgkmcnt(0)
	global_store_dwordx4 v166, v[208:211], s[14:15] offset:352
	s_nop 1
; DI void st_tr16x32(LAS unsigned char* area, bf16_t* dst_f0_t0  , f32x4 v0, f32x4 v1, int fr, int fq, int lane) {
;     const unsigned p01 = cvt_pk_bf16(v0[0], v0[1]), p23 = cvt_pk_bf16(v0[2], v0[3]), q01 = cvt_pk_bf16(v1[0], v1[1]), q23 = cvt_pk_bf16(v1[2], v1[3]);
;     LAS bf16_t* w = (LAS bf16_t*)(area + (4 * fq) * 32 + fr * 2);
;     w[0 * 16] = (bf16_t)(p01 & 0xffffu); w[1 * 16] = (bf16_t)(p01 >> 16); w[2 * 16] = (bf16_t)(p23 & 0xffffu); w[3 * 16] = (bf16_t)(p23 >> 16);
;     w[16 * 16] = (bf16_t)(q01 & 0xffffu); w[17 * 16] = (bf16_t)(q01 >> 16); w[18 * 16] = (bf16_t)(q23 & 0xffffu); w[19 * 16] = (bf16_t)(q23 >> 16);
;     asm volatile("s_waitcnt lgkmcnt(0)" ::: "memory");
;     const u32x4 row = *(const LAS u32x4*)(area + (lane >> 1) * 32 + (lane & 1) * 16);
;     asm volatile("" ::: "memory");
;     *(u32x4*)(dst_f0_t0 + (size_t)(lane >> 1) * RB + (lane & 1) * 8) = row;
; }
;     DI void operator()(const f32x4 (&acc)[2][2][4][2], const Unit& u, int wr, int wc, int fr, int fq) const {
;     ...
;                     if (colg >= C_NAV && colg < C_CQ) {
;                         st_tr16x32(spare + (wr * 4 + wc) * 1024, (bf16_t*)(ws + WS_VTNA) + ((size_t)b * 768 + (colg - C_NAV)) * RB + (r - fr), v0, v1, fr, fq, fq * 16 + fr);
;                     } else if (colg >= C_RV && colg < C_RG) {
;                         st_tr16x32(spare + (wr * 4 + wc) * 1024, (bf16_t*)(ws + WS_VTR) + ((size_t)b * 640 + (colg - C_RV)) * RB + (r - fr), v0, v1, fr, fq, fq * 16 + fr);
;                     } else if (colg >= C_KPE && colg < C_RQ) {
;                         if (lat) rope4(v0, v1, (const float*)(ws + WS_TABM) + ((size_t)t * 32 + ((colg - C_KPE) >> 5) * 16 + 4 * fq) * 2);
;                         bf16_t* kp = (bf16_t*)(ws + WS_KPE) + (size_t)row * 64 + (c0 - C_KPE);
;                         st_bf16x4(kp, v0); st_bf16x4(kp + 16, v1);
;                     } else if (colg >= C_RQ && colg < C_RV) {
;                         if (lat) rope4(v0, v1, (const float*)(ws + WS_TABR) + ((size_t)t * 64 + (((colg - C_RQ) & 127) >> 5) * 16 + 4 * fq) * 2);
;                         if (colg >= C_RK) {
;                             v0 *= 0.08838834764831845f; v1 *= 0.08838834764831845f;
;                             st_tr16x32(spare + (wr * 4 + wc) * 1024, (bf16_t*)(ws + WS_KTR) + ((size_t)b * 640 + (colg - C_RK)) * RB + (r - fr), v0, v1, fr, fq, fq * 16 + fr);
.Lip1_k1_plain:
	s_mul_i32 s54, s10, 0x300000
	s_add_u32 s12, s50, 0x113a0000
	s_addc_u32 s13, s51, 0
	s_add_u32 s12, s12, s54
	s_addc_u32 s13, s13, 0
	s_lshl_b32 s54, s29, 1
	s_add_u32 s12, s12, s54
	s_addc_u32 s13, s13, 0
	v_cvt_pk_bf16_f32 v116, v116, v117
	v_cvt_pk_bf16_f32 v117, v118, v119
	global_store_dwordx2 v150, v[116:117], s[12:13] offset:0
	v_cvt_pk_bf16_f32 v112, v112, v113
	v_cvt_pk_bf16_f32 v113, v114, v115
	global_store_dwordx2 v150, v[112:113], s[12:13] offset:32
	v_cvt_pk_bf16_f32 v100, v100, v101
	v_cvt_pk_bf16_f32 v101, v102, v103
	global_store_dwordx2 v151, v[100:101], s[12:13] offset:0
	v_cvt_pk_bf16_f32 v96, v96, v97
	v_cvt_pk_bf16_f32 v97, v98, v99
	global_store_dwordx2 v151, v[96:97], s[12:13] offset:32
	v_cvt_pk_bf16_f32 v84, v84, v85
	v_cvt_pk_bf16_f32 v85, v86, v87
	global_store_dwordx2 v152, v[84:85], s[12:13] offset:0
	v_cvt_pk_bf16_f32 v80, v80, v81
	v_cvt_pk_bf16_f32 v81, v82, v83
	global_store_dwordx2 v152, v[80:81], s[12:13] offset:32
	v_cvt_pk_bf16_f32 v68, v68, v69
	v_cvt_pk_bf16_f32 v69, v70, v71
	global_store_dwordx2 v153, v[68:69], s[12:13] offset:0
	v_cvt_pk_bf16_f32 v64, v64, v65
	v_cvt_pk_bf16_f32 v65, v66, v67
	global_store_dwordx2 v153, v[64:65], s[12:13] offset:32
	v_cvt_pk_bf16_f32 v52, v52, v53
	v_cvt_pk_bf16_f32 v53, v54, v55
	global_store_dwordx2 v154, v[52:53], s[12:13] offset:0
	v_cvt_pk_bf16_f32 v48, v48, v49
	v_cvt_pk_bf16_f32 v49, v50, v51
	global_store_dwordx2 v154, v[48:49], s[12:13] offset:32
	v_cvt_pk_bf16_f32 v36, v36, v37
	v_cvt_pk_bf16_f32 v37, v38, v39
	global_store_dwordx2 v155, v[36:37], s[12:13] offset:0
	v_cvt_pk_bf16_f32 v32, v32, v33
	v_cvt_pk_bf16_f32 v33, v34, v35
	global_store_dwordx2 v155, v[32:33], s[12:13] offset:32
	v_cvt_pk_bf16_f32 v20, v20, v21
	v_cvt_pk_bf16_f32 v21, v22, v23
	global_store_dwordx2 v156, v[20:21], s[12:13] offset:0
	v_cvt_pk_bf16_f32 v16, v16, v17
	v_cvt_pk_bf16_f32 v17, v18, v19
	global_store_dwordx2 v156, v[16:17], s[12:13] offset:32
	v_cvt_pk_bf16_f32 v4, v4, v5
	v_cvt_pk_bf16_f32 v5, v6, v7
	global_store_dwordx2 v157, v[4:5], s[12:13] offset:0
	v_cvt_pk_bf16_f32 v0, v0, v1
	v_cvt_pk_bf16_f32 v1, v2, v3
	global_store_dwordx2 v157, v[0:1], s[12:13] offset:32
	s_branch .Lip1_k1_end
.Lip1_k1_nav:
	s_mul_i32 s54, s27, 768
	s_add_u32 s54, s54, s29
	s_sub_u32 s54, s54, 0x600
	s_mul_i32 s54, s54, 0x900
	s_lshl_b32 s63, s22, 8
	s_add_u32 s54, s54, s63
	s_lshl_b32 s54, s54, 1
	s_add_u32 s14, s50, 0x17fa0000
	s_addc_u32 s15, s51, 0
	s_add_u32 s14, s14, s54
	s_addc_u32 s15, s15, 0
	v_cvt_pk_bf16_f32 v236, v116, v117
	v_cvt_pk_bf16_f32 v237, v118, v119
	v_cvt_pk_bf16_f32 v238, v112, v113
	v_cvt_pk_bf16_f32 v239, v114, v115
	ds_write_b16 v167, v236 offset:0
	ds_write_b16_d16_hi v167, v236 offset:32
	ds_write_b16 v167, v237 offset:64
	ds_write_b16_d16_hi v167, v237 offset:96
	ds_write_b16 v167, v238 offset:512
	ds_write_b16_d16_hi v167, v238 offset:544
	ds_write_b16 v167, v239 offset:576
	ds_write_b16_d16_hi v167, v239 offset:608
	ds_read_b128 v[204:207], v168
	v_cvt_pk_bf16_f32 v240, v100, v101
	v_cvt_pk_bf16_f32 v241, v102, v103
	v_cvt_pk_bf16_f32 v242, v96, v97
	v_cvt_pk_bf16_f32 v243, v98, v99
	ds_write_b16 v167, v240 offset:0
	ds_write_b16_d16_hi v167, v240 offset:32
	ds_write_b16 v167, v241 offset:64
	ds_write_b16_d16_hi v167, v241 offset:96
	ds_write_b16 v167, v242 offset:512
	ds_write_b16_d16_hi v167, v242 offset:544
	ds_write_b16 v167, v243 offset:576
	ds_write_b16_d16_hi v167, v243 offset:608
	ds_read_b128 v[208:211], v168
	s_waitcnt lgkmcnt(9)
	global_store_dwordx4 v166, v[204:207], s[14:15] offset:0
	v_cvt_pk_bf16_f32 v236, v84, v85
	v_cvt_pk_bf16_f32 v237, v86, v87
	v_cvt_pk_bf16_f32 v238, v80, v81
	v_cvt_pk_bf16_f32 v239, v82, v83
	ds_write_b16 v167, v236 offset:0
	ds_write_b16_d16_hi v167, v236 offset:32
	ds_write_b16 v167, v237 offset:64
	ds_write_b16_d16_hi v167, v237 offset:96
	ds_write_b16 v167, v238 offset:512
	ds_write_b16_d16_hi v167, v238 offset:544
	ds_write_b16 v167, v239 offset:576
	ds_write_b16_d16_hi v167, v239 offset:608
	ds_read_b128 v[204:207], v168
	s_waitcnt lgkmcnt(9)
	global_store_dwordx4 v166, v[208:211], s[14:15] offset:32
	v_cvt_pk_bf16_f32 v240, v68, v69
	v_cvt_pk_bf16_f32 v241, v70, v71
	v_cvt_pk_bf16_f32 v242, v64, v65
	v_cvt_pk_bf16_f32 v243, v66, v67
	ds_write_b16 v167, v240 offset:0
	ds_write_b16_d16_hi v167, v240 offset:32
	ds_write_b16 v167, v241 offset:64
	ds_write_b16_d16_hi v167, v241 offset:96
	ds_write_b16 v167, v242 offset:512
	ds_write_b16_d16_hi v167, v242 offset:544
	ds_write_b16 v167, v243 offset:576
	ds_write_b16_d16_hi v167, v243 offset:608
	ds_read_b128 v[208:211], v168
	s_waitcnt lgkmcnt(9)
	global_store_dwordx4 v166, v[204:207], s[14:15] offset:64
	v_cvt_pk_bf16_f32 v236, v52, v53
	v_cvt_pk_bf16_f32 v237, v54, v55
	v_cvt_pk_bf16_f32 v238, v48, v49
	v_cvt_pk_bf16_f32 v239, v50, v51
	ds_write_b16 v167, v236 offset:0
	ds_write_b16_d16_hi v167, v236 offset:32
	ds_write_b16 v167, v237 offset:64
	ds_write_b16_d16_hi v167, v237 offset:96
	ds_write_b16 v167, v238 offset:512
	ds_write_b16_d16_hi v167, v238 offset:544
	ds_write_b16 v167, v239 offset:576
	ds_write_b16_d16_hi v167, v239 offset:608
	ds_read_b128 v[204:207], v168
	s_waitcnt lgkmcnt(9)
	global_store_dwordx4 v166, v[208:211], s[14:15] offset:96
	v_cvt_pk_bf16_f32 v240, v36, v37
	v_cvt_pk_bf16_f32 v241, v38, v39
	v_cvt_pk_bf16_f32 v242, v32, v33
	v_cvt_pk_bf16_f32 v243, v34, v35
	ds_write_b16 v167, v240 offset:0
	ds_write_b16_d16_hi v167, v240 offset:32
	ds_write_b16 v167, v241 offset:64
	ds_write_b16_d16_hi v167, v241 offset:96
	ds_write_b16 v167, v242 offset:512
	ds_write_b16_d16_hi v167, v242 offset:544
	ds_write_b16 v167, v243 offset:576
	ds_write_b16_d16_hi v167, v243 offset:608
	ds_read_b128 v[208:211], v168
	s_waitcnt lgkmcnt(9)
	global_store_dwordx4 v166, v[204:207], s[14:15] offset:256
	v_cvt_pk_bf16_f32 v236, v20, v21
	v_cvt_pk_bf16_f32 v237, v22, v23
	v_cvt_pk_bf16_f32 v238, v16, v17
	v_cvt_pk_bf16_f32 v239, v18, v19
	ds_write_b16 v167, v236 offset:0
	ds_write_b16_d16_hi v167, v236 offset:32
	ds_write_b16 v167, v237 offset:64
	ds_write_b16_d16_hi v167, v237 offset:96
	ds_write_b16 v167, v238 offset:512
	ds_write_b16_d16_hi v167, v238 offset:544
	ds_write_b16 v167, v239 offset:576
	ds_write_b16_d16_hi v167, v239 offset:608
	ds_read_b128 v[204:207], v168
	s_waitcnt lgkmcnt(9)
	global_store_dwordx4 v166, v[208:211], s[14:15] offset:288
	v_cvt_pk_bf16_f32 v240, v4, v5
	v_cvt_pk_bf16_f32 v241, v6, v7
	v_cvt_pk_bf16_f32 v242, v0, v1
	v_cvt_pk_bf16_f32 v243, v2, v3
	ds_write_b16 v167, v240 offset:0
	ds_write_b16_d16_hi v167, v240 offset:32
	ds_write_b16 v167, v241 offset:64
	ds_write_b16_d16_hi v167, v241 offset:96
	ds_write_b16 v167, v242 offset:512
	ds_write_b16_d16_hi v167, v242 offset:544
	ds_write_b16 v167, v243 offset:576
	ds_write_b16_d16_hi v167, v243 offset:608
	ds_read_b128 v[208:211], v168
	s_waitcnt lgkmcnt(9)
	global_store_dwordx4 v166, v[204:207], s[14:15] offset:320
	s_waitcnt lgkmcnt(0)
	global_store_dwordx4 v166, v[208:211], s[14:15] offset:352
	s_nop 1
	s_branch .Lip1_k1_end
; #define LAS __attribute__((address_space(3)))
; DI unsigned cvt_pk_bf16(float lo, float hi) { unsigned r; asm volatile("v_cvt_pk_bf16_f32 %0, %1, %2" : "=v"(r) : "v"(lo), "v"(hi)); return r; }
; DI void st_tr16x32(LAS unsigned char* area, bf16_t* dst_f0_t0  , f32x4 v0, f32x4 v1, int fr, int fq, int lane) {
;     const unsigned p01 = cvt_pk_bf16(v0[0], v0[1]), p23 = cvt_pk_bf16(v0[2], v0[3]), q01 = cvt_pk_bf16(v1[0], v1[1]), q23 = cvt_pk_bf16(v1[2], v1[3]);
;     LAS bf16_t* w = (LAS bf16_t*)(area + (4 * fq) * 32 + fr * 2);
;     w[0 * 16] = (bf16_t)(p01 & 0xffffu); w[1 * 16] = (bf16_t)(p01 >> 16); w[2 * 16] = (bf16_t)(p23 & 0xffffu); w[3 * 16] = (bf16_t)(p23 >> 16);
;     w[16 * 16] = (bf16_t)(q01 & 0xffffu); w[17 * 16] = (bf16_t)(q01 >> 16); w[18 * 16] = (bf16_t)(q23 & 0xffffu); w[19 * 16] = (bf16_t)(q23 >> 16);
;     asm volatile("s_waitcnt lgkmcnt(0)" ::: "memory");
;     const u32x4 row = *(const LAS u32x4*)(area + (lane >> 1) * 32 + (lane & 1) * 16);
;     asm volatile("" ::: "memory");
;     *(u32x4*)(dst_f0_t0 + (size_t)(lane >> 1) * RB + (lane & 1) * 8) = row;
; }
;     DI void operator()(const f32x4 (&acc)[2][2][4][2], const Unit& u, int wr, int wc, int fr, int fq) const {
;     ...
;                     } else if (colg >= C_RV && colg < C_RG) {
;                         st_tr16x32(spare + (wr * 4 + wc) * 1024, (bf16_t*)(ws + WS_VTR) + ((size_t)b * 640 + (colg - C_RV)) * RB + (r - fr), v0, v1, fr, fq, fq * 16 + fr);
.Lip1_k1_rv:
	s_mul_i32 s54, s27, 640
	s_add_u32 s54, s54, s29
	s_sub_u32 s54, s54, 0x1240
	s_mul_i32 s54, s54, 0x900
	s_lshl_b32 s63, s22, 8
	s_add_u32 s54, s54, s63
	s_lshl_b32 s54, s54, 1
	s_add_u32 s14, s50, 0x18d20000
	s_addc_u32 s15, s51, 0
	s_add_u32 s14, s14, s54
	s_addc_u32 s15, s15, 0
	v_cvt_pk_bf16_f32 v236, v116, v117
	v_cvt_pk_bf16_f32 v237, v118, v119
	v_cvt_pk_bf16_f32 v238, v112, v113
	v_cvt_pk_bf16_f32 v239, v114, v115
	ds_write_b16 v167, v236 offset:0
	ds_write_b16_d16_hi v167, v236 offset:32
	ds_write_b16 v167, v237 offset:64
	ds_write_b16_d16_hi v167, v237 offset:96
	ds_write_b16 v167, v238 offset:512
	ds_write_b16_d16_hi v167, v238 offset:544
	ds_write_b16 v167, v239 offset:576
	ds_write_b16_d16_hi v167, v239 offset:608
	ds_read_b128 v[204:207], v168
	v_cvt_pk_bf16_f32 v240, v100, v101
	v_cvt_pk_bf16_f32 v241, v102, v103
	v_cvt_pk_bf16_f32 v242, v96, v97
	v_cvt_pk_bf16_f32 v243, v98, v99
	ds_write_b16 v167, v240 offset:0
	ds_write_b16_d16_hi v167, v240 offset:32
	ds_write_b16 v167, v241 offset:64
	ds_write_b16_d16_hi v167, v241 offset:96
	ds_write_b16 v167, v242 offset:512
	ds_write_b16_d16_hi v167, v242 offset:544
	ds_write_b16 v167, v243 offset:576
	ds_write_b16_d16_hi v167, v243 offset:608
	ds_read_b128 v[208:211], v168
	s_waitcnt lgkmcnt(9)
	global_store_dwordx4 v166, v[204:207], s[14:15] offset:0
	v_cvt_pk_bf16_f32 v236, v84, v85
	v_cvt_pk_bf16_f32 v237, v86, v87
	v_cvt_pk_bf16_f32 v238, v80, v81
	v_cvt_pk_bf16_f32 v239, v82, v83
	ds_write_b16 v167, v236 offset:0
	ds_write_b16_d16_hi v167, v236 offset:32
	ds_write_b16 v167, v237 offset:64
	ds_write_b16_d16_hi v167, v237 offset:96
	ds_write_b16 v167, v238 offset:512
	ds_write_b16_d16_hi v167, v238 offset:544
	ds_write_b16 v167, v239 offset:576
	ds_write_b16_d16_hi v167, v239 offset:608
	ds_read_b128 v[204:207], v168
	s_waitcnt lgkmcnt(9)
	global_store_dwordx4 v166, v[208:211], s[14:15] offset:32
	v_cvt_pk_bf16_f32 v240, v68, v69
	v_cvt_pk_bf16_f32 v241, v70, v71
	v_cvt_pk_bf16_f32 v242, v64, v65
	v_cvt_pk_bf16_f32 v243, v66, v67
	ds_write_b16 v167, v240 offset:0
	ds_write_b16_d16_hi v167, v240 offset:32
	ds_write_b16 v167, v241 offset:64
	ds_write_b16_d16_hi v167, v241 offset:96
	ds_write_b16 v167, v242 offset:512
	ds_write_b16_d16_hi v167, v242 offset:544
	ds_write_b16 v167, v243 offset:576
	ds_write_b16_d16_hi v167, v243 offset:608
	ds_read_b128 v[208:211], v168
	s_waitcnt lgkmcnt(9)
	global_store_dwordx4 v166, v[204:207], s[14:15] offset:64
	v_cvt_pk_bf16_f32 v236, v52, v53
	v_cvt_pk_bf16_f32 v237, v54, v55
	v_cvt_pk_bf16_f32 v238, v48, v49
	v_cvt_pk_bf16_f32 v239, v50, v51
	ds_write_b16 v167, v236 offset:0
	ds_write_b16_d16_hi v167, v236 offset:32
	ds_write_b16 v167, v237 offset:64
	ds_write_b16_d16_hi v167, v237 offset:96
	ds_write_b16 v167, v238 offset:512
	ds_write_b16_d16_hi v167, v238 offset:544
	ds_write_b16 v167, v239 offset:576
	ds_write_b16_d16_hi v167, v239 offset:608
	ds_read_b128 v[204:207], v168
	s_waitcnt lgkmcnt(9)
	global_store_dwordx4 v166, v[208:211], s[14:15] offset:96
	v_cvt_pk_bf16_f32 v240, v36, v37
	v_cvt_pk_bf16_f32 v241, v38, v39
	v_cvt_pk_bf16_f32 v242, v32, v33
	v_cvt_pk_bf16_f32 v243, v34, v35
	ds_write_b16 v167, v240 offset:0
	ds_write_b16_d16_hi v167, v240 offset:32
	ds_write_b16 v167, v241 offset:64
	ds_write_b16_d16_hi v167, v241 offset:96
	ds_write_b16 v167, v242 offset:512
	ds_write_b16_d16_hi v167, v242 offset:544
	ds_write_b16 v167, v243 offset:576
	ds_write_b16_d16_hi v167, v243 offset:608
	ds_read_b128 v[208:211], v168
	s_waitcnt lgkmcnt(9)
	global_store_dwordx4 v166, v[204:207], s[14:15] offset:256
	v_cvt_pk_bf16_f32 v236, v20, v21
	v_cvt_pk_bf16_f32 v237, v22, v23
	v_cvt_pk_bf16_f32 v238, v16, v17
	v_cvt_pk_bf16_f32 v239, v18, v19
	ds_write_b16 v167, v236 offset:0
	ds_write_b16_d16_hi v167, v236 offset:32
	ds_write_b16 v167, v237 offset:64
	ds_write_b16_d16_hi v167, v237 offset:96
	ds_write_b16 v167, v238 offset:512
	ds_write_b16_d16_hi v167, v238 offset:544
	ds_write_b16 v167, v239 offset:576
	ds_write_b16_d16_hi v167, v239 offset:608
	ds_read_b128 v[204:207], v168
	s_waitcnt lgkmcnt(9)
	global_store_dwordx4 v166, v[208:211], s[14:15] offset:288
	v_cvt_pk_bf16_f32 v240, v4, v5
	v_cvt_pk_bf16_f32 v241, v6, v7
	v_cvt_pk_bf16_f32 v242, v0, v1
	v_cvt_pk_bf16_f32 v243, v2, v3
	ds_write_b16 v167, v240 offset:0
	ds_write_b16_d16_hi v167, v240 offset:32
	ds_write_b16 v167, v241 offset:64
	ds_write_b16_d16_hi v167, v241 offset:96
	ds_write_b16 v167, v242 offset:512
	ds_write_b16_d16_hi v167, v242 offset:544
	ds_write_b16 v167, v243 offset:576
	ds_write_b16_d16_hi v167, v243 offset:608
	ds_read_b128 v[208:211], v168
	s_waitcnt lgkmcnt(9)
	global_store_dwordx4 v166, v[204:207], s[14:15] offset:320
	s_waitcnt lgkmcnt(0)
	global_store_dwordx4 v166, v[208:211], s[14:15] offset:352
	s_nop 1
	s_branch .Lip1_k1_end
; DI void st_bf16x4(bf16_t* p, f32x4 v) { u32x2 w; w.x = cvt_pk_bf16(v[0], v[1]); w.y = cvt_pk_bf16(v[2], v[3]); *(u32x2*)p = w; }
;     DI void operator()(const f32x4 (&acc)[2][2][4][2], const Unit& u, int wr, int wc, int fr, int fq) const {
;     ...
;                         if (colg >= C_CQ && colg < C_KPE) {
;                             float ss = v0[0] * v0[0] + v0[1] * v0[1] + v0[2] * v0[2] + v0[3] * v0[3] + v1[0] * v1[0] + v1[1] * v1[1] + v1[2] * v1[2] + v1[3] * v1[3];
;                             ss += __shfl_xor(ss, 16); ss += __shfl_xor(ss, 32);
;                             if (fq == 0) ((float*)(ws + WS_SSQ))[(size_t)row * 32 + ((colg - C_CQ) >> 5)] = ss;
;                         }
;                         st_bf16x4(P + (size_t)row * INP + c0, v0); st_bf16x4(P + (size_t)row * INP + c0 + 16, v1);
.Lip1_k1_ssq:
	v_xor_b32_e32 v198, 16, v197
	v_lshlrev_b32_e32 v198, 2, v198
	v_xor_b32_e32 v199, 32, v197
	v_lshlrev_b32_e32 v199, 2, v199
	v_mul_f32_e32 v158, v116, v116
	v_fmac_f32_e32 v158, v117, v117
	v_fmac_f32_e32 v158, v118, v118
	v_fmac_f32_e32 v158, v119, v119
	v_fmac_f32_e32 v158, v112, v112
	v_fmac_f32_e32 v158, v113, v113
	v_fmac_f32_e32 v158, v114, v114
	v_fmac_f32_e32 v158, v115, v115
	v_mul_f32_e32 v159, v100, v100
	v_fmac_f32_e32 v159, v101, v101
	v_fmac_f32_e32 v159, v102, v102
	v_fmac_f32_e32 v159, v103, v103
	v_fmac_f32_e32 v159, v96, v96
	v_fmac_f32_e32 v159, v97, v97
	v_fmac_f32_e32 v159, v98, v98
	v_fmac_f32_e32 v159, v99, v99
	v_mul_f32_e32 v160, v84, v84
	v_fmac_f32_e32 v160, v85, v85
	v_fmac_f32_e32 v160, v86, v86
	v_fmac_f32_e32 v160, v87, v87
	v_fmac_f32_e32 v160, v80, v80
	v_fmac_f32_e32 v160, v81, v81
	v_fmac_f32_e32 v160, v82, v82
	v_fmac_f32_e32 v160, v83, v83
	v_mul_f32_e32 v161, v68, v68
	v_fmac_f32_e32 v161, v69, v69
	v_fmac_f32_e32 v161, v70, v70
	v_fmac_f32_e32 v161, v71, v71
	v_fmac_f32_e32 v161, v64, v64
	v_fmac_f32_e32 v161, v65, v65
	v_fmac_f32_e32 v161, v66, v66
	v_fmac_f32_e32 v161, v67, v67
	v_mul_f32_e32 v162, v52, v52
	v_fmac_f32_e32 v162, v53, v53
	v_fmac_f32_e32 v162, v54, v54
	v_fmac_f32_e32 v162, v55, v55
	v_fmac_f32_e32 v162, v48, v48
	v_fmac_f32_e32 v162, v49, v49
	v_fmac_f32_e32 v162, v50, v50
	v_fmac_f32_e32 v162, v51, v51
	v_mul_f32_e32 v163, v36, v36
	v_fmac_f32_e32 v163, v37, v37
	v_fmac_f32_e32 v163, v38, v38
	v_fmac_f32_e32 v163, v39, v39
	v_fmac_f32_e32 v163, v32, v32
	v_fmac_f32_e32 v163, v33, v33
	v_fmac_f32_e32 v163, v34, v34
	v_fmac_f32_e32 v163, v35, v35
	v_mul_f32_e32 v164, v20, v20
	v_fmac_f32_e32 v164, v21, v21
	v_fmac_f32_e32 v164, v22, v22
	v_fmac_f32_e32 v164, v23, v23
	v_fmac_f32_e32 v164, v16, v16
	v_fmac_f32_e32 v164, v17, v17
	v_fmac_f32_e32 v164, v18, v18
	v_fmac_f32_e32 v164, v19, v19
	v_mul_f32_e32 v165, v4, v4
	v_fmac_f32_e32 v165, v5, v5
	v_fmac_f32_e32 v165, v6, v6
	v_fmac_f32_e32 v165, v7, v7
	v_fmac_f32_e32 v165, v0, v0
	v_fmac_f32_e32 v165, v1, v1
	v_fmac_f32_e32 v165, v2, v2
	v_fmac_f32_e32 v165, v3, v3
	ds_bpermute_b32 v204, v198, v158
	ds_bpermute_b32 v205, v198, v159
	ds_bpermute_b32 v206, v198, v160
	ds_bpermute_b32 v207, v198, v161
	ds_bpermute_b32 v208, v198, v162
	ds_bpermute_b32 v209, v198, v163
	ds_bpermute_b32 v210, v198, v164
	ds_bpermute_b32 v211, v198, v165
	s_waitcnt lgkmcnt(0)
	v_add_f32_e32 v158, v158, v204
	v_add_f32_e32 v159, v159, v205
	v_add_f32_e32 v160, v160, v206
	v_add_f32_e32 v161, v161, v207
	v_add_f32_e32 v162, v162, v208
	v_add_f32_e32 v163, v163, v209
	v_add_f32_e32 v164, v164, v210
	v_add_f32_e32 v165, v165, v211
	ds_bpermute_b32 v204, v199, v158
	ds_bpermute_b32 v205, v199, v159
	ds_bpermute_b32 v206, v199, v160
	ds_bpermute_b32 v207, v199, v161
	ds_bpermute_b32 v208, v199, v162
	ds_bpermute_b32 v209, v199, v163
	ds_bpermute_b32 v210, v199, v164
	ds_bpermute_b32 v211, v199, v165
	s_waitcnt lgkmcnt(0)
	v_add_f32_e32 v158, v158, v204
	v_add_f32_e32 v159, v159, v205
	v_add_f32_e32 v160, v160, v206
	v_add_f32_e32 v161, v161, v207
	v_add_f32_e32 v162, v162, v208
	v_add_f32_e32 v163, v163, v209
	v_add_f32_e32 v164, v164, v210
	v_add_f32_e32 v165, v165, v211
	s_lshl_b32 s54, s10, 15
	s_add_u32 s14, s50, 0x200000
	s_addc_u32 s15, s51, 0
	s_add_u32 s14, s14, s54
	s_addc_u32 s15, s15, 0
	s_sub_u32 s54, s29, 0x900
	s_lshr_b32 s54, s54, 5
	s_lshl_b32 s54, s54, 2
	s_add_u32 s14, s14, s54
	s_addc_u32 s15, s15, 0
	v_lshlrev_b32_e32 v212, 7, v195
	v_add_u32_e32 v213, 0x800, v212
	v_add_u32_e32 v214, 0x1000, v212
	v_add_u32_e32 v215, 0x1800, v212
	v_add_u32_e32 v216, 0x4000, v212
	v_add_u32_e32 v217, 0x4800, v212
	v_add_u32_e32 v218, 0x5000, v212
	v_add_u32_e32 v219, 0x5800, v212
	v_cmp_eq_u32_e64 s[12:13], 0, v196
	s_mov_b64 exec, s[12:13]
	global_store_dword v212, v158, s[14:15]
	global_store_dword v213, v159, s[14:15]
	global_store_dword v214, v160, s[14:15]
	global_store_dword v215, v161, s[14:15]
	global_store_dword v216, v162, s[14:15]
	global_store_dword v217, v163, s[14:15]
	global_store_dword v218, v164, s[14:15]
	global_store_dword v219, v165, s[14:15]
	s_mov_b64 exec, -1
	s_branch .Lip1_k1_plain
.Lip1_k1_end:
	s_sub_u32 s29, s29, 0x80
	s_branch .LBB0_1977
.Lip1_old:
	s_mul_hi_i32 s11, s10, 0x38e38e39
	s_lshr_b32 s12, s11, 31
	s_ashr_i32 s11, s11, 1
	s_add_i32 s71, s11, s12
	v_lshl_add_u32 v152, s10, 8, v139
	s_mul_i32 s21, s71, 0xfffff700
	s_lshl_b32 s22, s0, 8
	v_add_u32_e32 v154, s21, v152
	v_mov_b64_e32 v[150:151], s[18:19]
	s_or_b32 s76, s22, s96
	v_cmp_lt_i32_e64 s[10:11], s34, v154
	v_add_u32_e32 v132, 0xffffff00, v154
	v_ashrrev_i32_e32 v153, 31, v152
	v_mad_i64_i32 v[156:157], s[12:13], v152, s35, v[150:151]
	v_sub_u32_e32 v154, v154, v137
	s_cmpk_lt_i32 s76, 0x1740
	s_mul_hi_i32 s54, s71, 0x280
	s_mul_i32 s63, s71, 0x280
	s_mul_hi_i32 s69, s71, 0x300
	s_mulk_i32 s71, 0x300
	v_lshlrev_b64 v[160:161], 7, v[152:153]
	v_lshlrev_b64 v[158:159], 9, v[132:133]
	v_ashrrev_i32_e32 v155, 31, v154
	s_cselect_b64 s[12:13], -1, 0
	s_cmpk_gt_i32 s76, 0x173f
	v_or_b32_e32 v150, s76, v134
	s_cbranch_scc1 .LBB0_2008
	s_add_i32 s0, s22, 0xfffffa00
	s_cmpk_gt_u32 s0, 0x2ff
	s_mov_b64 s[14:15], -1
	s_cbranch_scc0 .LBB0_2006
	s_add_i32 s20, s76, 0xffffedc0
	s_cmpk_gt_u32 s20, 0x27f
	s_cbranch_scc0 .LBB0_2003
	s_and_b32 s0, s76, 0xffffff40
	s_cmpk_lg_i32 s0, 0xd00
	s_cbranch_scc0 .LBB0_1998
	s_add_i32 s0, s76, 0xfffff2c0
	s_cmpk_gt_u32 s0, 0x4ff
	s_cbranch_scc0 .LBB0_1992
	s_add_i32 s0, s22, 0xfffff700
	s_cmpk_gt_u32 s0, 0x3ff
	s_cbranch_scc1 .LBB0_1991
	v_mul_f32_e32 v151, v125, v125
	v_fmac_f32_e32 v151, v124, v124
	v_fmac_f32_e32 v151, v126, v126
	v_fmac_f32_e32 v151, v127, v127
	v_and_b32_e32 v162, 64, v177
	v_fmac_f32_e32 v151, v120, v120
	v_xor_b32_e32 v153, 16, v177
	v_add_u32_e32 v162, 64, v162
	v_fmac_f32_e32 v151, v121, v121
	v_cmp_lt_i32_e32 vcc, v153, v162
	v_fmac_f32_e32 v151, v122, v122
	v_fmac_f32_e32 v151, v123, v123
	v_cndmask_b32_e32 v153, v177, v153, vcc
	v_lshlrev_b32_e32 v153, 2, v153
	ds_bpermute_b32 v153, v153, v151
	s_waitcnt lgkmcnt(0)
	v_add_f32_e32 v151, v151, v153
	v_xor_b32_e32 v153, 32, v177
	v_cmp_lt_i32_e32 vcc, v153, v162
	s_nop 1
	v_cndmask_b32_e32 v153, v177, v153, vcc
	v_lshlrev_b32_e32 v153, 2, v153
	ds_bpermute_b32 v153, v153, v151
	s_and_saveexec_b64 s[14:15], s[2:3]
	s_cbranch_execz .LBB0_1990
	v_readlane_b32 s28, v253, 13
	v_readlane_b32 s29, v253, 14
	s_add_i32 s0, s76, 0xfffff700
	s_lshr_b32 s0, s0, 3
	v_lshl_add_u64 v[162:163], s[28:29], 0, v[160:161]
	v_lshl_add_u64 v[162:163], v[162:163], 0, s[0:1]
	s_waitcnt lgkmcnt(0)
	v_add_f32_e32 v151, v151, v153
	flat_store_dword v[162:163], v151
